# lp=1 fully hand-written: prep_ssd x2, prep_gla x2 rewritten (wave = 8 rows, lane = 8/4 channels, x4 row loads, in-lane transposes), 8-wave prep_dn_chunk; all compiled lp=1 code removed
# speedup vs baseline: 1.0326x; 1.0191x over previous
;     template <class Tp> __device__ __forceinline__ Tp* W(size_t off) const { return (Tp*)(ws + off); }
; __device__ __forceinline__ void prep_dn_load(const bf16_t* proj, const float* cw, int idx, u32x4 (&raw)[4], int& t, int& ch) {
;     if (idx >= 0) { t = idx / 384; const int j = idx - t * 384; ch = j * 8; }
; #pragma unroll
;     for (int k = 0; k < 4; ++k) { const int tt = t - 3 + k; raw[k] = (u32x4){0u, 0u, 0u, 0u};
;         if (tt >= 0) raw[k] = *(const u32x4*)(proj + (size_t)tt * NP + C_DNQ + ch); }
; }
; __device__ void prep_dn_chunk(const Ctx& c, int ck, int half) {
;     const bf16_t* proj = c.W<bf16_t>(WS_PROJ);
;     const float* cw = c.in(I_DNCONV) + (size_t)c.layer * 4 * 3072;
;     bf16_t* dq = c.W<bf16_t>(WS_DQ); bf16_t* dk = c.W<bf16_t>(WS_DK); bf16_t* dv = c.W<bf16_t>(WS_DV);
;     for (int it = c.tid; it < 64 * 192; it += 1024) {
;         u32x4 r0[4], r1[4]; int t0, c0, t1, c1;
;         { const int l = it / 192, j = it - l * 192; t0 = ck * 64 + l; c0 = (j >> 6) * 1024 + half * 512 + (j & 63) * 8; }
;         { const int i2 = it + 512, l = i2 / 192, j = i2 - l * 192; t1 = ck * 64 + l; c1 = (j >> 6) * 1024 + half * 512 + (j & 63) * 8; }
;         prep_dn_load(proj, cw, -1, r0, t0, c0);
;         prep_dn_load(proj, cw, -1, r1, t1, c1);
;         prep_dn_finish(cw, dq, dk, dv, r0, t0, c0);
;         prep_dn_finish(cw, dq, dk, dv, r1, t1, c1);
;     }
; }
.LBB0_609:
	v_writelane_b32 v248, s28, 35
	v_writelane_b32 v248, s29, 36
	v_writelane_b32 v248, s30, 37
	v_writelane_b32 v248, s31, 38
	s_waitcnt vmcnt(0)
	s_mov_b64 exec, -1
	v_readlane_b32 s0, v247, 1
	v_readlane_b32 s1, v247, 2
	v_readlane_b32 s6, v247, 0
	v_readlane_b32 s16, v248, 25
	s_nop 1
	s_load_dwordx2 s[4:5], s[0:1], 0x20
	s_lshr_b32 s16, s16, 3
	s_mul_i32 s16, s16, 0xc000
	s_lshr_b32 s20, s6, 1
	s_lshl_b32 s20, s20, 6
	s_and_b32 s2, s6, 1
	s_lshl_b32 s2, s2, 9
	s_waitcnt lgkmcnt(0)
	s_add_u32 s4, s4, s16
	s_addc_u32 s5, s5, 0
	s_load_dwordx2 s[8:9], s[0:1], 0xe8
	v_lshrrev_b32_e32 v7, 6, v234
	s_mov_b32 s12, 0xbfb8aa3b
	v_readfirstlane_b32 s11, v7
	s_mov_b32 s13, 0xbfb8aa3b
	s_mov_b32 s14, 1.0
	s_mov_b32 s15, 1.0
	v_lshlrev_b32_e32 v7, 3, v237
	v_add_u32_e32 v7, s2, v7
	v_lshlrev_b32_e32 v0, 1, v7
	v_lshlrev_b32_e32 v3, 2, v7
	v_add_u32_e32 v1, 0x800, v0
	v_add_u32_e32 v2, 0x1000, v0
	v_add_u32_e32 v4, 0x1f100000, v0
	v_add_u32_e32 v5, 0x20100000, v0
	v_add_u32_e32 v6, 0x21100000, v0
	s_lshl_b32 s3, s11, 3
	s_add_u32 s3, s3, s20
	s_add_i32 s10, s3, -3
	s_lshl_b32 s3, s3, 11
	s_waitcnt lgkmcnt(0)
	s_add_u32 s6, s8, s3
	s_addc_u32 s7, s9, 0
	s_mul_i32 s3, s10, 0x7e00
	s_ashr_i32 vcc_lo, s3, 31
	s_add_u32 s100, s8, s3
	s_addc_u32 s101, s9, vcc_lo
	s_add_u32 s100, s100, 0x9c00000
	s_addc_u32 s101, s101, 0
	global_load_dwordx4 v[96:99], v3, s[4:5]
	global_load_dwordx4 v[100:103], v3, s[4:5] offset:16
	s_add_u32 vcc_lo, s4, 0x3000
	s_addc_u32 vcc_hi, s5, 0
	global_load_dwordx4 v[104:107], v3, vcc
	global_load_dwordx4 v[108:111], v3, vcc offset:16
	s_add_u32 vcc_lo, s4, 0x6000
	s_addc_u32 vcc_hi, s5, 0
	global_load_dwordx4 v[112:115], v3, vcc
	global_load_dwordx4 v[116:119], v3, vcc offset:16
	s_add_u32 vcc_lo, s4, 0x9000
	s_addc_u32 vcc_hi, s5, 0
	global_load_dwordx4 v[120:123], v3, vcc
	global_load_dwordx4 v[124:127], v3, vcc offset:16
	global_load_dwordx4 v[52:55], v0, s[100:101]
	s_add_u32 s100, s100, 0x7e00
	s_addc_u32 s101, s101, 0
	global_load_dwordx4 v[56:59], v0, s[100:101]
	s_add_u32 s100, s100, 0x7e00
	s_addc_u32 s101, s101, 0
	global_load_dwordx4 v[60:63], v0, s[100:101]
	s_add_u32 s100, s100, 0x7e00
	s_addc_u32 s101, s101, 0
	global_load_dwordx4 v[64:67], v0, s[100:101]
	s_add_u32 s100, s100, 0x7e00
	s_addc_u32 s101, s101, 0
	global_load_dwordx4 v[68:71], v0, s[100:101]
	s_add_u32 s100, s100, 0x7e00
	s_addc_u32 s101, s101, 0
	global_load_dwordx4 v[72:75], v0, s[100:101]
	s_add_u32 s100, s100, 0x7e00
	s_addc_u32 s101, s101, 0
	global_load_dwordx4 v[76:79], v0, s[100:101]
	s_add_u32 s100, s100, 0x7e00
	s_addc_u32 s101, s101, 0
	global_load_dwordx4 v[80:83], v0, s[100:101]
	s_add_u32 s100, s100, 0x7e00
	s_addc_u32 s101, s101, 0
	global_load_dwordx4 v[84:87], v0, s[100:101]
	s_add_u32 s100, s100, 0x7e00
	s_addc_u32 s101, s101, 0
	global_load_dwordx4 v[88:91], v0, s[100:101]
	s_add_u32 s100, s100, 0x7e00
	s_addc_u32 s101, s101, 0
	global_load_dwordx4 v[92:95], v0, s[100:101]
	s_sub_u32 s100, s100, 0x4ec00
	s_subb_u32 s101, s101, 0
	s_add_u32 vcc_lo, s4, 0x1000
	s_addc_u32 vcc_hi, s5, 0
	global_load_dwordx4 v[8:11], v3, vcc
	global_load_dwordx4 v[12:15], v3, vcc offset:16
	s_add_u32 vcc_lo, s4, 0x4000
	s_addc_u32 vcc_hi, s5, 0
	global_load_dwordx4 v[16:19], v3, vcc
	global_load_dwordx4 v[20:23], v3, vcc offset:16
	s_add_u32 vcc_lo, s4, 0x7000
	s_addc_u32 vcc_hi, s5, 0
	global_load_dwordx4 v[24:27], v3, vcc
	global_load_dwordx4 v[28:31], v3, vcc offset:16
	s_add_u32 vcc_lo, s4, 0xa000
	s_addc_u32 vcc_hi, s5, 0
	global_load_dwordx4 v[32:35], v3, vcc
	global_load_dwordx4 v[36:39], v3, vcc offset:16
	s_waitcnt vmcnt(16)
	s_cmp_lt_i32 s10, 0
	s_cbranch_scc0 .Ldnc_nz0
	v_mov_b32_e32 v52, 0
	v_mov_b32_e32 v53, 0
	v_mov_b32_e32 v54, 0
	v_mov_b32_e32 v55, 0
	v_mov_b32_e32 v56, 0
	v_mov_b32_e32 v57, 0
	v_mov_b32_e32 v58, 0
	v_mov_b32_e32 v59, 0
	v_mov_b32_e32 v60, 0
	v_mov_b32_e32 v61, 0
	v_mov_b32_e32 v62, 0
	v_mov_b32_e32 v63, 0

; __device__ __forceinline__ float bf2f(bf16_t b) { return __uint_as_float(((unsigned)b) << 16); }
; __device__ __forceinline__ float softplusf_(float x) { return fmaxf(x, 0.f) + __logf(1.0f + __expf(-fabsf(x))); }
;     template <class Tp> __device__ __forceinline__ Tp* W(size_t off) const { return (Tp*)(ws + off); }
; __device__ void prep_ssd(const Ctx& c, int ck, int blk) {
;     ...
;     const int tid = c.tid, t0 = ck * 64;
;     float* dt_s = c.ldsf; float* acs_s = c.ldsf + 512;
;     __syncthreads();
;     if (blk < 2) {
;         { const int hh = tid >> 6, l = tid & 63, h = blk * 8 + hh;
;           const float raw = bf2f(proj[(size_t)(t0 + l) * NP + C_SDT + h]);
;           const float dt = softplusf_(raw + c.in(I_SDTB)[c.layer * 16 + h]);
;           float a = dt * (-__expf(c.in(I_SALOG)[c.layer * 16 + h]));
; #pragma unroll
;           for (int d = 1; d < 64; d <<= 1) { const float o = __shfl_up(a, d); if (l >= d) a += o; }
;           dt_s[tid] = dt; acs_s[tid] = a; }
;         __syncthreads();
;         { const int h = blk * 8 + (tid >> 6); c.W<float>(WS_SACS)[(size_t)(ck * 16 + h) * 64 + (tid & 63)] = acs_s[tid]; }
;         const int ch = blk * 512 + tid, h = ch >> 6, p = ch & 63, hh = tid >> 6;
;         const float w0 = cw[ch], w1 = cw[1536 + ch], w2 = cw[2 * 1536 + ch], w3 = cw[3 * 1536 + ch], bb = cb[ch];
;         float xm3 = 0.f, xm2 = 0.f, xm1 = 0.f;
;         if (t0 > 0) { xm3 = bf2f(proj[(size_t)(t0 - 3) * NP + C_SX + ch]); xm2 = bf2f(proj[(size_t)(t0 - 2) * NP + C_SX + ch]); xm1 = bf2f(proj[(size_t)(t0 - 1) * NP + C_SX + ch]); }
;         const float acl = acs_s[hh * 64 + 63];
.Lprep_entry:
	s_mov_b64 exec, -1
	v_readlane_b32 s0, v247, 1
	v_readlane_b32 s1, v247, 2
	v_readlane_b32 s6, v247, 0
	v_readlane_b32 s16, v248, 25
	v_readfirstlane_b32 s9, v234
	s_load_dwordx2 s[4:5], s[0:1], 0xe8
	s_lshr_b32 s16, s16, 3
	s_lshr_b32 s9, s9, 6
	s_lshr_b32 s7, s6, 1
	s_and_b32 s8, s6, 1
	s_lshl_b32 s15, s7, 6
	v_and_b32_e32 v3, 63, v234
	s_mov_b32 s18, 0xbfb8aa3b
	s_mov_b32 s19, 0xbfb8aa3b
	s_mov_b32 s28, 0xbfb8aa3b
	s_mov_b32 s36, 1.0
	s_mov_b32 s37, 1.0
	s_lshl_b32 s17, s9, 3
	s_add_u32 s17, s17, s15
	s_add_i32 s10, s17, -3
	s_waitcnt lgkmcnt(0)
	s_mul_i32 s22, s10, 0x7e00
	s_ashr_i32 s23, s22, 31
	s_add_u32 s38, s4, s22
	s_addc_u32 s39, s5, s23
	s_add_u32 s38, s38, 0x9c00000
	s_addc_u32 s39, s39, 0
	s_lshl_b32 s13, s8, 3
	s_add_u32 s13, s13, s9
	v_add_u32_e32 v12, s15, v3
	s_mov_b32 s25, 0x7e00
	v_mul_lo_u32 v12, v12, s25
	s_lshl_b32 s22, s13, 1
	v_add_u32_e32 v12, s22, v12
	v_add_u32_e32 v12, 0x9c03420, v12
	global_load_ushort v13, v12, s[4:5]
	s_load_dwordx2 s[32:33], s[0:1], 0x50
	s_load_dwordx2 s[34:35], s[0:1], 0x58
	s_lshl_b32 s22, s16, 4
	s_add_u32 s22, s22, s13
	s_lshl_b32 s22, s22, 2
	s_waitcnt lgkmcnt(0)
	s_load_dword s26, s[32:33], s22
	s_load_dword s27, s[34:35], s22
	v_lshlrev_b32_e32 v0, 3, v3
	s_lshl_b32 s22, s8, 9
	v_add_u32_e32 v0, s22, v0
	v_lshlrev_b32_e32 v1, 2, v0
	v_lshlrev_b32_e32 v0, 1, v0
	v_add_u32_e32 v2, 0x29901000, v0
	v_add_u32_e32 v0, 0x2820, v0
	s_mov_b64 s[100:101], s[38:39]
	global_load_dwordx4 v[16:19], v0, s[100:101]
	s_add_u32 s100, s100, 0x7e00
	s_addc_u32 s101, s101, 0
	global_load_dwordx4 v[20:23], v0, s[100:101]
	s_add_u32 s100, s100, 0x7e00
	s_addc_u32 s101, s101, 0
	global_load_dwordx4 v[24:27], v0, s[100:101]
	s_add_u32 s100, s100, 0x7e00
	s_addc_u32 s101, s101, 0
	global_load_dwordx4 v[28:31], v0, s[100:101]
	s_add_u32 s100, s100, 0x7e00
	s_addc_u32 s101, s101, 0
	global_load_dwordx4 v[32:35], v0, s[100:101]
	s_add_u32 s100, s100, 0x7e00
	s_addc_u32 s101, s101, 0
	global_load_dwordx4 v[36:39], v0, s[100:101]
	s_add_u32 s100, s100, 0x7e00
	s_addc_u32 s101, s101, 0
	global_load_dwordx4 v[40:43], v0, s[100:101]
	s_add_u32 s100, s100, 0x7e00
	s_addc_u32 s101, s101, 0
	global_load_dwordx4 v[44:47], v0, s[100:101]
	s_add_u32 s100, s100, 0x7e00
	s_addc_u32 s101, s101, 0
	global_load_dwordx4 v[48:51], v0, s[100:101]
	s_add_u32 s100, s100, 0x7e00
	s_addc_u32 s101, s101, 0
	global_load_dwordx4 v[52:55], v0, s[100:101]
	s_add_u32 s100, s100, 0x7e00
	s_addc_u32 s101, s101, 0
	global_load_dwordx4 v[56:59], v0, s[100:101]
	s_load_dwordx2 s[40:41], s[0:1], 0x40
	s_load_dwordx2 s[42:43], s[0:1], 0x48
	s_mul_i32 s22, s16, 0x6000
	s_mul_i32 s23, s16, 0x1800
	s_waitcnt lgkmcnt(0)
	s_add_u32 s40, s40, s22
	s_addc_u32 s41, s41, 0
	s_add_u32 s42, s42, s23
	s_addc_u32 s43, s43, 0
	global_load_dwordx4 v[60:63], v1, s[40:41] offset:0
	global_load_dwordx4 v[64:67], v1, s[40:41] offset:16
	s_add_u32 s40, s40, 0x1800
	s_addc_u32 s41, s41, 0
	global_load_dwordx4 v[68:71], v1, s[40:41] offset:0
	global_load_dwordx4 v[72:75], v1, s[40:41] offset:16
	s_add_u32 s40, s40, 0x1800
	s_addc_u32 s41, s41, 0
	global_load_dwordx4 v[76:79], v1, s[40:41] offset:0
	global_load_dwordx4 v[80:83], v1, s[40:41] offset:16
	s_add_u32 s40, s40, 0x1800
	s_addc_u32 s41, s41, 0
	global_load_dwordx4 v[84:87], v1, s[40:41] offset:0
	global_load_dwordx4 v[88:91], v1, s[40:41] offset:16
	global_load_dwordx4 v[92:95], v1, s[42:43] offset:0
	global_load_dwordx4 v[96:99], v1, s[42:43] offset:16
	s_waitcnt vmcnt(21) lgkmcnt(0)
	v_lshlrev_b32_e32 v13, 16, v13
	v_add_f32_e32 v14, s26, v13
	v_mul_f32_e64 v15, |v14|, s28
	v_exp_f32_e32 v15, v15
	v_max_f32_e32 v14, 0, v14
	v_add_f32_e32 v15, 1.0, v15
	v_log_f32_e32 v15, v15
	s_nop 0
	v_fmac_f32_e32 v14, 0x3f317218, v15
	v_mov_b32_e32 v12, s27
	v_mul_f32_e32 v12, 0x3fb8aa3b, v12
	v_exp_f32_e32 v12, v12
	s_nop 0
	v_mul_f32_e64 v15, v14, -v12
	v_subrev_u32_e32 v12, 1, v3
	v_max_i32_e32 v12, 0, v12
	v_lshlrev_b32_e32 v12, 2, v12
	ds_bpermute_b32 v13, v12, v15
	v_cmp_le_u32_e32 vcc, 1, v3
	s_waitcnt lgkmcnt(0)
	v_add_f32_e32 v13, v15, v13
	v_cndmask_b32_e32 v15, v15, v13, vcc
	v_subrev_u32_e32 v12, 2, v3
	v_max_i32_e32 v12, 0, v12
	v_lshlrev_b32_e32 v12, 2, v12
	ds_bpermute_b32 v13, v12, v15
	v_cmp_le_u32_e32 vcc, 2, v3
	s_waitcnt lgkmcnt(0)
	v_add_f32_e32 v13, v15, v13
	v_cndmask_b32_e32 v15, v15, v13, vcc
	v_subrev_u32_e32 v12, 4, v3
	v_max_i32_e32 v12, 0, v12
	v_lshlrev_b32_e32 v12, 2, v12
	ds_bpermute_b32 v13, v12, v15
	v_cmp_le_u32_e32 vcc, 4, v3
	s_waitcnt lgkmcnt(0)
	v_add_f32_e32 v13, v15, v13
	v_cndmask_b32_e32 v15, v15, v13, vcc
	v_subrev_u32_e32 v12, 8, v3
	v_max_i32_e32 v12, 0, v12
	v_lshlrev_b32_e32 v12, 2, v12
	ds_bpermute_b32 v13, v12, v15
	v_cmp_le_u32_e32 vcc, 8, v3
	s_waitcnt lgkmcnt(0)
	v_add_f32_e32 v13, v15, v13
	v_cndmask_b32_e32 v15, v15, v13, vcc
	v_subrev_u32_e32 v12, 16, v3
	v_max_i32_e32 v12, 0, v12
	v_lshlrev_b32_e32 v12, 2, v12
	ds_bpermute_b32 v13, v12, v15
	v_cmp_le_u32_e32 vcc, 16, v3
	s_waitcnt lgkmcnt(0)
	v_add_f32_e32 v13, v15, v13
	v_cndmask_b32_e32 v15, v15, v13, vcc
	v_subrev_u32_e32 v12, 32, v3
	v_max_i32_e32 v12, 0, v12
	v_lshlrev_b32_e32 v12, 2, v12
	ds_bpermute_b32 v13, v12, v15
	v_cmp_le_u32_e32 vcc, 32, v3
	s_waitcnt lgkmcnt(0)
	v_add_f32_e32 v13, v15, v13
	v_cndmask_b32_e32 v15, v15, v13, vcc
	s_nop 1
	v_readlane_b32 s29, v15, 63
	v_lshlrev_b32_e32 v12, 2, v3
	s_lshl_b32 s22, s9, 8
	v_add_u32_e32 v12, s22, v12
	ds_write_b32 v12, v14 offset:0
	v_sub_f32_e32 v13, s29, v15
	v_mul_f32_e32 v13, 0x3fb8aa3b, v13
	v_exp_f32_e32 v13, v13
	s_lshl_b32 s22, s7, 4
	s_add_u32 s22, s22, s13
	s_lshl_b32 s22, s22, 8
	v_lshl_add_u32 v14, v3, 2, s22
	v_add_u32_e32 v14, 0x30501000, v14
	global_store_dword v14, v15, s[4:5]
	ds_write_b32 v12, v13 offset:2048
	s_waitcnt lgkmcnt(0)
	s_barrier
	v_lshrrev_b32_e32 v6, 3, v3
	v_lshlrev_b32_e32 v6, 8, v6
	s_lshl_b32 s22, s9, 5
	v_add_u32_e32 v6, s22, v6
	ds_read_b128 v[224:227], v6 offset:0
	ds_read_b128 v[228:231], v6 offset:16
	ds_read_b128 v[8:11], v6 offset:2048
	ds_read_b128 v[12:15], v6 offset:2064
	s_lshl_b32 s22, s7, 4
	s_lshl_b32 s23, s8, 3
	s_add_u32 s22, s22, s23
	s_lshl_b32 s22, s22, 13
	v_lshl_add_u32 v4, v3, 10, s22
	s_lshl_b32 s23, s9, 4
	v_add_u32_e32 v4, s23, v4
	v_add_u32_e32 v5, 0x2b901000, v4
	v_add_u32_e32 v4, 0x2a901000, v4
	s_lshl_b32 s22, s17, 11
	s_add_u32 s44, s4, s22
	s_addc_u32 s45, s5, 0
	s_waitcnt vmcnt(0) lgkmcnt(0)
	s_cmp_lt_i32 s10, 0
	s_cbranch_scc0 .Lprep_nz_ssda
	v_mov_b32_e32 v16, 0
	v_mov_b32_e32 v17, 0
	v_mov_b32_e32 v18, 0
	v_mov_b32_e32 v19, 0
	v_mov_b32_e32 v20, 0
	v_mov_b32_e32 v21, 0
	v_mov_b32_e32 v22, 0
	v_mov_b32_e32 v23, 0
	v_mov_b32_e32 v24, 0
	v_mov_b32_e32 v25, 0
	v_mov_b32_e32 v26, 0
	v_mov_b32_e32 v27, 0
; __device__ __forceinline__ unsigned pk2(float lo, float hi) { const f32v2_t v = {lo, hi}; const bf16v2_t b = __builtin_convertvector(v, bf16v2_t); return __builtin_bit_cast(unsigned, b); }
; __device__ __forceinline__ float siluf_(float x) { return x * __builtin_amdgcn_rcpf(1.0f + __expf(-x)); }
; #define PIN16(a, o) asm volatile("" : "+v"(a[(o)+0]), "+v"(a[(o)+1]), "+v"(a[(o)+2]), "+v"(a[(o)+3]), "+v"(a[(o)+4]), "+v"(a[(o)+5]), "+v"(a[(o)+6]), "+v"(a[(o)+7]), \
;     "+v"(a[(o)+8]), "+v"(a[(o)+9]), "+v"(a[(o)+10]), "+v"(a[(o)+11]), "+v"(a[(o)+12]), "+v"(a[(o)+13]), "+v"(a[(o)+14]), "+v"(a[(o)+15]))
; __device__ void prep_ssd(const Ctx& c, int ck, int blk) {
;     ...
;           for (int l = 0; l < 64; ++l) rw[l] = proj[(size_t)(t0 + l) * NP + C_SX + ch];
;           PIN16(rw, 0); PIN16(rw, 16); PIN16(rw, 32); PIN16(rw, 48);
; #pragma unroll
;           for (int l = 0; l < 64; ++l) raw[l] = __uint_as_float(rw[l] << 16); }
; #pragma unroll
;         for (int l0 = 0; l0 < 64; l0 += 8) {
;             float xd[8], xw[8];
; #pragma unroll
;             for (int j = 0; j < 8; ++j) { const int l = l0 + j;
;                 const float xc = raw[l];
;                 const float y = w0 * xm3 + w1 * xm2 + w2 * xm1 + w3 * xc + bb; xm3 = xm2; xm2 = xm1; xm1 = xc;
;                 const float x = siluf_(y);
;                 sX[(size_t)(t0 + l) * 1024 + ch] = f2bf(x);
;                 const float dtl = dt_s[hh * 64 + l];
;                 xd[j] = x * dtl; xw[j] = x * dtl * __expf(acl - acs_s[hh * 64 + l]); }
;             u32x4 a, b; a.x = pk2(xd[0], xd[1]); a.y = pk2(xd[2], xd[3]); a.z = pk2(xd[4], xd[5]); a.w = pk2(xd[6], xd[7]);
;             b.x = pk2(xw[0], xw[1]); b.y = pk2(xw[2], xw[3]); b.z = pk2(xw[4], xw[5]); b.w = pk2(xw[6], xw[7]);
;             const size_t o = ((size_t)(ck * 16 + h) * 64 + p) * 64 + l0;
;             *(u32x4*)(sXdT + o) = a; *(u32x4*)(sXwT + o) = b;
;         }
.Lprep_nz_ssda:
	v_lshlrev_b32_e32 v132, 16, v16
	v_and_b32_e32 v133, 0xffff0000, v16
	v_lshlrev_b32_e32 v134, 16, v17
	v_and_b32_e32 v135, 0xffff0000, v17
	v_lshlrev_b32_e32 v136, 16, v20
	v_and_b32_e32 v137, 0xffff0000, v20
	v_lshlrev_b32_e32 v138, 16, v21
	v_and_b32_e32 v139, 0xffff0000, v21
	v_lshlrev_b32_e32 v140, 16, v24
	v_and_b32_e32 v141, 0xffff0000, v24
	v_lshlrev_b32_e32 v142, 16, v25
	v_and_b32_e32 v143, 0xffff0000, v25
	v_lshlrev_b32_e32 v144, 16, v28
	v_and_b32_e32 v145, 0xffff0000, v28
	v_lshlrev_b32_e32 v146, 16, v29
	v_and_b32_e32 v147, 0xffff0000, v29
	v_pk_mul_f32 v[148:149], v[60:61], v[132:133]
	v_pk_mul_f32 v[150:151], v[62:63], v[134:135]
	v_pk_fma_f32 v[148:149], v[68:69], v[136:137], v[148:149]
	v_pk_fma_f32 v[150:151], v[70:71], v[138:139], v[150:151]
	v_pk_fma_f32 v[148:149], v[76:77], v[140:141], v[148:149]
	v_pk_fma_f32 v[150:151], v[78:79], v[142:143], v[150:151]
	v_pk_fma_f32 v[148:149], v[84:85], v[144:145], v[148:149]
	v_pk_fma_f32 v[150:151], v[86:87], v[146:147], v[150:151]
	v_pk_add_f32 v[148:149], v[148:149], v[92:93]
	v_pk_add_f32 v[150:151], v[150:151], v[94:95]
	v_pk_mul_f32 v[152:153], v[148:149], s[18:19]
	v_pk_mul_f32 v[154:155], v[150:151], s[18:19]
	v_exp_f32_e32 v152, v152
	v_exp_f32_e32 v153, v153
	v_exp_f32_e32 v154, v154
	v_exp_f32_e32 v155, v155
	v_pk_add_f32 v[152:153], v[152:153], s[36:37]
	v_pk_add_f32 v[154:155], v[154:155], s[36:37]
	v_rcp_f32_e32 v152, v152
	v_rcp_f32_e32 v153, v153
	v_rcp_f32_e32 v154, v154
	v_rcp_f32_e32 v155, v155
	s_nop 0
	v_pk_mul_f32 v[148:149], v[148:149], v[152:153]
	v_pk_mul_f32 v[150:151], v[150:151], v[154:155]
	v_cvt_pk_bf16_f32 v100, v148, v149
	v_cvt_pk_bf16_f32 v101, v150, v151
	v_mul_f32_e32 v156, v148, v224
	v_mul_f32_e32 v157, v149, v224
	v_mul_f32_e32 v158, v150, v224
	v_mul_f32_e32 v159, v151, v224
	v_mul_f32_e32 v160, v156, v8
	v_mul_f32_e32 v161, v157, v8
	v_mul_f32_e32 v162, v158, v8
	v_mul_f32_e32 v163, v159, v8
	v_lshlrev_b32_e32 v132, 16, v32
	v_and_b32_e32 v133, 0xffff0000, v32
	v_lshlrev_b32_e32 v134, 16, v33
	v_and_b32_e32 v135, 0xffff0000, v33
	v_pk_mul_f32 v[148:149], v[60:61], v[136:137]
	v_pk_mul_f32 v[150:151], v[62:63], v[138:139]
	v_pk_fma_f32 v[148:149], v[68:69], v[140:141], v[148:149]
	v_pk_fma_f32 v[150:151], v[70:71], v[142:143], v[150:151]
	v_pk_fma_f32 v[148:149], v[76:77], v[144:145], v[148:149]
	v_pk_fma_f32 v[150:151], v[78:79], v[146:147], v[150:151]
	v_pk_fma_f32 v[148:149], v[84:85], v[132:133], v[148:149]
	v_pk_fma_f32 v[150:151], v[86:87], v[134:135], v[150:151]
	v_pk_add_f32 v[148:149], v[148:149], v[92:93]
	v_pk_add_f32 v[150:151], v[150:151], v[94:95]
	v_pk_mul_f32 v[152:153], v[148:149], s[18:19]
	v_pk_mul_f32 v[154:155], v[150:151], s[18:19]
	v_exp_f32_e32 v152, v152
	v_exp_f32_e32 v153, v153
	v_exp_f32_e32 v154, v154
	v_exp_f32_e32 v155, v155
	v_pk_add_f32 v[152:153], v[152:153], s[36:37]
	v_pk_add_f32 v[154:155], v[154:155], s[36:37]
	v_rcp_f32_e32 v152, v152
	v_rcp_f32_e32 v153, v153
	v_rcp_f32_e32 v154, v154
	v_rcp_f32_e32 v155, v155
	s_nop 0
	v_pk_mul_f32 v[148:149], v[148:149], v[152:153]
	v_pk_mul_f32 v[150:151], v[150:151], v[154:155]
	v_cvt_pk_bf16_f32 v104, v148, v149
	v_cvt_pk_bf16_f32 v105, v150, v151
	v_mul_f32_e32 v164, v148, v225
	v_mul_f32_e32 v165, v149, v225
	v_mul_f32_e32 v166, v150, v225
	v_mul_f32_e32 v167, v151, v225
	v_mul_f32_e32 v168, v164, v9
	v_mul_f32_e32 v169, v165, v9
	v_mul_f32_e32 v170, v166, v9
	v_mul_f32_e32 v171, v167, v9
	v_cvt_pk_bf16_f32 v192, v156, v164
	v_cvt_pk_bf16_f32 v208, v160, v168
	v_cvt_pk_bf16_f32 v196, v157, v165
	v_cvt_pk_bf16_f32 v212, v161, v169
	v_cvt_pk_bf16_f32 v200, v158, v166
	v_cvt_pk_bf16_f32 v216, v162, v170
	v_cvt_pk_bf16_f32 v204, v159, v167
	v_cvt_pk_bf16_f32 v220, v163, v171
	v_lshlrev_b32_e32 v136, 16, v36
	v_and_b32_e32 v137, 0xffff0000, v36
	v_lshlrev_b32_e32 v138, 16, v37
	v_and_b32_e32 v139, 0xffff0000, v37
	v_pk_mul_f32 v[148:149], v[60:61], v[140:141]
	v_pk_mul_f32 v[150:151], v[62:63], v[142:143]
	v_pk_fma_f32 v[148:149], v[68:69], v[144:145], v[148:149]
	v_pk_fma_f32 v[150:151], v[70:71], v[146:147], v[150:151]
	v_pk_fma_f32 v[148:149], v[76:77], v[132:133], v[148:149]
	v_pk_fma_f32 v[150:151], v[78:79], v[134:135], v[150:151]
	v_pk_fma_f32 v[148:149], v[84:85], v[136:137], v[148:149]
	v_pk_fma_f32 v[150:151], v[86:87], v[138:139], v[150:151]
	v_pk_add_f32 v[148:149], v[148:149], v[92:93]
	v_pk_add_f32 v[150:151], v[150:151], v[94:95]
	v_pk_mul_f32 v[152:153], v[148:149], s[18:19]
	v_pk_mul_f32 v[154:155], v[150:151], s[18:19]
	v_exp_f32_e32 v152, v152
	v_exp_f32_e32 v153, v153
	v_exp_f32_e32 v154, v154
	v_exp_f32_e32 v155, v155
	v_pk_add_f32 v[152:153], v[152:153], s[36:37]
	v_pk_add_f32 v[154:155], v[154:155], s[36:37]
	v_rcp_f32_e32 v152, v152
	v_rcp_f32_e32 v153, v153
	v_rcp_f32_e32 v154, v154
	v_rcp_f32_e32 v155, v155
	s_nop 0
	v_pk_mul_f32 v[148:149], v[148:149], v[152:153]
	v_pk_mul_f32 v[150:151], v[150:151], v[154:155]
	v_cvt_pk_bf16_f32 v108, v148, v149
	v_cvt_pk_bf16_f32 v109, v150, v151
	v_mul_f32_e32 v156, v148, v226
	v_mul_f32_e32 v157, v149, v226
	v_mul_f32_e32 v158, v150, v226
	v_mul_f32_e32 v159, v151, v226
	v_mul_f32_e32 v160, v156, v10
	v_mul_f32_e32 v161, v157, v10
	v_mul_f32_e32 v162, v158, v10
	v_mul_f32_e32 v163, v159, v10
	v_lshlrev_b32_e32 v140, 16, v40
	v_and_b32_e32 v141, 0xffff0000, v40
	v_lshlrev_b32_e32 v142, 16, v41
	v_and_b32_e32 v143, 0xffff0000, v41
	v_pk_mul_f32 v[148:149], v[60:61], v[144:145]
	v_pk_mul_f32 v[150:151], v[62:63], v[146:147]
	v_pk_fma_f32 v[148:149], v[68:69], v[132:133], v[148:149]
	v_pk_fma_f32 v[150:151], v[70:71], v[134:135], v[150:151]
	v_pk_fma_f32 v[148:149], v[76:77], v[136:137], v[148:149]
; __device__ __forceinline__ unsigned pk2(float lo, float hi) { const f32v2_t v = {lo, hi}; const bf16v2_t b = __builtin_convertvector(v, bf16v2_t); return __builtin_bit_cast(unsigned, b); }
; __device__ __forceinline__ float siluf_(float x) { return x * __builtin_amdgcn_rcpf(1.0f + __expf(-x)); }
; #define PIN16(a, o) asm volatile("" : "+v"(a[(o)+0]), "+v"(a[(o)+1]), "+v"(a[(o)+2]), "+v"(a[(o)+3]), "+v"(a[(o)+4]), "+v"(a[(o)+5]), "+v"(a[(o)+6]), "+v"(a[(o)+7]), \
;     "+v"(a[(o)+8]), "+v"(a[(o)+9]), "+v"(a[(o)+10]), "+v"(a[(o)+11]), "+v"(a[(o)+12]), "+v"(a[(o)+13]), "+v"(a[(o)+14]), "+v"(a[(o)+15]))
; __device__ void prep_ssd(const Ctx& c, int ck, int blk) {
;     ...
;           for (int l = 0; l < 64; ++l) rw[l] = proj[(size_t)(t0 + l) * NP + C_SX + ch];
;           PIN16(rw, 0); PIN16(rw, 16); PIN16(rw, 32); PIN16(rw, 48);
; #pragma unroll
;           for (int l = 0; l < 64; ++l) raw[l] = __uint_as_float(rw[l] << 16); }
; #pragma unroll
;         for (int l0 = 0; l0 < 64; l0 += 8) {
;             float xd[8], xw[8];
; #pragma unroll
;             for (int j = 0; j < 8; ++j) { const int l = l0 + j;
;                 const float xc = raw[l];
;                 const float y = w0 * xm3 + w1 * xm2 + w2 * xm1 + w3 * xc + bb; xm3 = xm2; xm2 = xm1; xm1 = xc;
;                 const float x = siluf_(y);
;                 sX[(size_t)(t0 + l) * 1024 + ch] = f2bf(x);
;                 const float dtl = dt_s[hh * 64 + l];
;                 xd[j] = x * dtl; xw[j] = x * dtl * __expf(acl - acs_s[hh * 64 + l]); }
;             u32x4 a, b; a.x = pk2(xd[0], xd[1]); a.y = pk2(xd[2], xd[3]); a.z = pk2(xd[4], xd[5]); a.w = pk2(xd[6], xd[7]);
;             b.x = pk2(xw[0], xw[1]); b.y = pk2(xw[2], xw[3]); b.z = pk2(xw[4], xw[5]); b.w = pk2(xw[6], xw[7]);
;             const size_t o = ((size_t)(ck * 16 + h) * 64 + p) * 64 + l0;
;             *(u32x4*)(sXdT + o) = a; *(u32x4*)(sXwT + o) = b;
;         }
	v_pk_fma_f32 v[150:151], v[78:79], v[138:139], v[150:151]
	v_pk_fma_f32 v[148:149], v[84:85], v[140:141], v[148:149]
	v_pk_fma_f32 v[150:151], v[86:87], v[142:143], v[150:151]
	v_pk_add_f32 v[148:149], v[148:149], v[92:93]
	v_pk_add_f32 v[150:151], v[150:151], v[94:95]
	v_pk_mul_f32 v[152:153], v[148:149], s[18:19]
	v_pk_mul_f32 v[154:155], v[150:151], s[18:19]
	v_exp_f32_e32 v152, v152
	v_exp_f32_e32 v153, v153
	v_exp_f32_e32 v154, v154
	v_exp_f32_e32 v155, v155
	v_pk_add_f32 v[152:153], v[152:153], s[36:37]
	v_pk_add_f32 v[154:155], v[154:155], s[36:37]
	v_rcp_f32_e32 v152, v152
	v_rcp_f32_e32 v153, v153
	v_rcp_f32_e32 v154, v154
	v_rcp_f32_e32 v155, v155
	s_nop 0
	v_pk_mul_f32 v[148:149], v[148:149], v[152:153]
	v_pk_mul_f32 v[150:151], v[150:151], v[154:155]
	v_cvt_pk_bf16_f32 v112, v148, v149
	v_cvt_pk_bf16_f32 v113, v150, v151
	v_mul_f32_e32 v164, v148, v227
	v_mul_f32_e32 v165, v149, v227
	v_mul_f32_e32 v166, v150, v227
	v_mul_f32_e32 v167, v151, v227
	v_mul_f32_e32 v168, v164, v11
	v_mul_f32_e32 v169, v165, v11
	v_mul_f32_e32 v170, v166, v11
	v_mul_f32_e32 v171, v167, v11
	v_cvt_pk_bf16_f32 v193, v156, v164
	v_cvt_pk_bf16_f32 v209, v160, v168
	v_cvt_pk_bf16_f32 v197, v157, v165
	v_cvt_pk_bf16_f32 v213, v161, v169
	v_cvt_pk_bf16_f32 v201, v158, v166
	v_cvt_pk_bf16_f32 v217, v162, v170
	v_cvt_pk_bf16_f32 v205, v159, v167
	v_cvt_pk_bf16_f32 v221, v163, v171
	v_lshlrev_b32_e32 v144, 16, v44
	v_and_b32_e32 v145, 0xffff0000, v44
	v_lshlrev_b32_e32 v146, 16, v45
	v_and_b32_e32 v147, 0xffff0000, v45
	v_pk_mul_f32 v[148:149], v[60:61], v[132:133]
	v_pk_mul_f32 v[150:151], v[62:63], v[134:135]
	v_pk_fma_f32 v[148:149], v[68:69], v[136:137], v[148:149]
	v_pk_fma_f32 v[150:151], v[70:71], v[138:139], v[150:151]
	v_pk_fma_f32 v[148:149], v[76:77], v[140:141], v[148:149]
	v_pk_fma_f32 v[150:151], v[78:79], v[142:143], v[150:151]
	v_pk_fma_f32 v[148:149], v[84:85], v[144:145], v[148:149]
	v_pk_fma_f32 v[150:151], v[86:87], v[146:147], v[150:151]
	v_pk_add_f32 v[148:149], v[148:149], v[92:93]
	v_pk_add_f32 v[150:151], v[150:151], v[94:95]
	v_pk_mul_f32 v[152:153], v[148:149], s[18:19]
	v_pk_mul_f32 v[154:155], v[150:151], s[18:19]
	v_exp_f32_e32 v152, v152
	v_exp_f32_e32 v153, v153
	v_exp_f32_e32 v154, v154
	v_exp_f32_e32 v155, v155
	v_pk_add_f32 v[152:153], v[152:153], s[36:37]
	v_pk_add_f32 v[154:155], v[154:155], s[36:37]
	v_rcp_f32_e32 v152, v152
	v_rcp_f32_e32 v153, v153
	v_rcp_f32_e32 v154, v154
	v_rcp_f32_e32 v155, v155
	s_nop 0
	v_pk_mul_f32 v[148:149], v[148:149], v[152:153]
	v_pk_mul_f32 v[150:151], v[150:151], v[154:155]
	v_cvt_pk_bf16_f32 v116, v148, v149
	v_cvt_pk_bf16_f32 v117, v150, v151
	v_mul_f32_e32 v156, v148, v228
	v_mul_f32_e32 v157, v149, v228
	v_mul_f32_e32 v158, v150, v228
	v_mul_f32_e32 v159, v151, v228
	v_mul_f32_e32 v160, v156, v12
	v_mul_f32_e32 v161, v157, v12
	v_mul_f32_e32 v162, v158, v12
	v_mul_f32_e32 v163, v159, v12
	v_lshlrev_b32_e32 v132, 16, v48
	v_and_b32_e32 v133, 0xffff0000, v48
	v_lshlrev_b32_e32 v134, 16, v49
	v_and_b32_e32 v135, 0xffff0000, v49
	v_pk_mul_f32 v[148:149], v[60:61], v[136:137]
	v_pk_mul_f32 v[150:151], v[62:63], v[138:139]
	v_pk_fma_f32 v[148:149], v[68:69], v[140:141], v[148:149]
	v_pk_fma_f32 v[150:151], v[70:71], v[142:143], v[150:151]
	v_pk_fma_f32 v[148:149], v[76:77], v[144:145], v[148:149]
	v_pk_fma_f32 v[150:151], v[78:79], v[146:147], v[150:151]
	v_pk_fma_f32 v[148:149], v[84:85], v[132:133], v[148:149]
	v_pk_fma_f32 v[150:151], v[86:87], v[134:135], v[150:151]
	v_pk_add_f32 v[148:149], v[148:149], v[92:93]
	v_pk_add_f32 v[150:151], v[150:151], v[94:95]
	v_pk_mul_f32 v[152:153], v[148:149], s[18:19]
	v_pk_mul_f32 v[154:155], v[150:151], s[18:19]
	v_exp_f32_e32 v152, v152
	v_exp_f32_e32 v153, v153
	v_exp_f32_e32 v154, v154
	v_exp_f32_e32 v155, v155
	v_pk_add_f32 v[152:153], v[152:153], s[36:37]
	v_pk_add_f32 v[154:155], v[154:155], s[36:37]
	v_rcp_f32_e32 v152, v152
	v_rcp_f32_e32 v153, v153
	v_rcp_f32_e32 v154, v154
	v_rcp_f32_e32 v155, v155
	s_nop 0
	v_pk_mul_f32 v[148:149], v[148:149], v[152:153]
	v_pk_mul_f32 v[150:151], v[150:151], v[154:155]
	v_cvt_pk_bf16_f32 v120, v148, v149
	v_cvt_pk_bf16_f32 v121, v150, v151
	v_mul_f32_e32 v164, v148, v229
	v_mul_f32_e32 v165, v149, v229
	v_mul_f32_e32 v166, v150, v229
	v_mul_f32_e32 v167, v151, v229
	v_mul_f32_e32 v168, v164, v13
	v_mul_f32_e32 v169, v165, v13
	v_mul_f32_e32 v170, v166, v13
	v_mul_f32_e32 v171, v167, v13
	v_cvt_pk_bf16_f32 v194, v156, v164
	v_cvt_pk_bf16_f32 v210, v160, v168
	v_cvt_pk_bf16_f32 v198, v157, v165
	v_cvt_pk_bf16_f32 v214, v161, v169
	v_cvt_pk_bf16_f32 v202, v158, v166
	v_cvt_pk_bf16_f32 v218, v162, v170
	v_cvt_pk_bf16_f32 v206, v159, v167
	v_cvt_pk_bf16_f32 v222, v163, v171
	v_lshlrev_b32_e32 v136, 16, v52
	v_and_b32_e32 v137, 0xffff0000, v52
	v_lshlrev_b32_e32 v138, 16, v53
	v_and_b32_e32 v139, 0xffff0000, v53
	v_pk_mul_f32 v[148:149], v[60:61], v[140:141]
	v_pk_mul_f32 v[150:151], v[62:63], v[142:143]
	v_pk_fma_f32 v[148:149], v[68:69], v[144:145], v[148:149]
	v_pk_fma_f32 v[150:151], v[70:71], v[146:147], v[150:151]
	v_pk_fma_f32 v[148:149], v[76:77], v[132:133], v[148:149]
	v_pk_fma_f32 v[150:151], v[78:79], v[134:135], v[150:151]
	v_pk_fma_f32 v[148:149], v[84:85], v[136:137], v[148:149]
	v_pk_fma_f32 v[150:151], v[86:87], v[138:139], v[150:151]
	v_pk_add_f32 v[148:149], v[148:149], v[92:93]
	v_pk_add_f32 v[150:151], v[150:151], v[94:95]
	v_pk_mul_f32 v[152:153], v[148:149], s[18:19]
	v_pk_mul_f32 v[154:155], v[150:151], s[18:19]
	v_exp_f32_e32 v152, v152
	v_exp_f32_e32 v153, v153
	v_exp_f32_e32 v154, v154
	v_exp_f32_e32 v155, v155
	v_pk_add_f32 v[152:153], v[152:153], s[36:37]
; __device__ __forceinline__ unsigned pk2(float lo, float hi) { const f32v2_t v = {lo, hi}; const bf16v2_t b = __builtin_convertvector(v, bf16v2_t); return __builtin_bit_cast(unsigned, b); }
; __device__ __forceinline__ float siluf_(float x) { return x * __builtin_amdgcn_rcpf(1.0f + __expf(-x)); }
; #define PIN16(a, o) asm volatile("" : "+v"(a[(o)+0]), "+v"(a[(o)+1]), "+v"(a[(o)+2]), "+v"(a[(o)+3]), "+v"(a[(o)+4]), "+v"(a[(o)+5]), "+v"(a[(o)+6]), "+v"(a[(o)+7]), \
;     "+v"(a[(o)+8]), "+v"(a[(o)+9]), "+v"(a[(o)+10]), "+v"(a[(o)+11]), "+v"(a[(o)+12]), "+v"(a[(o)+13]), "+v"(a[(o)+14]), "+v"(a[(o)+15]))
; __device__ void prep_ssd(const Ctx& c, int ck, int blk) {
;     ...
;           for (int l = 0; l < 64; ++l) rw[l] = proj[(size_t)(t0 + l) * NP + C_SX + ch];
;           PIN16(rw, 0); PIN16(rw, 16); PIN16(rw, 32); PIN16(rw, 48);
; #pragma unroll
;           for (int l = 0; l < 64; ++l) raw[l] = __uint_as_float(rw[l] << 16); }
; #pragma unroll
;         for (int l0 = 0; l0 < 64; l0 += 8) {
;             float xd[8], xw[8];
; #pragma unroll
;             for (int j = 0; j < 8; ++j) { const int l = l0 + j;
;                 const float xc = raw[l];
;                 const float y = w0 * xm3 + w1 * xm2 + w2 * xm1 + w3 * xc + bb; xm3 = xm2; xm2 = xm1; xm1 = xc;
;                 const float x = siluf_(y);
;                 sX[(size_t)(t0 + l) * 1024 + ch] = f2bf(x);
;                 const float dtl = dt_s[hh * 64 + l];
;                 xd[j] = x * dtl; xw[j] = x * dtl * __expf(acl - acs_s[hh * 64 + l]); }
;             u32x4 a, b; a.x = pk2(xd[0], xd[1]); a.y = pk2(xd[2], xd[3]); a.z = pk2(xd[4], xd[5]); a.w = pk2(xd[6], xd[7]);
;             b.x = pk2(xw[0], xw[1]); b.y = pk2(xw[2], xw[3]); b.z = pk2(xw[4], xw[5]); b.w = pk2(xw[6], xw[7]);
;             const size_t o = ((size_t)(ck * 16 + h) * 64 + p) * 64 + l0;
;             *(u32x4*)(sXdT + o) = a; *(u32x4*)(sXwT + o) = b;
;         }
	v_pk_add_f32 v[154:155], v[154:155], s[36:37]
	v_rcp_f32_e32 v152, v152
	v_rcp_f32_e32 v153, v153
	v_rcp_f32_e32 v154, v154
	v_rcp_f32_e32 v155, v155
	s_nop 0
	v_pk_mul_f32 v[148:149], v[148:149], v[152:153]
	v_pk_mul_f32 v[150:151], v[150:151], v[154:155]
	v_cvt_pk_bf16_f32 v124, v148, v149
	v_cvt_pk_bf16_f32 v125, v150, v151
	v_mul_f32_e32 v156, v148, v230
	v_mul_f32_e32 v157, v149, v230
	v_mul_f32_e32 v158, v150, v230
	v_mul_f32_e32 v159, v151, v230
	v_mul_f32_e32 v160, v156, v14
	v_mul_f32_e32 v161, v157, v14
	v_mul_f32_e32 v162, v158, v14
	v_mul_f32_e32 v163, v159, v14
	v_lshlrev_b32_e32 v140, 16, v56
	v_and_b32_e32 v141, 0xffff0000, v56
	v_lshlrev_b32_e32 v142, 16, v57
	v_and_b32_e32 v143, 0xffff0000, v57
	v_pk_mul_f32 v[148:149], v[60:61], v[144:145]
	v_pk_mul_f32 v[150:151], v[62:63], v[146:147]
	v_pk_fma_f32 v[148:149], v[68:69], v[132:133], v[148:149]
	v_pk_fma_f32 v[150:151], v[70:71], v[134:135], v[150:151]
	v_pk_fma_f32 v[148:149], v[76:77], v[136:137], v[148:149]
	v_pk_fma_f32 v[150:151], v[78:79], v[138:139], v[150:151]
	v_pk_fma_f32 v[148:149], v[84:85], v[140:141], v[148:149]
	v_pk_fma_f32 v[150:151], v[86:87], v[142:143], v[150:151]
	v_pk_add_f32 v[148:149], v[148:149], v[92:93]
	v_pk_add_f32 v[150:151], v[150:151], v[94:95]
	v_pk_mul_f32 v[152:153], v[148:149], s[18:19]
	v_pk_mul_f32 v[154:155], v[150:151], s[18:19]
	v_exp_f32_e32 v152, v152
	v_exp_f32_e32 v153, v153
	v_exp_f32_e32 v154, v154
	v_exp_f32_e32 v155, v155
	v_pk_add_f32 v[152:153], v[152:153], s[36:37]
	v_pk_add_f32 v[154:155], v[154:155], s[36:37]
	v_rcp_f32_e32 v152, v152
	v_rcp_f32_e32 v153, v153
	v_rcp_f32_e32 v154, v154
	v_rcp_f32_e32 v155, v155
	s_nop 0
	v_pk_mul_f32 v[148:149], v[148:149], v[152:153]
	v_pk_mul_f32 v[150:151], v[150:151], v[154:155]
	v_cvt_pk_bf16_f32 v128, v148, v149
	v_cvt_pk_bf16_f32 v129, v150, v151
	v_mul_f32_e32 v164, v148, v231
	v_mul_f32_e32 v165, v149, v231
	v_mul_f32_e32 v166, v150, v231
	v_mul_f32_e32 v167, v151, v231
	v_mul_f32_e32 v168, v164, v15
	v_mul_f32_e32 v169, v165, v15
	v_mul_f32_e32 v170, v166, v15
	v_mul_f32_e32 v171, v167, v15
	v_cvt_pk_bf16_f32 v195, v156, v164
	v_cvt_pk_bf16_f32 v211, v160, v168
	v_cvt_pk_bf16_f32 v199, v157, v165
	v_cvt_pk_bf16_f32 v215, v161, v169
	v_cvt_pk_bf16_f32 v203, v158, v166
	v_cvt_pk_bf16_f32 v219, v162, v170
	v_cvt_pk_bf16_f32 v207, v159, v167
	v_cvt_pk_bf16_f32 v223, v163, v171
	global_store_dwordx4 v4, v[192:195], s[4:5] offset:0
	global_store_dwordx4 v5, v[208:211], s[4:5] offset:0
	global_store_dwordx4 v4, v[196:199], s[4:5] offset:128
	global_store_dwordx4 v5, v[212:215], s[4:5] offset:128
	global_store_dwordx4 v4, v[200:203], s[4:5] offset:256
	global_store_dwordx4 v5, v[216:219], s[4:5] offset:256
	global_store_dwordx4 v4, v[204:207], s[4:5] offset:384
	global_store_dwordx4 v5, v[220:223], s[4:5] offset:384
	v_lshlrev_b32_e32 v132, 16, v18
	v_and_b32_e32 v133, 0xffff0000, v18
	v_lshlrev_b32_e32 v134, 16, v19
	v_and_b32_e32 v135, 0xffff0000, v19
	v_lshlrev_b32_e32 v136, 16, v22
	v_and_b32_e32 v137, 0xffff0000, v22
	v_lshlrev_b32_e32 v138, 16, v23
	v_and_b32_e32 v139, 0xffff0000, v23
	v_lshlrev_b32_e32 v140, 16, v26
	v_and_b32_e32 v141, 0xffff0000, v26
	v_lshlrev_b32_e32 v142, 16, v27
	v_and_b32_e32 v143, 0xffff0000, v27
	v_lshlrev_b32_e32 v144, 16, v30
	v_and_b32_e32 v145, 0xffff0000, v30
	v_lshlrev_b32_e32 v146, 16, v31
	v_and_b32_e32 v147, 0xffff0000, v31
	v_pk_mul_f32 v[148:149], v[64:65], v[132:133]
	v_pk_mul_f32 v[150:151], v[66:67], v[134:135]
	v_pk_fma_f32 v[148:149], v[72:73], v[136:137], v[148:149]
	v_pk_fma_f32 v[150:151], v[74:75], v[138:139], v[150:151]
	v_pk_fma_f32 v[148:149], v[80:81], v[140:141], v[148:149]
	v_pk_fma_f32 v[150:151], v[82:83], v[142:143], v[150:151]
	v_pk_fma_f32 v[148:149], v[88:89], v[144:145], v[148:149]
	v_pk_fma_f32 v[150:151], v[90:91], v[146:147], v[150:151]
	v_pk_add_f32 v[148:149], v[148:149], v[96:97]
	v_pk_add_f32 v[150:151], v[150:151], v[98:99]
	v_pk_mul_f32 v[152:153], v[148:149], s[18:19]
	v_pk_mul_f32 v[154:155], v[150:151], s[18:19]
	v_exp_f32_e32 v152, v152
	v_exp_f32_e32 v153, v153
	v_exp_f32_e32 v154, v154
	v_exp_f32_e32 v155, v155
	v_pk_add_f32 v[152:153], v[152:153], s[36:37]
	v_pk_add_f32 v[154:155], v[154:155], s[36:37]
	v_rcp_f32_e32 v152, v152
	v_rcp_f32_e32 v153, v153
	v_rcp_f32_e32 v154, v154
	v_rcp_f32_e32 v155, v155
	s_nop 0
	v_pk_mul_f32 v[148:149], v[148:149], v[152:153]
	v_pk_mul_f32 v[150:151], v[150:151], v[154:155]
	v_cvt_pk_bf16_f32 v102, v148, v149
	v_cvt_pk_bf16_f32 v103, v150, v151
	v_mul_f32_e32 v156, v148, v224
	v_mul_f32_e32 v157, v149, v224
	v_mul_f32_e32 v158, v150, v224
	v_mul_f32_e32 v159, v151, v224
	v_mul_f32_e32 v160, v156, v8
	v_mul_f32_e32 v161, v157, v8
	v_mul_f32_e32 v162, v158, v8
	v_mul_f32_e32 v163, v159, v8
	global_store_dwordx4 v2, v[100:103], s[44:45]
	s_add_u32 s44, s44, 0x800
	s_addc_u32 s45, s45, 0
	v_lshlrev_b32_e32 v132, 16, v34
	v_and_b32_e32 v133, 0xffff0000, v34
	v_lshlrev_b32_e32 v134, 16, v35
	v_and_b32_e32 v135, 0xffff0000, v35
	v_pk_mul_f32 v[148:149], v[64:65], v[136:137]
	v_pk_mul_f32 v[150:151], v[66:67], v[138:139]
	v_pk_fma_f32 v[148:149], v[72:73], v[140:141], v[148:149]
	v_pk_fma_f32 v[150:151], v[74:75], v[142:143], v[150:151]
	v_pk_fma_f32 v[148:149], v[80:81], v[144:145], v[148:149]
	v_pk_fma_f32 v[150:151], v[82:83], v[146:147], v[150:151]
	v_pk_fma_f32 v[148:149], v[88:89], v[132:133], v[148:149]
	v_pk_fma_f32 v[150:151], v[90:91], v[134:135], v[150:151]
	v_pk_add_f32 v[148:149], v[148:149], v[96:97]
	v_pk_add_f32 v[150:151], v[150:151], v[98:99]
	v_pk_mul_f32 v[152:153], v[148:149], s[18:19]
	v_pk_mul_f32 v[154:155], v[150:151], s[18:19]
	v_exp_f32_e32 v152, v152
; __device__ __forceinline__ unsigned pk2(float lo, float hi) { const f32v2_t v = {lo, hi}; const bf16v2_t b = __builtin_convertvector(v, bf16v2_t); return __builtin_bit_cast(unsigned, b); }
; __device__ __forceinline__ float siluf_(float x) { return x * __builtin_amdgcn_rcpf(1.0f + __expf(-x)); }
; __device__ void prep_ssd(const Ctx& c, int ck, int blk) {
;     ...
;             for (int j = 0; j < 8; ++j) { const int l = l0 + j;
;                 const float xc = raw[l];
;                 const float y = w0 * xm3 + w1 * xm2 + w2 * xm1 + w3 * xc + bb; xm3 = xm2; xm2 = xm1; xm1 = xc;
;                 const float x = siluf_(y);
;                 sX[(size_t)(t0 + l) * 1024 + ch] = f2bf(x);
;                 const float dtl = dt_s[hh * 64 + l];
;                 xd[j] = x * dtl; xw[j] = x * dtl * __expf(acl - acs_s[hh * 64 + l]); }
;             u32x4 a, b; a.x = pk2(xd[0], xd[1]); a.y = pk2(xd[2], xd[3]); a.z = pk2(xd[4], xd[5]); a.w = pk2(xd[6], xd[7]);
;             b.x = pk2(xw[0], xw[1]); b.y = pk2(xw[2], xw[3]); b.z = pk2(xw[4], xw[5]); b.w = pk2(xw[6], xw[7]);
;             const size_t o = ((size_t)(ck * 16 + h) * 64 + p) * 64 + l0;
;             *(u32x4*)(sXdT + o) = a; *(u32x4*)(sXwT + o) = b;
	v_exp_f32_e32 v153, v153
	v_exp_f32_e32 v154, v154
	v_exp_f32_e32 v155, v155
	v_pk_add_f32 v[152:153], v[152:153], s[36:37]
	v_pk_add_f32 v[154:155], v[154:155], s[36:37]
	v_rcp_f32_e32 v152, v152
	v_rcp_f32_e32 v153, v153
	v_rcp_f32_e32 v154, v154
	v_rcp_f32_e32 v155, v155
	s_nop 0
	v_pk_mul_f32 v[148:149], v[148:149], v[152:153]
	v_pk_mul_f32 v[150:151], v[150:151], v[154:155]
	v_cvt_pk_bf16_f32 v106, v148, v149
	v_cvt_pk_bf16_f32 v107, v150, v151
	v_mul_f32_e32 v164, v148, v225
	v_mul_f32_e32 v165, v149, v225
	v_mul_f32_e32 v166, v150, v225
	v_mul_f32_e32 v167, v151, v225
	v_mul_f32_e32 v168, v164, v9
	v_mul_f32_e32 v169, v165, v9
	v_mul_f32_e32 v170, v166, v9
	v_mul_f32_e32 v171, v167, v9
	v_cvt_pk_bf16_f32 v192, v156, v164
	v_cvt_pk_bf16_f32 v208, v160, v168
	v_cvt_pk_bf16_f32 v196, v157, v165
	v_cvt_pk_bf16_f32 v212, v161, v169
	v_cvt_pk_bf16_f32 v200, v158, v166
	v_cvt_pk_bf16_f32 v216, v162, v170
	v_cvt_pk_bf16_f32 v204, v159, v167
	v_cvt_pk_bf16_f32 v220, v163, v171
	global_store_dwordx4 v2, v[104:107], s[44:45]
	s_add_u32 s44, s44, 0x800
	s_addc_u32 s45, s45, 0
	v_lshlrev_b32_e32 v136, 16, v38
	v_and_b32_e32 v137, 0xffff0000, v38
	v_lshlrev_b32_e32 v138, 16, v39
	v_and_b32_e32 v139, 0xffff0000, v39
	v_pk_mul_f32 v[148:149], v[64:65], v[140:141]
	v_pk_mul_f32 v[150:151], v[66:67], v[142:143]
	v_pk_fma_f32 v[148:149], v[72:73], v[144:145], v[148:149]
	v_pk_fma_f32 v[150:151], v[74:75], v[146:147], v[150:151]
	v_pk_fma_f32 v[148:149], v[80:81], v[132:133], v[148:149]
	v_pk_fma_f32 v[150:151], v[82:83], v[134:135], v[150:151]
	v_pk_fma_f32 v[148:149], v[88:89], v[136:137], v[148:149]
	v_pk_fma_f32 v[150:151], v[90:91], v[138:139], v[150:151]
	v_pk_add_f32 v[148:149], v[148:149], v[96:97]
	v_pk_add_f32 v[150:151], v[150:151], v[98:99]
	v_pk_mul_f32 v[152:153], v[148:149], s[18:19]
	v_pk_mul_f32 v[154:155], v[150:151], s[18:19]
	v_exp_f32_e32 v152, v152
	v_exp_f32_e32 v153, v153
	v_exp_f32_e32 v154, v154
	v_exp_f32_e32 v155, v155
	v_pk_add_f32 v[152:153], v[152:153], s[36:37]
	v_pk_add_f32 v[154:155], v[154:155], s[36:37]
	v_rcp_f32_e32 v152, v152
	v_rcp_f32_e32 v153, v153
	v_rcp_f32_e32 v154, v154
	v_rcp_f32_e32 v155, v155
	s_nop 0
	v_pk_mul_f32 v[148:149], v[148:149], v[152:153]
	v_pk_mul_f32 v[150:151], v[150:151], v[154:155]
	v_cvt_pk_bf16_f32 v110, v148, v149
	v_cvt_pk_bf16_f32 v111, v150, v151
	v_mul_f32_e32 v156, v148, v226
	v_mul_f32_e32 v157, v149, v226
	v_mul_f32_e32 v158, v150, v226
	v_mul_f32_e32 v159, v151, v226
	v_mul_f32_e32 v160, v156, v10
	v_mul_f32_e32 v161, v157, v10
	v_mul_f32_e32 v162, v158, v10
	v_mul_f32_e32 v163, v159, v10
	global_store_dwordx4 v2, v[108:111], s[44:45]
	s_add_u32 s44, s44, 0x800
	s_addc_u32 s45, s45, 0
	v_lshlrev_b32_e32 v140, 16, v42
	v_and_b32_e32 v141, 0xffff0000, v42
	v_lshlrev_b32_e32 v142, 16, v43
	v_and_b32_e32 v143, 0xffff0000, v43
	v_pk_mul_f32 v[148:149], v[64:65], v[144:145]
	v_pk_mul_f32 v[150:151], v[66:67], v[146:147]
	v_pk_fma_f32 v[148:149], v[72:73], v[132:133], v[148:149]
	v_pk_fma_f32 v[150:151], v[74:75], v[134:135], v[150:151]
	v_pk_fma_f32 v[148:149], v[80:81], v[136:137], v[148:149]
	v_pk_fma_f32 v[150:151], v[82:83], v[138:139], v[150:151]
	v_pk_fma_f32 v[148:149], v[88:89], v[140:141], v[148:149]
	v_pk_fma_f32 v[150:151], v[90:91], v[142:143], v[150:151]
	v_pk_add_f32 v[148:149], v[148:149], v[96:97]
	v_pk_add_f32 v[150:151], v[150:151], v[98:99]
	v_pk_mul_f32 v[152:153], v[148:149], s[18:19]
	v_pk_mul_f32 v[154:155], v[150:151], s[18:19]
	v_exp_f32_e32 v152, v152
	v_exp_f32_e32 v153, v153
	v_exp_f32_e32 v154, v154
	v_exp_f32_e32 v155, v155
	v_pk_add_f32 v[152:153], v[152:153], s[36:37]
	v_pk_add_f32 v[154:155], v[154:155], s[36:37]
	v_rcp_f32_e32 v152, v152
	v_rcp_f32_e32 v153, v153
	v_rcp_f32_e32 v154, v154
	v_rcp_f32_e32 v155, v155
	s_nop 0
	v_pk_mul_f32 v[148:149], v[148:149], v[152:153]
	v_pk_mul_f32 v[150:151], v[150:151], v[154:155]
	v_cvt_pk_bf16_f32 v114, v148, v149
	v_cvt_pk_bf16_f32 v115, v150, v151
	v_mul_f32_e32 v164, v148, v227
	v_mul_f32_e32 v165, v149, v227
	v_mul_f32_e32 v166, v150, v227
	v_mul_f32_e32 v167, v151, v227
	v_mul_f32_e32 v168, v164, v11
	v_mul_f32_e32 v169, v165, v11
	v_mul_f32_e32 v170, v166, v11
	v_mul_f32_e32 v171, v167, v11
	v_cvt_pk_bf16_f32 v193, v156, v164
	v_cvt_pk_bf16_f32 v209, v160, v168
	v_cvt_pk_bf16_f32 v197, v157, v165
	v_cvt_pk_bf16_f32 v213, v161, v169
	v_cvt_pk_bf16_f32 v201, v158, v166
	v_cvt_pk_bf16_f32 v217, v162, v170
	v_cvt_pk_bf16_f32 v205, v159, v167
	v_cvt_pk_bf16_f32 v221, v163, v171
	global_store_dwordx4 v2, v[112:115], s[44:45]
	s_add_u32 s44, s44, 0x800
	s_addc_u32 s45, s45, 0
	v_lshlrev_b32_e32 v144, 16, v46
	v_and_b32_e32 v145, 0xffff0000, v46
	v_lshlrev_b32_e32 v146, 16, v47
	v_and_b32_e32 v147, 0xffff0000, v47
	v_pk_mul_f32 v[148:149], v[64:65], v[132:133]
	v_pk_mul_f32 v[150:151], v[66:67], v[134:135]
	v_pk_fma_f32 v[148:149], v[72:73], v[136:137], v[148:149]
	v_pk_fma_f32 v[150:151], v[74:75], v[138:139], v[150:151]
	v_pk_fma_f32 v[148:149], v[80:81], v[140:141], v[148:149]
	v_pk_fma_f32 v[150:151], v[82:83], v[142:143], v[150:151]
	v_pk_fma_f32 v[148:149], v[88:89], v[144:145], v[148:149]
	v_pk_fma_f32 v[150:151], v[90:91], v[146:147], v[150:151]
	v_pk_add_f32 v[148:149], v[148:149], v[96:97]
	v_pk_add_f32 v[150:151], v[150:151], v[98:99]
	v_pk_mul_f32 v[152:153], v[148:149], s[18:19]
	v_pk_mul_f32 v[154:155], v[150:151], s[18:19]
	v_exp_f32_e32 v152, v152
	v_exp_f32_e32 v153, v153
	v_exp_f32_e32 v154, v154
	v_exp_f32_e32 v155, v155
	v_pk_add_f32 v[152:153], v[152:153], s[36:37]
	v_pk_add_f32 v[154:155], v[154:155], s[36:37]
	v_rcp_f32_e32 v152, v152
	v_rcp_f32_e32 v153, v153
	v_rcp_f32_e32 v154, v154
; __device__ __forceinline__ unsigned pk2(float lo, float hi) { const f32v2_t v = {lo, hi}; const bf16v2_t b = __builtin_convertvector(v, bf16v2_t); return __builtin_bit_cast(unsigned, b); }
; __device__ __forceinline__ float siluf_(float x) { return x * __builtin_amdgcn_rcpf(1.0f + __expf(-x)); }
; __device__ void prep_ssd(const Ctx& c, int ck, int blk) {
;     ...
;             for (int j = 0; j < 8; ++j) { const int l = l0 + j;
;                 const float xc = raw[l];
;                 const float y = w0 * xm3 + w1 * xm2 + w2 * xm1 + w3 * xc + bb; xm3 = xm2; xm2 = xm1; xm1 = xc;
;                 const float x = siluf_(y);
;                 sX[(size_t)(t0 + l) * 1024 + ch] = f2bf(x);
;                 const float dtl = dt_s[hh * 64 + l];
;                 xd[j] = x * dtl; xw[j] = x * dtl * __expf(acl - acs_s[hh * 64 + l]); }
;             u32x4 a, b; a.x = pk2(xd[0], xd[1]); a.y = pk2(xd[2], xd[3]); a.z = pk2(xd[4], xd[5]); a.w = pk2(xd[6], xd[7]);
;             b.x = pk2(xw[0], xw[1]); b.y = pk2(xw[2], xw[3]); b.z = pk2(xw[4], xw[5]); b.w = pk2(xw[6], xw[7]);
;             const size_t o = ((size_t)(ck * 16 + h) * 64 + p) * 64 + l0;
;             *(u32x4*)(sXdT + o) = a; *(u32x4*)(sXwT + o) = b;
	v_rcp_f32_e32 v155, v155
	s_nop 0
	v_pk_mul_f32 v[148:149], v[148:149], v[152:153]
	v_pk_mul_f32 v[150:151], v[150:151], v[154:155]
	v_cvt_pk_bf16_f32 v118, v148, v149
	v_cvt_pk_bf16_f32 v119, v150, v151
	v_mul_f32_e32 v156, v148, v228
	v_mul_f32_e32 v157, v149, v228
	v_mul_f32_e32 v158, v150, v228
	v_mul_f32_e32 v159, v151, v228
	v_mul_f32_e32 v160, v156, v12
	v_mul_f32_e32 v161, v157, v12
	v_mul_f32_e32 v162, v158, v12
	v_mul_f32_e32 v163, v159, v12
	global_store_dwordx4 v2, v[116:119], s[44:45]
	s_add_u32 s44, s44, 0x800
	s_addc_u32 s45, s45, 0
	v_lshlrev_b32_e32 v132, 16, v50
	v_and_b32_e32 v133, 0xffff0000, v50
	v_lshlrev_b32_e32 v134, 16, v51
	v_and_b32_e32 v135, 0xffff0000, v51
	v_pk_mul_f32 v[148:149], v[64:65], v[136:137]
	v_pk_mul_f32 v[150:151], v[66:67], v[138:139]
	v_pk_fma_f32 v[148:149], v[72:73], v[140:141], v[148:149]
	v_pk_fma_f32 v[150:151], v[74:75], v[142:143], v[150:151]
	v_pk_fma_f32 v[148:149], v[80:81], v[144:145], v[148:149]
	v_pk_fma_f32 v[150:151], v[82:83], v[146:147], v[150:151]
	v_pk_fma_f32 v[148:149], v[88:89], v[132:133], v[148:149]
	v_pk_fma_f32 v[150:151], v[90:91], v[134:135], v[150:151]
	v_pk_add_f32 v[148:149], v[148:149], v[96:97]
	v_pk_add_f32 v[150:151], v[150:151], v[98:99]
	v_pk_mul_f32 v[152:153], v[148:149], s[18:19]
	v_pk_mul_f32 v[154:155], v[150:151], s[18:19]
	v_exp_f32_e32 v152, v152
	v_exp_f32_e32 v153, v153
	v_exp_f32_e32 v154, v154
	v_exp_f32_e32 v155, v155
	v_pk_add_f32 v[152:153], v[152:153], s[36:37]
	v_pk_add_f32 v[154:155], v[154:155], s[36:37]
	v_rcp_f32_e32 v152, v152
	v_rcp_f32_e32 v153, v153
	v_rcp_f32_e32 v154, v154
	v_rcp_f32_e32 v155, v155
	s_nop 0
	v_pk_mul_f32 v[148:149], v[148:149], v[152:153]
	v_pk_mul_f32 v[150:151], v[150:151], v[154:155]
	v_cvt_pk_bf16_f32 v122, v148, v149
	v_cvt_pk_bf16_f32 v123, v150, v151
	v_mul_f32_e32 v164, v148, v229
	v_mul_f32_e32 v165, v149, v229
	v_mul_f32_e32 v166, v150, v229
	v_mul_f32_e32 v167, v151, v229
	v_mul_f32_e32 v168, v164, v13
	v_mul_f32_e32 v169, v165, v13
	v_mul_f32_e32 v170, v166, v13
	v_mul_f32_e32 v171, v167, v13
	v_cvt_pk_bf16_f32 v194, v156, v164
	v_cvt_pk_bf16_f32 v210, v160, v168
	v_cvt_pk_bf16_f32 v198, v157, v165
	v_cvt_pk_bf16_f32 v214, v161, v169
	v_cvt_pk_bf16_f32 v202, v158, v166
	v_cvt_pk_bf16_f32 v218, v162, v170
	v_cvt_pk_bf16_f32 v206, v159, v167
	v_cvt_pk_bf16_f32 v222, v163, v171
	global_store_dwordx4 v2, v[120:123], s[44:45]
	s_add_u32 s44, s44, 0x800
	s_addc_u32 s45, s45, 0
	v_lshlrev_b32_e32 v136, 16, v54
	v_and_b32_e32 v137, 0xffff0000, v54
	v_lshlrev_b32_e32 v138, 16, v55
	v_and_b32_e32 v139, 0xffff0000, v55
	v_pk_mul_f32 v[148:149], v[64:65], v[140:141]
	v_pk_mul_f32 v[150:151], v[66:67], v[142:143]
	v_pk_fma_f32 v[148:149], v[72:73], v[144:145], v[148:149]
	v_pk_fma_f32 v[150:151], v[74:75], v[146:147], v[150:151]
	v_pk_fma_f32 v[148:149], v[80:81], v[132:133], v[148:149]
	v_pk_fma_f32 v[150:151], v[82:83], v[134:135], v[150:151]
	v_pk_fma_f32 v[148:149], v[88:89], v[136:137], v[148:149]
	v_pk_fma_f32 v[150:151], v[90:91], v[138:139], v[150:151]
	v_pk_add_f32 v[148:149], v[148:149], v[96:97]
	v_pk_add_f32 v[150:151], v[150:151], v[98:99]
	v_pk_mul_f32 v[152:153], v[148:149], s[18:19]
	v_pk_mul_f32 v[154:155], v[150:151], s[18:19]
	v_exp_f32_e32 v152, v152
	v_exp_f32_e32 v153, v153
	v_exp_f32_e32 v154, v154
	v_exp_f32_e32 v155, v155
	v_pk_add_f32 v[152:153], v[152:153], s[36:37]
	v_pk_add_f32 v[154:155], v[154:155], s[36:37]
	v_rcp_f32_e32 v152, v152
	v_rcp_f32_e32 v153, v153
	v_rcp_f32_e32 v154, v154
	v_rcp_f32_e32 v155, v155
	s_nop 0
	v_pk_mul_f32 v[148:149], v[148:149], v[152:153]
	v_pk_mul_f32 v[150:151], v[150:151], v[154:155]
	v_cvt_pk_bf16_f32 v126, v148, v149
	v_cvt_pk_bf16_f32 v127, v150, v151
	v_mul_f32_e32 v156, v148, v230
	v_mul_f32_e32 v157, v149, v230
	v_mul_f32_e32 v158, v150, v230
	v_mul_f32_e32 v159, v151, v230
	v_mul_f32_e32 v160, v156, v14
	v_mul_f32_e32 v161, v157, v14
	v_mul_f32_e32 v162, v158, v14
	v_mul_f32_e32 v163, v159, v14
	global_store_dwordx4 v2, v[124:127], s[44:45]
	s_add_u32 s44, s44, 0x800
	s_addc_u32 s45, s45, 0
	v_lshlrev_b32_e32 v140, 16, v58
	v_and_b32_e32 v141, 0xffff0000, v58
	v_lshlrev_b32_e32 v142, 16, v59
	v_and_b32_e32 v143, 0xffff0000, v59
	v_pk_mul_f32 v[148:149], v[64:65], v[144:145]
	v_pk_mul_f32 v[150:151], v[66:67], v[146:147]
	v_pk_fma_f32 v[148:149], v[72:73], v[132:133], v[148:149]
	v_pk_fma_f32 v[150:151], v[74:75], v[134:135], v[150:151]
	v_pk_fma_f32 v[148:149], v[80:81], v[136:137], v[148:149]
	v_pk_fma_f32 v[150:151], v[82:83], v[138:139], v[150:151]
	v_pk_fma_f32 v[148:149], v[88:89], v[140:141], v[148:149]
	v_pk_fma_f32 v[150:151], v[90:91], v[142:143], v[150:151]
	v_pk_add_f32 v[148:149], v[148:149], v[96:97]
	v_pk_add_f32 v[150:151], v[150:151], v[98:99]
	v_pk_mul_f32 v[152:153], v[148:149], s[18:19]
	v_pk_mul_f32 v[154:155], v[150:151], s[18:19]
	v_exp_f32_e32 v152, v152
	v_exp_f32_e32 v153, v153
	v_exp_f32_e32 v154, v154
	v_exp_f32_e32 v155, v155
	v_pk_add_f32 v[152:153], v[152:153], s[36:37]
	v_pk_add_f32 v[154:155], v[154:155], s[36:37]
	v_rcp_f32_e32 v152, v152
	v_rcp_f32_e32 v153, v153
	v_rcp_f32_e32 v154, v154
	v_rcp_f32_e32 v155, v155
	s_nop 0
	v_pk_mul_f32 v[148:149], v[148:149], v[152:153]
	v_pk_mul_f32 v[150:151], v[150:151], v[154:155]
	v_cvt_pk_bf16_f32 v130, v148, v149
	v_cvt_pk_bf16_f32 v131, v150, v151
	v_mul_f32_e32 v164, v148, v231
	v_mul_f32_e32 v165, v149, v231
	v_mul_f32_e32 v166, v150, v231
	v_mul_f32_e32 v167, v151, v231
	v_mul_f32_e32 v168, v164, v15
	v_mul_f32_e32 v169, v165, v15
	v_mul_f32_e32 v170, v166, v15
	v_mul_f32_e32 v171, v167, v15
	v_cvt_pk_bf16_f32 v195, v156, v164
	v_cvt_pk_bf16_f32 v211, v160, v168
; __device__ __forceinline__ float bf2f(bf16_t b) { return __uint_as_float(((unsigned)b) << 16); }
; __device__ __forceinline__ unsigned pk2(float lo, float hi) { const f32v2_t v = {lo, hi}; const bf16v2_t b = __builtin_convertvector(v, bf16v2_t); return __builtin_bit_cast(unsigned, b); }
; __device__ __forceinline__ float siluf_(float x) { return x * __builtin_amdgcn_rcpf(1.0f + __expf(-x)); }
;     template <class Tp> __device__ __forceinline__ Tp* W(size_t off) const { return (Tp*)(ws + off); }
; __device__ void prep_ssd(const Ctx& c, int ck, int blk) {
;     ...
;             u32x4 a, b; a.x = pk2(xd[0], xd[1]); a.y = pk2(xd[2], xd[3]); a.z = pk2(xd[4], xd[5]); a.w = pk2(xd[6], xd[7]);
;             b.x = pk2(xw[0], xw[1]); b.y = pk2(xw[2], xw[3]); b.z = pk2(xw[4], xw[5]); b.w = pk2(xw[6], xw[7]);
;             const size_t o = ((size_t)(ck * 16 + h) * 64 + p) * 64 + l0;
;             *(u32x4*)(sXdT + o) = a; *(u32x4*)(sXwT + o) = b;
;     ...
;         const int isC = tid >> 7, cc = (blk - 2) * 128 + (tid & 127), ch = 1024 + isC * 256 + cc;
;         const float w0 = cw[ch], w1 = cw[1536 + ch], w2 = cw[2 * 1536 + ch], w3 = cw[3 * 1536 + ch], bb = cb[ch];
;         float xm3 = 0.f, xm2 = 0.f, xm1 = 0.f;
;         if (t0 > 0) { xm3 = bf2f(proj[(size_t)(t0 - 3) * NP + C_SX + ch]); xm2 = bf2f(proj[(size_t)(t0 - 2) * NP + C_SX + ch]); xm1 = bf2f(proj[(size_t)(t0 - 1) * NP + C_SX + ch]); }
;         bf16_t* rowdst = isC ? c.W<bf16_t>(WS_SC) : c.W<bf16_t>(WS_SB);
;         bf16_t* sBT = c.W<bf16_t>(WS_SBT);
;         const int g = cc >> 7, n = cc & 127;
;         float raw[64];
;         { unsigned rw[64];
; #pragma unroll
;           for (int l = 0; l < 64; ++l) rw[l] = proj[(size_t)(t0 + l) * NP + C_SX + ch];
;           PIN16(rw, 0); PIN16(rw, 16); PIN16(rw, 32); PIN16(rw, 48);
; #pragma unroll
;           for (int l = 0; l < 64; ++l) raw[l] = __uint_as_float(rw[l] << 16); }
; #pragma unroll
;         for (int l0 = 0; l0 < 64; l0 += 8) {
;             float xv[8];
; #pragma unroll
;             for (int j = 0; j < 8; ++j) { const int l = l0 + j;
;                 const float xc = raw[l];
;                 const float y = w0 * xm3 + w1 * xm2 + w2 * xm1 + w3 * xc + bb; xm3 = xm2; xm2 = xm1; xm1 = xc;
;                 const float x = siluf_(y); xv[j] = x;
;                 rowdst[(size_t)(t0 + l) * 256 + cc] = f2bf(x); }
	v_cvt_pk_bf16_f32 v199, v157, v165
	v_cvt_pk_bf16_f32 v215, v161, v169
	v_cvt_pk_bf16_f32 v203, v158, v166
	v_cvt_pk_bf16_f32 v219, v162, v170
	v_cvt_pk_bf16_f32 v207, v159, v167
	v_cvt_pk_bf16_f32 v223, v163, v171
	global_store_dwordx4 v2, v[128:131], s[44:45]
	global_store_dwordx4 v4, v[192:195], s[4:5] offset:512
	global_store_dwordx4 v5, v[208:211], s[4:5] offset:512
	global_store_dwordx4 v4, v[196:199], s[4:5] offset:640
	global_store_dwordx4 v5, v[212:215], s[4:5] offset:640
	global_store_dwordx4 v4, v[200:203], s[4:5] offset:768
	global_store_dwordx4 v5, v[216:219], s[4:5] offset:768
	global_store_dwordx4 v4, v[204:207], s[4:5] offset:896
	global_store_dwordx4 v5, v[220:223], s[4:5] offset:896
	v_and_b32_e32 v12, 31, v3
	s_lshl_b32 s22, s8, 7
	v_lshl_add_u32 v12, v12, 2, s22
	v_lshrrev_b32_e32 v13, 5, v3
	v_lshl_add_u32 v14, v13, 8, v12
	v_add_u32_e32 v14, 0x400, v14
	v_lshlrev_b32_e32 v1, 2, v14
	v_lshlrev_b32_e32 v0, 1, v14
	v_add_u32_e32 v0, 0x2820, v0
	v_mul_u32_u24_e32 v2, 0x400000, v13
	v_lshl_add_u32 v2, v12, 1, v2
	v_add_u32_e32 v2, 0x2c901000, v2
	s_lshl_b32 s22, s7, 1
	s_add_u32 s22, s22, s8
	s_lshl_b32 s22, s22, 14
	v_lshl_add_u32 v4, v3, 9, s22
	s_lshl_b32 s23, s9, 4
	v_add_u32_e32 v4, s23, v4
	v_add_u32_e32 v4, 0x2d101000, v4
	s_mov_b64 s[100:101], s[38:39]
	global_load_dwordx2 v[16:17], v0, s[100:101]
	s_add_u32 s100, s100, 0x7e00
	s_addc_u32 s101, s101, 0
	global_load_dwordx2 v[18:19], v0, s[100:101]
	s_add_u32 s100, s100, 0x7e00
	s_addc_u32 s101, s101, 0
	global_load_dwordx2 v[20:21], v0, s[100:101]
	s_add_u32 s100, s100, 0x7e00
	s_addc_u32 s101, s101, 0
	global_load_dwordx2 v[22:23], v0, s[100:101]
	s_add_u32 s100, s100, 0x7e00
	s_addc_u32 s101, s101, 0
	global_load_dwordx2 v[24:25], v0, s[100:101]
	s_add_u32 s100, s100, 0x7e00
	s_addc_u32 s101, s101, 0
	global_load_dwordx2 v[26:27], v0, s[100:101]
	s_add_u32 s100, s100, 0x7e00
	s_addc_u32 s101, s101, 0
	global_load_dwordx2 v[28:29], v0, s[100:101]
	s_add_u32 s100, s100, 0x7e00
	s_addc_u32 s101, s101, 0
	global_load_dwordx2 v[30:31], v0, s[100:101]
	s_add_u32 s100, s100, 0x7e00
	s_addc_u32 s101, s101, 0
	global_load_dwordx2 v[32:33], v0, s[100:101]
	s_add_u32 s100, s100, 0x7e00
	s_addc_u32 s101, s101, 0
	global_load_dwordx2 v[34:35], v0, s[100:101]
	s_add_u32 s100, s100, 0x7e00
	s_addc_u32 s101, s101, 0
	global_load_dwordx2 v[36:37], v0, s[100:101]
	s_load_dwordx2 s[40:41], s[0:1], 0x40
	s_load_dwordx2 s[42:43], s[0:1], 0x48
	s_mul_i32 s22, s16, 0x6000
	s_mul_i32 s23, s16, 0x1800
	s_waitcnt lgkmcnt(0)
	s_add_u32 s40, s40, s22
	s_addc_u32 s41, s41, 0
	s_add_u32 s42, s42, s23
	s_addc_u32 s43, s43, 0
	global_load_dwordx4 v[60:63], v1, s[40:41] offset:0
	s_add_u32 s40, s40, 0x1800
	s_addc_u32 s41, s41, 0
	global_load_dwordx4 v[64:67], v1, s[40:41] offset:0
	s_add_u32 s40, s40, 0x1800
	s_addc_u32 s41, s41, 0
	global_load_dwordx4 v[68:71], v1, s[40:41] offset:0
	s_add_u32 s40, s40, 0x1800
	s_addc_u32 s41, s41, 0
	global_load_dwordx4 v[72:75], v1, s[40:41] offset:0
	global_load_dwordx4 v[76:79], v1, s[42:43] offset:0
	s_lshl_b32 s22, s17, 9
	s_add_u32 s44, s4, s22
	s_addc_u32 s45, s5, 0
	s_waitcnt vmcnt(0)
	s_cmp_lt_i32 s10, 0
	s_cbranch_scc0 .Lprep_nz_ssdb
	v_mov_b32_e32 v16, 0
	v_mov_b32_e32 v17, 0
	v_mov_b32_e32 v18, 0
	v_mov_b32_e32 v19, 0
	v_mov_b32_e32 v20, 0
	v_mov_b32_e32 v21, 0
.Lprep_nz_ssdb:
	v_lshlrev_b32_e32 v132, 16, v16
	v_and_b32_e32 v133, 0xffff0000, v16
	v_lshlrev_b32_e32 v134, 16, v17
	v_and_b32_e32 v135, 0xffff0000, v17
	v_lshlrev_b32_e32 v136, 16, v18
	v_and_b32_e32 v137, 0xffff0000, v18
	v_lshlrev_b32_e32 v138, 16, v19
	v_and_b32_e32 v139, 0xffff0000, v19
	v_lshlrev_b32_e32 v140, 16, v20
	v_and_b32_e32 v141, 0xffff0000, v20
	v_lshlrev_b32_e32 v142, 16, v21
	v_and_b32_e32 v143, 0xffff0000, v21
	v_lshlrev_b32_e32 v144, 16, v22
	v_and_b32_e32 v145, 0xffff0000, v22
	v_lshlrev_b32_e32 v146, 16, v23
	v_and_b32_e32 v147, 0xffff0000, v23
	v_pk_mul_f32 v[148:149], v[60:61], v[132:133]
	v_pk_mul_f32 v[150:151], v[62:63], v[134:135]
	v_pk_fma_f32 v[148:149], v[64:65], v[136:137], v[148:149]
	v_pk_fma_f32 v[150:151], v[66:67], v[138:139], v[150:151]
	v_pk_fma_f32 v[148:149], v[68:69], v[140:141], v[148:149]
	v_pk_fma_f32 v[150:151], v[70:71], v[142:143], v[150:151]
	v_pk_fma_f32 v[148:149], v[72:73], v[144:145], v[148:149]
	v_pk_fma_f32 v[150:151], v[74:75], v[146:147], v[150:151]
	v_pk_add_f32 v[148:149], v[148:149], v[76:77]
	v_pk_add_f32 v[150:151], v[150:151], v[78:79]
	v_pk_mul_f32 v[152:153], v[148:149], s[18:19]
	v_pk_mul_f32 v[154:155], v[150:151], s[18:19]
	v_exp_f32_e32 v152, v152
	v_exp_f32_e32 v153, v153
	v_exp_f32_e32 v154, v154
	v_exp_f32_e32 v155, v155
	v_pk_add_f32 v[152:153], v[152:153], s[36:37]
	v_pk_add_f32 v[154:155], v[154:155], s[36:37]
	v_rcp_f32_e32 v152, v152
	v_rcp_f32_e32 v153, v153
	v_rcp_f32_e32 v154, v154
	v_rcp_f32_e32 v155, v155
	s_nop 0
	v_pk_mul_f32 v[148:149], v[148:149], v[152:153]
	v_pk_mul_f32 v[150:151], v[150:151], v[154:155]
	v_cvt_pk_bf16_f32 v100, v148, v149
	v_cvt_pk_bf16_f32 v101, v150, v151
	global_store_dwordx2 v2, v[100:101], s[44:45]
	s_add_u32 s44, s44, 0x200
	s_addc_u32 s45, s45, 0
	v_mov_b32_e32 v156, v148
	v_mov_b32_e32 v157, v149
	v_mov_b32_e32 v158, v150
	v_mov_b32_e32 v159, v151
	v_lshlrev_b32_e32 v132, 16, v24
	v_and_b32_e32 v133, 0xffff0000, v24
	v_lshlrev_b32_e32 v134, 16, v25
	v_and_b32_e32 v135, 0xffff0000, v25
	v_pk_mul_f32 v[148:149], v[60:61], v[136:137]
	v_pk_mul_f32 v[150:151], v[62:63], v[138:139]
	v_pk_fma_f32 v[148:149], v[64:65], v[140:141], v[148:149]
	v_pk_fma_f32 v[150:151], v[66:67], v[142:143], v[150:151]
	v_pk_fma_f32 v[148:149], v[68:69], v[144:145], v[148:149]
; __device__ __forceinline__ unsigned pk2(float lo, float hi) { const f32v2_t v = {lo, hi}; const bf16v2_t b = __builtin_convertvector(v, bf16v2_t); return __builtin_bit_cast(unsigned, b); }
; __device__ __forceinline__ float siluf_(float x) { return x * __builtin_amdgcn_rcpf(1.0f + __expf(-x)); }
; __device__ void prep_ssd(const Ctx& c, int ck, int blk) {
;     ...
;             for (int j = 0; j < 8; ++j) { const int l = l0 + j;
;                 const float xc = raw[l];
;                 const float y = w0 * xm3 + w1 * xm2 + w2 * xm1 + w3 * xc + bb; xm3 = xm2; xm2 = xm1; xm1 = xc;
;                 const float x = siluf_(y); xv[j] = x;
;                 rowdst[(size_t)(t0 + l) * 256 + cc] = f2bf(x); }
;             if (!isC) { u32x4 a; a.x = pk2(xv[0], xv[1]); a.y = pk2(xv[2], xv[3]); a.z = pk2(xv[4], xv[5]); a.w = pk2(xv[6], xv[7]);
;                 *(u32x4*)(sBT + ((size_t)(ck * 2 + g) * 128 + n) * 64 + l0) = a; }
	v_pk_fma_f32 v[150:151], v[70:71], v[146:147], v[150:151]
	v_pk_fma_f32 v[148:149], v[72:73], v[132:133], v[148:149]
	v_pk_fma_f32 v[150:151], v[74:75], v[134:135], v[150:151]
	v_pk_add_f32 v[148:149], v[148:149], v[76:77]
	v_pk_add_f32 v[150:151], v[150:151], v[78:79]
	v_pk_mul_f32 v[152:153], v[148:149], s[18:19]
	v_pk_mul_f32 v[154:155], v[150:151], s[18:19]
	v_exp_f32_e32 v152, v152
	v_exp_f32_e32 v153, v153
	v_exp_f32_e32 v154, v154
	v_exp_f32_e32 v155, v155
	v_pk_add_f32 v[152:153], v[152:153], s[36:37]
	v_pk_add_f32 v[154:155], v[154:155], s[36:37]
	v_rcp_f32_e32 v152, v152
	v_rcp_f32_e32 v153, v153
	v_rcp_f32_e32 v154, v154
	v_rcp_f32_e32 v155, v155
	s_nop 0
	v_pk_mul_f32 v[148:149], v[148:149], v[152:153]
	v_pk_mul_f32 v[150:151], v[150:151], v[154:155]
	v_cvt_pk_bf16_f32 v102, v148, v149
	v_cvt_pk_bf16_f32 v103, v150, v151
	global_store_dwordx2 v2, v[102:103], s[44:45]
	s_add_u32 s44, s44, 0x200
	s_addc_u32 s45, s45, 0
	v_mov_b32_e32 v160, v148
	v_mov_b32_e32 v161, v149
	v_mov_b32_e32 v162, v150
	v_mov_b32_e32 v163, v151
	v_cvt_pk_bf16_f32 v192, v156, v160
	v_cvt_pk_bf16_f32 v196, v157, v161
	v_cvt_pk_bf16_f32 v200, v158, v162
	v_cvt_pk_bf16_f32 v204, v159, v163
	v_lshlrev_b32_e32 v136, 16, v26
	v_and_b32_e32 v137, 0xffff0000, v26
	v_lshlrev_b32_e32 v138, 16, v27
	v_and_b32_e32 v139, 0xffff0000, v27
	v_pk_mul_f32 v[148:149], v[60:61], v[140:141]
	v_pk_mul_f32 v[150:151], v[62:63], v[142:143]
	v_pk_fma_f32 v[148:149], v[64:65], v[144:145], v[148:149]
	v_pk_fma_f32 v[150:151], v[66:67], v[146:147], v[150:151]
	v_pk_fma_f32 v[148:149], v[68:69], v[132:133], v[148:149]
	v_pk_fma_f32 v[150:151], v[70:71], v[134:135], v[150:151]
	v_pk_fma_f32 v[148:149], v[72:73], v[136:137], v[148:149]
	v_pk_fma_f32 v[150:151], v[74:75], v[138:139], v[150:151]
	v_pk_add_f32 v[148:149], v[148:149], v[76:77]
	v_pk_add_f32 v[150:151], v[150:151], v[78:79]
	v_pk_mul_f32 v[152:153], v[148:149], s[18:19]
	v_pk_mul_f32 v[154:155], v[150:151], s[18:19]
	v_exp_f32_e32 v152, v152
	v_exp_f32_e32 v153, v153
	v_exp_f32_e32 v154, v154
	v_exp_f32_e32 v155, v155
	v_pk_add_f32 v[152:153], v[152:153], s[36:37]
	v_pk_add_f32 v[154:155], v[154:155], s[36:37]
	v_rcp_f32_e32 v152, v152
	v_rcp_f32_e32 v153, v153
	v_rcp_f32_e32 v154, v154
	v_rcp_f32_e32 v155, v155
	s_nop 0
	v_pk_mul_f32 v[148:149], v[148:149], v[152:153]
	v_pk_mul_f32 v[150:151], v[150:151], v[154:155]
	v_cvt_pk_bf16_f32 v100, v148, v149
	v_cvt_pk_bf16_f32 v101, v150, v151
	global_store_dwordx2 v2, v[100:101], s[44:45]
	s_add_u32 s44, s44, 0x200
	s_addc_u32 s45, s45, 0
	v_mov_b32_e32 v156, v148
	v_mov_b32_e32 v157, v149
	v_mov_b32_e32 v158, v150
	v_mov_b32_e32 v159, v151
	v_lshlrev_b32_e32 v140, 16, v28
	v_and_b32_e32 v141, 0xffff0000, v28
	v_lshlrev_b32_e32 v142, 16, v29
	v_and_b32_e32 v143, 0xffff0000, v29
	v_pk_mul_f32 v[148:149], v[60:61], v[144:145]
	v_pk_mul_f32 v[150:151], v[62:63], v[146:147]
	v_pk_fma_f32 v[148:149], v[64:65], v[132:133], v[148:149]
	v_pk_fma_f32 v[150:151], v[66:67], v[134:135], v[150:151]
	v_pk_fma_f32 v[148:149], v[68:69], v[136:137], v[148:149]
	v_pk_fma_f32 v[150:151], v[70:71], v[138:139], v[150:151]
	v_pk_fma_f32 v[148:149], v[72:73], v[140:141], v[148:149]
	v_pk_fma_f32 v[150:151], v[74:75], v[142:143], v[150:151]
	v_pk_add_f32 v[148:149], v[148:149], v[76:77]
	v_pk_add_f32 v[150:151], v[150:151], v[78:79]
	v_pk_mul_f32 v[152:153], v[148:149], s[18:19]
	v_pk_mul_f32 v[154:155], v[150:151], s[18:19]
	v_exp_f32_e32 v152, v152
	v_exp_f32_e32 v153, v153
	v_exp_f32_e32 v154, v154
	v_exp_f32_e32 v155, v155
	v_pk_add_f32 v[152:153], v[152:153], s[36:37]
	v_pk_add_f32 v[154:155], v[154:155], s[36:37]
	v_rcp_f32_e32 v152, v152
	v_rcp_f32_e32 v153, v153
	v_rcp_f32_e32 v154, v154
	v_rcp_f32_e32 v155, v155
	s_nop 0
	v_pk_mul_f32 v[148:149], v[148:149], v[152:153]
	v_pk_mul_f32 v[150:151], v[150:151], v[154:155]
	v_cvt_pk_bf16_f32 v102, v148, v149
	v_cvt_pk_bf16_f32 v103, v150, v151
	global_store_dwordx2 v2, v[102:103], s[44:45]
	s_add_u32 s44, s44, 0x200
	s_addc_u32 s45, s45, 0
	v_mov_b32_e32 v160, v148
	v_mov_b32_e32 v161, v149
	v_mov_b32_e32 v162, v150
	v_mov_b32_e32 v163, v151
	v_cvt_pk_bf16_f32 v193, v156, v160
	v_cvt_pk_bf16_f32 v197, v157, v161
	v_cvt_pk_bf16_f32 v201, v158, v162
	v_cvt_pk_bf16_f32 v205, v159, v163
	v_lshlrev_b32_e32 v144, 16, v30
	v_and_b32_e32 v145, 0xffff0000, v30
	v_lshlrev_b32_e32 v146, 16, v31
	v_and_b32_e32 v147, 0xffff0000, v31
	v_pk_mul_f32 v[148:149], v[60:61], v[132:133]
	v_pk_mul_f32 v[150:151], v[62:63], v[134:135]
	v_pk_fma_f32 v[148:149], v[64:65], v[136:137], v[148:149]
	v_pk_fma_f32 v[150:151], v[66:67], v[138:139], v[150:151]
	v_pk_fma_f32 v[148:149], v[68:69], v[140:141], v[148:149]
	v_pk_fma_f32 v[150:151], v[70:71], v[142:143], v[150:151]
	v_pk_fma_f32 v[148:149], v[72:73], v[144:145], v[148:149]
	v_pk_fma_f32 v[150:151], v[74:75], v[146:147], v[150:151]
	v_pk_add_f32 v[148:149], v[148:149], v[76:77]
	v_pk_add_f32 v[150:151], v[150:151], v[78:79]
	v_pk_mul_f32 v[152:153], v[148:149], s[18:19]
	v_pk_mul_f32 v[154:155], v[150:151], s[18:19]
	v_exp_f32_e32 v152, v152
	v_exp_f32_e32 v153, v153
	v_exp_f32_e32 v154, v154
	v_exp_f32_e32 v155, v155
	v_pk_add_f32 v[152:153], v[152:153], s[36:37]
	v_pk_add_f32 v[154:155], v[154:155], s[36:37]
	v_rcp_f32_e32 v152, v152
	v_rcp_f32_e32 v153, v153
	v_rcp_f32_e32 v154, v154
	v_rcp_f32_e32 v155, v155
	s_nop 0
	v_pk_mul_f32 v[148:149], v[148:149], v[152:153]
	v_pk_mul_f32 v[150:151], v[150:151], v[154:155]
	v_cvt_pk_bf16_f32 v100, v148, v149
	v_cvt_pk_bf16_f32 v101, v150, v151
	global_store_dwordx2 v2, v[100:101], s[44:45]
	s_add_u32 s44, s44, 0x200
	s_addc_u32 s45, s45, 0
	v_mov_b32_e32 v156, v148
; __device__ __forceinline__ unsigned pk2(float lo, float hi) { const f32v2_t v = {lo, hi}; const bf16v2_t b = __builtin_convertvector(v, bf16v2_t); return __builtin_bit_cast(unsigned, b); }
; __device__ __forceinline__ float siluf_(float x) { return x * __builtin_amdgcn_rcpf(1.0f + __expf(-x)); }
; #define PIN16(a, o) asm volatile("" : "+v"(a[(o)+0]), "+v"(a[(o)+1]), "+v"(a[(o)+2]), "+v"(a[(o)+3]), "+v"(a[(o)+4]), "+v"(a[(o)+5]), "+v"(a[(o)+6]), "+v"(a[(o)+7]), \
;     "+v"(a[(o)+8]), "+v"(a[(o)+9]), "+v"(a[(o)+10]), "+v"(a[(o)+11]), "+v"(a[(o)+12]), "+v"(a[(o)+13]), "+v"(a[(o)+14]), "+v"(a[(o)+15]))
; __device__ void prep_ssd(const Ctx& c, int ck, int blk) {
;     ...
;         for (int l0 = 0; l0 < 64; l0 += 8) {
;             float xv[8];
; #pragma unroll
;             for (int j = 0; j < 8; ++j) { const int l = l0 + j;
;                 const float xc = raw[l];
;                 const float y = w0 * xm3 + w1 * xm2 + w2 * xm1 + w3 * xc + bb; xm3 = xm2; xm2 = xm1; xm1 = xc;
;                 const float x = siluf_(y); xv[j] = x;
;                 rowdst[(size_t)(t0 + l) * 256 + cc] = f2bf(x); }
;             if (!isC) { u32x4 a; a.x = pk2(xv[0], xv[1]); a.y = pk2(xv[2], xv[3]); a.z = pk2(xv[4], xv[5]); a.w = pk2(xv[6], xv[7]);
;                 *(u32x4*)(sBT + ((size_t)(ck * 2 + g) * 128 + n) * 64 + l0) = a; }
; __device__ void prep_gla(const Ctx& c, int ck, int blk) {
;     ...
;         const int ch = (blk - 10) * 256 + tid, h = ch >> 7, k = ch & 127;
;         const float* w2 = c.in(I_GW2) + (size_t)c.layer * 16 * 512;
;         float w2r[16];
; #pragma unroll
;         for (int r = 0; r < 16; ++r) w2r[r] = w2[r * 512 + ch];
;         const float b2 = c.in(I_GB)[c.layer * 512 + ch];
;         bf16_t* gQg = c.W<bf16_t>(WS_GQG); bf16_t* gKn = c.W<bf16_t>(WS_GKN); bf16_t* gKnT = c.W<bf16_t>(WS_GKNT);
;         float G = 0.f;
;         for (int lh = 0; lh < 64; lh += 32) {
;             float qr[32], kr[32];
;             { unsigned qw[32], kw[32];
; #pragma unroll
;               for (int l = 0; l < 32; ++l) { const size_t rb = (size_t)(t0 + lh + l) * NP; qw[l] = proj[rb + C_GQ + ch]; kw[l] = proj[rb + C_GK + ch]; }
;               PIN16(qw, 0); PIN16(kw, 0); PIN16(qw, 16); PIN16(kw, 16);
; #pragma unroll
;               for (int l = 0; l < 32; ++l) { qr[l] = __uint_as_float(qw[l] << 16); kr[l] = __uint_as_float(kw[l] << 16); } }
	v_mov_b32_e32 v157, v149
	v_mov_b32_e32 v158, v150
	v_mov_b32_e32 v159, v151
	v_lshlrev_b32_e32 v132, 16, v32
	v_and_b32_e32 v133, 0xffff0000, v32
	v_lshlrev_b32_e32 v134, 16, v33
	v_and_b32_e32 v135, 0xffff0000, v33
	v_pk_mul_f32 v[148:149], v[60:61], v[136:137]
	v_pk_mul_f32 v[150:151], v[62:63], v[138:139]
	v_pk_fma_f32 v[148:149], v[64:65], v[140:141], v[148:149]
	v_pk_fma_f32 v[150:151], v[66:67], v[142:143], v[150:151]
	v_pk_fma_f32 v[148:149], v[68:69], v[144:145], v[148:149]
	v_pk_fma_f32 v[150:151], v[70:71], v[146:147], v[150:151]
	v_pk_fma_f32 v[148:149], v[72:73], v[132:133], v[148:149]
	v_pk_fma_f32 v[150:151], v[74:75], v[134:135], v[150:151]
	v_pk_add_f32 v[148:149], v[148:149], v[76:77]
	v_pk_add_f32 v[150:151], v[150:151], v[78:79]
	v_pk_mul_f32 v[152:153], v[148:149], s[18:19]
	v_pk_mul_f32 v[154:155], v[150:151], s[18:19]
	v_exp_f32_e32 v152, v152
	v_exp_f32_e32 v153, v153
	v_exp_f32_e32 v154, v154
	v_exp_f32_e32 v155, v155
	v_pk_add_f32 v[152:153], v[152:153], s[36:37]
	v_pk_add_f32 v[154:155], v[154:155], s[36:37]
	v_rcp_f32_e32 v152, v152
	v_rcp_f32_e32 v153, v153
	v_rcp_f32_e32 v154, v154
	v_rcp_f32_e32 v155, v155
	s_nop 0
	v_pk_mul_f32 v[148:149], v[148:149], v[152:153]
	v_pk_mul_f32 v[150:151], v[150:151], v[154:155]
	v_cvt_pk_bf16_f32 v102, v148, v149
	v_cvt_pk_bf16_f32 v103, v150, v151
	global_store_dwordx2 v2, v[102:103], s[44:45]
	s_add_u32 s44, s44, 0x200
	s_addc_u32 s45, s45, 0
	v_mov_b32_e32 v160, v148
	v_mov_b32_e32 v161, v149
	v_mov_b32_e32 v162, v150
	v_mov_b32_e32 v163, v151
	v_cvt_pk_bf16_f32 v194, v156, v160
	v_cvt_pk_bf16_f32 v198, v157, v161
	v_cvt_pk_bf16_f32 v202, v158, v162
	v_cvt_pk_bf16_f32 v206, v159, v163
	v_lshlrev_b32_e32 v136, 16, v34
	v_and_b32_e32 v137, 0xffff0000, v34
	v_lshlrev_b32_e32 v138, 16, v35
	v_and_b32_e32 v139, 0xffff0000, v35
	v_pk_mul_f32 v[148:149], v[60:61], v[140:141]
	v_pk_mul_f32 v[150:151], v[62:63], v[142:143]
	v_pk_fma_f32 v[148:149], v[64:65], v[144:145], v[148:149]
	v_pk_fma_f32 v[150:151], v[66:67], v[146:147], v[150:151]
	v_pk_fma_f32 v[148:149], v[68:69], v[132:133], v[148:149]
	v_pk_fma_f32 v[150:151], v[70:71], v[134:135], v[150:151]
	v_pk_fma_f32 v[148:149], v[72:73], v[136:137], v[148:149]
	v_pk_fma_f32 v[150:151], v[74:75], v[138:139], v[150:151]
	v_pk_add_f32 v[148:149], v[148:149], v[76:77]
	v_pk_add_f32 v[150:151], v[150:151], v[78:79]
	v_pk_mul_f32 v[152:153], v[148:149], s[18:19]
	v_pk_mul_f32 v[154:155], v[150:151], s[18:19]
	v_exp_f32_e32 v152, v152
	v_exp_f32_e32 v153, v153
	v_exp_f32_e32 v154, v154
	v_exp_f32_e32 v155, v155
	v_pk_add_f32 v[152:153], v[152:153], s[36:37]
	v_pk_add_f32 v[154:155], v[154:155], s[36:37]
	v_rcp_f32_e32 v152, v152
	v_rcp_f32_e32 v153, v153
	v_rcp_f32_e32 v154, v154
	v_rcp_f32_e32 v155, v155
	s_nop 0
	v_pk_mul_f32 v[148:149], v[148:149], v[152:153]
	v_pk_mul_f32 v[150:151], v[150:151], v[154:155]
	v_cvt_pk_bf16_f32 v100, v148, v149
	v_cvt_pk_bf16_f32 v101, v150, v151
	global_store_dwordx2 v2, v[100:101], s[44:45]
	s_add_u32 s44, s44, 0x200
	s_addc_u32 s45, s45, 0
	v_mov_b32_e32 v156, v148
	v_mov_b32_e32 v157, v149
	v_mov_b32_e32 v158, v150
	v_mov_b32_e32 v159, v151
	v_lshlrev_b32_e32 v140, 16, v36
	v_and_b32_e32 v141, 0xffff0000, v36
	v_lshlrev_b32_e32 v142, 16, v37
	v_and_b32_e32 v143, 0xffff0000, v37
	v_pk_mul_f32 v[148:149], v[60:61], v[144:145]
	v_pk_mul_f32 v[150:151], v[62:63], v[146:147]
	v_pk_fma_f32 v[148:149], v[64:65], v[132:133], v[148:149]
	v_pk_fma_f32 v[150:151], v[66:67], v[134:135], v[150:151]
	v_pk_fma_f32 v[148:149], v[68:69], v[136:137], v[148:149]
	v_pk_fma_f32 v[150:151], v[70:71], v[138:139], v[150:151]
	v_pk_fma_f32 v[148:149], v[72:73], v[140:141], v[148:149]
	v_pk_fma_f32 v[150:151], v[74:75], v[142:143], v[150:151]
	v_pk_add_f32 v[148:149], v[148:149], v[76:77]
	v_pk_add_f32 v[150:151], v[150:151], v[78:79]
	v_pk_mul_f32 v[152:153], v[148:149], s[18:19]
	v_pk_mul_f32 v[154:155], v[150:151], s[18:19]
	v_exp_f32_e32 v152, v152
	v_exp_f32_e32 v153, v153
	v_exp_f32_e32 v154, v154
	v_exp_f32_e32 v155, v155
	v_pk_add_f32 v[152:153], v[152:153], s[36:37]
	v_pk_add_f32 v[154:155], v[154:155], s[36:37]
	v_rcp_f32_e32 v152, v152
	v_rcp_f32_e32 v153, v153
	v_rcp_f32_e32 v154, v154
	v_rcp_f32_e32 v155, v155
	s_nop 0
	v_pk_mul_f32 v[148:149], v[148:149], v[152:153]
	v_pk_mul_f32 v[150:151], v[150:151], v[154:155]
	v_cvt_pk_bf16_f32 v102, v148, v149
	v_cvt_pk_bf16_f32 v103, v150, v151
	global_store_dwordx2 v2, v[102:103], s[44:45]
	v_mov_b32_e32 v160, v148
	v_mov_b32_e32 v161, v149
	v_mov_b32_e32 v162, v150
	v_mov_b32_e32 v163, v151
	v_cvt_pk_bf16_f32 v195, v156, v160
	v_cvt_pk_bf16_f32 v199, v157, v161
	v_cvt_pk_bf16_f32 v203, v158, v162
	v_cvt_pk_bf16_f32 v207, v159, v163
	s_mov_b64 exec, 0xffffffff
	global_store_dwordx4 v4, v[192:195], s[4:5] offset:0
	global_store_dwordx4 v4, v[196:199], s[4:5] offset:128
	global_store_dwordx4 v4, v[200:203], s[4:5] offset:256
	global_store_dwordx4 v4, v[204:207], s[4:5] offset:384
	s_mov_b64 exec, -1
	v_lshlrev_b32_e32 v12, 2, v3
	s_lshl_b32 s22, s8, 8
	v_add_u32_e32 v12, s22, v12
	v_lshlrev_b32_e32 v1, 2, v12
	v_lshlrev_b32_e32 v0, 1, v12
	v_add_u32_e32 v2, 0x3840, v0
	v_add_u32_e32 v0, 0x3440, v0
	s_add_u32 s100, s38, 0x17a00
	s_addc_u32 s101, s39, 0
	s_mov_b64 s[46:47], s[100:101]
	global_load_dwordx2 v[16:17], v0, s[100:101]
	global_load_dwordx2 v[32:33], v2, s[100:101]
	s_add_u32 s100, s100, 0x7e00
	s_addc_u32 s101, s101, 0
	global_load_dwordx2 v[18:19], v0, s[100:101]
	global_load_dwordx2 v[34:35], v2, s[100:101]
	s_add_u32 s100, s100, 0x7e00
	s_addc_u32 s101, s101, 0
	global_load_dwordx2 v[20:21], v0, s[100:101]
	global_load_dwordx2 v[36:37], v2, s[100:101]
	s_add_u32 s100, s100, 0x7e00
	s_addc_u32 s101, s101, 0
	global_load_dwordx2 v[22:23], v0, s[100:101]
	global_load_dwordx2 v[38:39], v2, s[100:101]
	s_add_u32 s100, s100, 0x7e00
	s_addc_u32 s101, s101, 0
	global_load_dwordx2 v[24:25], v0, s[100:101]
	global_load_dwordx2 v[40:41], v2, s[100:101]
	s_add_u32 s100, s100, 0x7e00
	s_addc_u32 s101, s101, 0
	global_load_dwordx2 v[26:27], v0, s[100:101]
	global_load_dwordx2 v[42:43], v2, s[100:101]
	s_add_u32 s100, s100, 0x7e00
	s_addc_u32 s101, s101, 0
	global_load_dwordx2 v[28:29], v0, s[100:101]
	global_load_dwordx2 v[44:45], v2, s[100:101]
	s_add_u32 s100, s100, 0x7e00
	s_addc_u32 s101, s101, 0
	global_load_dwordx2 v[30:31], v0, s[100:101]
	global_load_dwordx2 v[46:47], v2, s[100:101]
	s_load_dwordx2 s[40:41], s[0:1], 0x70
	s_load_dwordx2 s[42:43], s[0:1], 0x78
	s_mul_i32 s22, s16, 0x8000
	s_mul_i32 s23, s16, 0x800
	s_waitcnt lgkmcnt(0)
; __device__ __forceinline__ float lo16(unsigned u) { return __uint_as_float(u << 16); }
; __device__ __forceinline__ float hi16(unsigned u) { return __uint_as_float(u & 0xffff0000u); }
; __device__ __forceinline__ float softplusf_(float x) { return fmaxf(x, 0.f) + __logf(1.0f + __expf(-fabsf(x))); }
; __device__ void prep_gla(const Ctx& c, int ck, int blk) {
;     ...
;         { const int l = tid >> 3, r2 = (tid & 7) * 2; const unsigned u = *(const unsigned*)(proj + (size_t)(t0 + l) * NP + C_GLR + r2); lr_s[l * 16 + r2] = lo16(u); lr_s[l * 16 + r2 + 1] = hi16(u); }
;     ...
;                 for (int j = 0; j < 8; ++j) { const int l = lh + l0 + j;
;                     float x = b2;
; #pragma unroll
;                     for (int r4 = 0; r4 < 16; r4 += 4) { const f32x4 lv = *(const f32x4*)(lr_s + l * 16 + r4); x += lv[0] * w2r[r4] + lv[1] * w2r[r4 + 1] + lv[2] * w2r[r4 + 2] + lv[3] * w2r[r4 + 3]; }
;                     G += -softplusf_(-x) * (1.0f / 16.0f);
	s_add_u32 s40, s40, s22
	s_addc_u32 s41, s41, 0
	s_add_u32 s42, s42, s23
	s_addc_u32 s43, s43, 0
	global_load_dwordx4 v[48:51], v1, s[40:41]
	s_add_u32 s40, s40, 0x800
	s_addc_u32 s41, s41, 0
	global_load_dwordx4 v[52:55], v1, s[40:41]
	s_add_u32 s40, s40, 0x800
	s_addc_u32 s41, s41, 0
	global_load_dwordx4 v[56:59], v1, s[40:41]
	s_add_u32 s40, s40, 0x800
	s_addc_u32 s41, s41, 0
	global_load_dwordx4 v[60:63], v1, s[40:41]
	s_add_u32 s40, s40, 0x800
	s_addc_u32 s41, s41, 0
	global_load_dwordx4 v[64:67], v1, s[40:41]
	s_add_u32 s40, s40, 0x800
	s_addc_u32 s41, s41, 0
	global_load_dwordx4 v[68:71], v1, s[40:41]
	s_add_u32 s40, s40, 0x800
	s_addc_u32 s41, s41, 0
	global_load_dwordx4 v[72:75], v1, s[40:41]
	s_add_u32 s40, s40, 0x800
	s_addc_u32 s41, s41, 0
	global_load_dwordx4 v[76:79], v1, s[40:41]
	s_add_u32 s40, s40, 0x800
	s_addc_u32 s41, s41, 0
	global_load_dwordx4 v[80:83], v1, s[40:41]
	s_add_u32 s40, s40, 0x800
	s_addc_u32 s41, s41, 0
	global_load_dwordx4 v[84:87], v1, s[40:41]
	s_add_u32 s40, s40, 0x800
	s_addc_u32 s41, s41, 0
	global_load_dwordx4 v[88:91], v1, s[40:41]
	s_add_u32 s40, s40, 0x800
	s_addc_u32 s41, s41, 0
	global_load_dwordx4 v[92:95], v1, s[40:41]
	s_add_u32 s40, s40, 0x800
	s_addc_u32 s41, s41, 0
	global_load_dwordx4 v[96:99], v1, s[40:41]
	s_add_u32 s40, s40, 0x800
	s_addc_u32 s41, s41, 0
	global_load_dwordx4 v[100:103], v1, s[40:41]
	s_add_u32 s40, s40, 0x800
	s_addc_u32 s41, s41, 0
	global_load_dwordx4 v[104:107], v1, s[40:41]
	s_add_u32 s40, s40, 0x800
	s_addc_u32 s41, s41, 0
	global_load_dwordx4 v[108:111], v1, s[40:41]
	global_load_dwordx4 v[112:115], v1, s[42:43]
	v_lshrrev_b32_e32 v13, 3, v3
	s_mov_b32 s25, 0x7e00
	v_mul_lo_u32 v13, v13, s25
	v_and_b32_e32 v14, 7, v3
	v_lshl_add_u32 v13, v14, 2, v13
	v_add_u32_e32 v13, 0x4440, v13
	global_load_dword v176, v13, s[46:47]
	s_waitcnt vmcnt(0)
	v_readlane_b32 s48, v176, 0
	v_readlane_b32 s49, v176, 1
	v_readlane_b32 s50, v176, 2
	v_readlane_b32 s51, v176, 3
	v_readlane_b32 s52, v176, 4
	v_readlane_b32 s53, v176, 5
	v_readlane_b32 s54, v176, 6
	v_readlane_b32 s55, v176, 7
	v_mov_b32_e32 v148, v112
	v_mov_b32_e32 v149, v113
	v_mov_b32_e32 v150, v114
	v_mov_b32_e32 v151, v115
	s_lshl_b32 s56, s48, 16
	s_and_b32 s57, s48, 0xffff0000
	v_fmac_f32_e32 v148, s56, v48
	v_fmac_f32_e32 v149, s56, v49
	v_fmac_f32_e32 v150, s56, v50
	v_fmac_f32_e32 v151, s56, v51
	v_fmac_f32_e32 v148, s57, v52
	v_fmac_f32_e32 v149, s57, v53
	v_fmac_f32_e32 v150, s57, v54
	v_fmac_f32_e32 v151, s57, v55
	s_lshl_b32 s56, s49, 16
	s_and_b32 s57, s49, 0xffff0000
	v_fmac_f32_e32 v148, s56, v56
	v_fmac_f32_e32 v149, s56, v57
	v_fmac_f32_e32 v150, s56, v58
	v_fmac_f32_e32 v151, s56, v59
	v_fmac_f32_e32 v148, s57, v60
	v_fmac_f32_e32 v149, s57, v61
	v_fmac_f32_e32 v150, s57, v62
	v_fmac_f32_e32 v151, s57, v63
	s_lshl_b32 s56, s50, 16
	s_and_b32 s57, s50, 0xffff0000
	v_fmac_f32_e32 v148, s56, v64
	v_fmac_f32_e32 v149, s56, v65
	v_fmac_f32_e32 v150, s56, v66
	v_fmac_f32_e32 v151, s56, v67
	v_fmac_f32_e32 v148, s57, v68
	v_fmac_f32_e32 v149, s57, v69
	v_fmac_f32_e32 v150, s57, v70
	v_fmac_f32_e32 v151, s57, v71
	s_lshl_b32 s56, s51, 16
	s_and_b32 s57, s51, 0xffff0000
	v_fmac_f32_e32 v148, s56, v72
	v_fmac_f32_e32 v149, s56, v73
	v_fmac_f32_e32 v150, s56, v74
	v_fmac_f32_e32 v151, s56, v75
	v_fmac_f32_e32 v148, s57, v76
	v_fmac_f32_e32 v149, s57, v77
	v_fmac_f32_e32 v150, s57, v78
	v_fmac_f32_e32 v151, s57, v79
	s_lshl_b32 s56, s52, 16
	s_and_b32 s57, s52, 0xffff0000
	v_fmac_f32_e32 v148, s56, v80
	v_fmac_f32_e32 v149, s56, v81
	v_fmac_f32_e32 v150, s56, v82
	v_fmac_f32_e32 v151, s56, v83
	v_fmac_f32_e32 v148, s57, v84
	v_fmac_f32_e32 v149, s57, v85
	v_fmac_f32_e32 v150, s57, v86
	v_fmac_f32_e32 v151, s57, v87
	s_lshl_b32 s56, s53, 16
	s_and_b32 s57, s53, 0xffff0000
	v_fmac_f32_e32 v148, s56, v88
	v_fmac_f32_e32 v149, s56, v89
	v_fmac_f32_e32 v150, s56, v90
	v_fmac_f32_e32 v151, s56, v91
	v_fmac_f32_e32 v148, s57, v92
	v_fmac_f32_e32 v149, s57, v93
	v_fmac_f32_e32 v150, s57, v94
	v_fmac_f32_e32 v151, s57, v95
	s_lshl_b32 s56, s54, 16
	s_and_b32 s57, s54, 0xffff0000
	v_fmac_f32_e32 v148, s56, v96
	v_fmac_f32_e32 v149, s56, v97
	v_fmac_f32_e32 v150, s56, v98
	v_fmac_f32_e32 v151, s56, v99
	v_fmac_f32_e32 v148, s57, v100
	v_fmac_f32_e32 v149, s57, v101
	v_fmac_f32_e32 v150, s57, v102
	v_fmac_f32_e32 v151, s57, v103
	s_lshl_b32 s56, s55, 16
	s_and_b32 s57, s55, 0xffff0000
	v_fmac_f32_e32 v148, s56, v104
	v_fmac_f32_e32 v149, s56, v105
	v_fmac_f32_e32 v150, s56, v106
	v_fmac_f32_e32 v151, s56, v107
	v_fmac_f32_e32 v148, s57, v108
	v_fmac_f32_e32 v149, s57, v109
	v_fmac_f32_e32 v150, s57, v110
	v_fmac_f32_e32 v151, s57, v111
	v_xor_b32_e32 v148, 0x80000000, v148
	v_mul_f32_e64 v152, |v148|, s28
	v_exp_f32_e32 v152, v152
	v_max_f32_e32 v148, 0, v148
	v_add_f32_e32 v152, 1.0, v152
	v_log_f32_e32 v152, v152
	s_nop 0
	v_fmac_f32_e32 v148, 0x3f317218, v152
	v_mul_f32_e32 v116, 0xbd800000, v148
	v_xor_b32_e32 v149, 0x80000000, v149
	v_mul_f32_e64 v152, |v149|, s28
	v_exp_f32_e32 v152, v152
	v_max_f32_e32 v149, 0, v149
	v_add_f32_e32 v152, 1.0, v152
	v_log_f32_e32 v152, v152
	s_nop 0
	v_fmac_f32_e32 v149, 0x3f317218, v152
	v_mul_f32_e32 v117, 0xbd800000, v149
	v_xor_b32_e32 v150, 0x80000000, v150
	v_mul_f32_e64 v152, |v150|, s28
	v_exp_f32_e32 v152, v152
	v_max_f32_e32 v150, 0, v150
	v_add_f32_e32 v152, 1.0, v152
	v_log_f32_e32 v152, v152
	s_nop 0
	v_fmac_f32_e32 v150, 0x3f317218, v152
	v_mul_f32_e32 v118, 0xbd800000, v150
	v_xor_b32_e32 v151, 0x80000000, v151
	v_mul_f32_e64 v152, |v151|, s28
	v_exp_f32_e32 v152, v152
	v_max_f32_e32 v151, 0, v151
	v_add_f32_e32 v152, 1.0, v152
	v_log_f32_e32 v152, v152
	s_nop 0
; __device__ __forceinline__ float softplusf_(float x) { return fmaxf(x, 0.f) + __logf(1.0f + __expf(-fabsf(x))); }
; __device__ void prep_gla(const Ctx& c, int ck, int blk) {
;     ...
;                 for (int j = 0; j < 8; ++j) { const int l = lh + l0 + j;
;                     float x = b2;
; #pragma unroll
;                     for (int r4 = 0; r4 < 16; r4 += 4) { const f32x4 lv = *(const f32x4*)(lr_s + l * 16 + r4); x += lv[0] * w2r[r4] + lv[1] * w2r[r4 + 1] + lv[2] * w2r[r4 + 2] + lv[3] * w2r[r4 + 3]; }
;                     G += -softplusf_(-x) * (1.0f / 16.0f);
	v_fmac_f32_e32 v151, 0x3f317218, v152
	v_mul_f32_e32 v119, 0xbd800000, v151
	v_readlane_b32 s48, v176, 8
	v_readlane_b32 s49, v176, 9
	v_readlane_b32 s50, v176, 10
	v_readlane_b32 s51, v176, 11
	v_readlane_b32 s52, v176, 12
	v_readlane_b32 s53, v176, 13
	v_readlane_b32 s54, v176, 14
	v_readlane_b32 s55, v176, 15
	v_mov_b32_e32 v148, v112
	v_mov_b32_e32 v149, v113
	v_mov_b32_e32 v150, v114
	v_mov_b32_e32 v151, v115
	s_lshl_b32 s56, s48, 16
	s_and_b32 s57, s48, 0xffff0000
	v_fmac_f32_e32 v148, s56, v48
	v_fmac_f32_e32 v149, s56, v49
	v_fmac_f32_e32 v150, s56, v50
	v_fmac_f32_e32 v151, s56, v51
	v_fmac_f32_e32 v148, s57, v52
	v_fmac_f32_e32 v149, s57, v53
	v_fmac_f32_e32 v150, s57, v54
	v_fmac_f32_e32 v151, s57, v55
	s_lshl_b32 s56, s49, 16
	s_and_b32 s57, s49, 0xffff0000
	v_fmac_f32_e32 v148, s56, v56
	v_fmac_f32_e32 v149, s56, v57
	v_fmac_f32_e32 v150, s56, v58
	v_fmac_f32_e32 v151, s56, v59
	v_fmac_f32_e32 v148, s57, v60
	v_fmac_f32_e32 v149, s57, v61
	v_fmac_f32_e32 v150, s57, v62
	v_fmac_f32_e32 v151, s57, v63
	s_lshl_b32 s56, s50, 16
	s_and_b32 s57, s50, 0xffff0000
	v_fmac_f32_e32 v148, s56, v64
	v_fmac_f32_e32 v149, s56, v65
	v_fmac_f32_e32 v150, s56, v66
	v_fmac_f32_e32 v151, s56, v67
	v_fmac_f32_e32 v148, s57, v68
	v_fmac_f32_e32 v149, s57, v69
	v_fmac_f32_e32 v150, s57, v70
	v_fmac_f32_e32 v151, s57, v71
	s_lshl_b32 s56, s51, 16
	s_and_b32 s57, s51, 0xffff0000
	v_fmac_f32_e32 v148, s56, v72
	v_fmac_f32_e32 v149, s56, v73
	v_fmac_f32_e32 v150, s56, v74
	v_fmac_f32_e32 v151, s56, v75
	v_fmac_f32_e32 v148, s57, v76
	v_fmac_f32_e32 v149, s57, v77
	v_fmac_f32_e32 v150, s57, v78
	v_fmac_f32_e32 v151, s57, v79
	s_lshl_b32 s56, s52, 16
	s_and_b32 s57, s52, 0xffff0000
	v_fmac_f32_e32 v148, s56, v80
	v_fmac_f32_e32 v149, s56, v81
	v_fmac_f32_e32 v150, s56, v82
	v_fmac_f32_e32 v151, s56, v83
	v_fmac_f32_e32 v148, s57, v84
	v_fmac_f32_e32 v149, s57, v85
	v_fmac_f32_e32 v150, s57, v86
	v_fmac_f32_e32 v151, s57, v87
	s_lshl_b32 s56, s53, 16
	s_and_b32 s57, s53, 0xffff0000
	v_fmac_f32_e32 v148, s56, v88
	v_fmac_f32_e32 v149, s56, v89
	v_fmac_f32_e32 v150, s56, v90
	v_fmac_f32_e32 v151, s56, v91
	v_fmac_f32_e32 v148, s57, v92
	v_fmac_f32_e32 v149, s57, v93
	v_fmac_f32_e32 v150, s57, v94
	v_fmac_f32_e32 v151, s57, v95
	s_lshl_b32 s56, s54, 16
	s_and_b32 s57, s54, 0xffff0000
	v_fmac_f32_e32 v148, s56, v96
	v_fmac_f32_e32 v149, s56, v97
	v_fmac_f32_e32 v150, s56, v98
	v_fmac_f32_e32 v151, s56, v99
	v_fmac_f32_e32 v148, s57, v100
	v_fmac_f32_e32 v149, s57, v101
	v_fmac_f32_e32 v150, s57, v102
	v_fmac_f32_e32 v151, s57, v103
	s_lshl_b32 s56, s55, 16
	s_and_b32 s57, s55, 0xffff0000
	v_fmac_f32_e32 v148, s56, v104
	v_fmac_f32_e32 v149, s56, v105
	v_fmac_f32_e32 v150, s56, v106
	v_fmac_f32_e32 v151, s56, v107
	v_fmac_f32_e32 v148, s57, v108
	v_fmac_f32_e32 v149, s57, v109
	v_fmac_f32_e32 v150, s57, v110
	v_fmac_f32_e32 v151, s57, v111
	v_xor_b32_e32 v148, 0x80000000, v148
	v_mul_f32_e64 v152, |v148|, s28
	v_exp_f32_e32 v152, v152
	v_max_f32_e32 v148, 0, v148
	v_add_f32_e32 v152, 1.0, v152
	v_log_f32_e32 v152, v152
	s_nop 0
	v_fmac_f32_e32 v148, 0x3f317218, v152
	v_mul_f32_e32 v120, 0xbd800000, v148
	v_xor_b32_e32 v149, 0x80000000, v149
	v_mul_f32_e64 v152, |v149|, s28
	v_exp_f32_e32 v152, v152
	v_max_f32_e32 v149, 0, v149
	v_add_f32_e32 v152, 1.0, v152
	v_log_f32_e32 v152, v152
	s_nop 0
	v_fmac_f32_e32 v149, 0x3f317218, v152
	v_mul_f32_e32 v121, 0xbd800000, v149
	v_xor_b32_e32 v150, 0x80000000, v150
	v_mul_f32_e64 v152, |v150|, s28
	v_exp_f32_e32 v152, v152
	v_max_f32_e32 v150, 0, v150
	v_add_f32_e32 v152, 1.0, v152
	v_log_f32_e32 v152, v152
	s_nop 0
	v_fmac_f32_e32 v150, 0x3f317218, v152
	v_mul_f32_e32 v122, 0xbd800000, v150
	v_xor_b32_e32 v151, 0x80000000, v151
	v_mul_f32_e64 v152, |v151|, s28
	v_exp_f32_e32 v152, v152
	v_max_f32_e32 v151, 0, v151
	v_add_f32_e32 v152, 1.0, v152
	v_log_f32_e32 v152, v152
	s_nop 0
	v_fmac_f32_e32 v151, 0x3f317218, v152
	v_mul_f32_e32 v123, 0xbd800000, v151
	v_add_f32_e32 v120, v120, v116
	v_add_f32_e32 v121, v121, v117
	v_add_f32_e32 v122, v122, v118
	v_add_f32_e32 v123, v123, v119
	v_readlane_b32 s48, v176, 16
	v_readlane_b32 s49, v176, 17
	v_readlane_b32 s50, v176, 18
	v_readlane_b32 s51, v176, 19
	v_readlane_b32 s52, v176, 20
	v_readlane_b32 s53, v176, 21
	v_readlane_b32 s54, v176, 22
	v_readlane_b32 s55, v176, 23
	v_mov_b32_e32 v148, v112
	v_mov_b32_e32 v149, v113
	v_mov_b32_e32 v150, v114
	v_mov_b32_e32 v151, v115
	s_lshl_b32 s56, s48, 16
	s_and_b32 s57, s48, 0xffff0000
	v_fmac_f32_e32 v148, s56, v48
	v_fmac_f32_e32 v149, s56, v49
	v_fmac_f32_e32 v150, s56, v50
	v_fmac_f32_e32 v151, s56, v51
	v_fmac_f32_e32 v148, s57, v52
	v_fmac_f32_e32 v149, s57, v53
	v_fmac_f32_e32 v150, s57, v54
	v_fmac_f32_e32 v151, s57, v55
	s_lshl_b32 s56, s49, 16
	s_and_b32 s57, s49, 0xffff0000
	v_fmac_f32_e32 v148, s56, v56
	v_fmac_f32_e32 v149, s56, v57
	v_fmac_f32_e32 v150, s56, v58
	v_fmac_f32_e32 v151, s56, v59
	v_fmac_f32_e32 v148, s57, v60
	v_fmac_f32_e32 v149, s57, v61
	v_fmac_f32_e32 v150, s57, v62
	v_fmac_f32_e32 v151, s57, v63
	s_lshl_b32 s56, s50, 16
	s_and_b32 s57, s50, 0xffff0000
	v_fmac_f32_e32 v148, s56, v64
	v_fmac_f32_e32 v149, s56, v65
	v_fmac_f32_e32 v150, s56, v66
	v_fmac_f32_e32 v151, s56, v67
	v_fmac_f32_e32 v148, s57, v68
	v_fmac_f32_e32 v149, s57, v69
	v_fmac_f32_e32 v150, s57, v70
	v_fmac_f32_e32 v151, s57, v71
	s_lshl_b32 s56, s51, 16
	s_and_b32 s57, s51, 0xffff0000
	v_fmac_f32_e32 v148, s56, v72
	v_fmac_f32_e32 v149, s56, v73
	v_fmac_f32_e32 v150, s56, v74
	v_fmac_f32_e32 v151, s56, v75
	v_fmac_f32_e32 v148, s57, v76
	v_fmac_f32_e32 v149, s57, v77
	v_fmac_f32_e32 v150, s57, v78
	v_fmac_f32_e32 v151, s57, v79
; __device__ __forceinline__ float softplusf_(float x) { return fmaxf(x, 0.f) + __logf(1.0f + __expf(-fabsf(x))); }
; __device__ void prep_gla(const Ctx& c, int ck, int blk) {
;     ...
;                 for (int j = 0; j < 8; ++j) { const int l = lh + l0 + j;
;                     float x = b2;
; #pragma unroll
;                     for (int r4 = 0; r4 < 16; r4 += 4) { const f32x4 lv = *(const f32x4*)(lr_s + l * 16 + r4); x += lv[0] * w2r[r4] + lv[1] * w2r[r4 + 1] + lv[2] * w2r[r4 + 2] + lv[3] * w2r[r4 + 3]; }
;                     G += -softplusf_(-x) * (1.0f / 16.0f);
	s_lshl_b32 s56, s52, 16
	s_and_b32 s57, s52, 0xffff0000
	v_fmac_f32_e32 v148, s56, v80
	v_fmac_f32_e32 v149, s56, v81
	v_fmac_f32_e32 v150, s56, v82
	v_fmac_f32_e32 v151, s56, v83
	v_fmac_f32_e32 v148, s57, v84
	v_fmac_f32_e32 v149, s57, v85
	v_fmac_f32_e32 v150, s57, v86
	v_fmac_f32_e32 v151, s57, v87
	s_lshl_b32 s56, s53, 16
	s_and_b32 s57, s53, 0xffff0000
	v_fmac_f32_e32 v148, s56, v88
	v_fmac_f32_e32 v149, s56, v89
	v_fmac_f32_e32 v150, s56, v90
	v_fmac_f32_e32 v151, s56, v91
	v_fmac_f32_e32 v148, s57, v92
	v_fmac_f32_e32 v149, s57, v93
	v_fmac_f32_e32 v150, s57, v94
	v_fmac_f32_e32 v151, s57, v95
	s_lshl_b32 s56, s54, 16
	s_and_b32 s57, s54, 0xffff0000
	v_fmac_f32_e32 v148, s56, v96
	v_fmac_f32_e32 v149, s56, v97
	v_fmac_f32_e32 v150, s56, v98
	v_fmac_f32_e32 v151, s56, v99
	v_fmac_f32_e32 v148, s57, v100
	v_fmac_f32_e32 v149, s57, v101
	v_fmac_f32_e32 v150, s57, v102
	v_fmac_f32_e32 v151, s57, v103
	s_lshl_b32 s56, s55, 16
	s_and_b32 s57, s55, 0xffff0000
	v_fmac_f32_e32 v148, s56, v104
	v_fmac_f32_e32 v149, s56, v105
	v_fmac_f32_e32 v150, s56, v106
	v_fmac_f32_e32 v151, s56, v107
	v_fmac_f32_e32 v148, s57, v108
	v_fmac_f32_e32 v149, s57, v109
	v_fmac_f32_e32 v150, s57, v110
	v_fmac_f32_e32 v151, s57, v111
	v_xor_b32_e32 v148, 0x80000000, v148
	v_mul_f32_e64 v152, |v148|, s28
	v_exp_f32_e32 v152, v152
	v_max_f32_e32 v148, 0, v148
	v_add_f32_e32 v152, 1.0, v152
	v_log_f32_e32 v152, v152
	s_nop 0
	v_fmac_f32_e32 v148, 0x3f317218, v152
	v_mul_f32_e32 v124, 0xbd800000, v148
	v_xor_b32_e32 v149, 0x80000000, v149
	v_mul_f32_e64 v152, |v149|, s28
	v_exp_f32_e32 v152, v152
	v_max_f32_e32 v149, 0, v149
	v_add_f32_e32 v152, 1.0, v152
	v_log_f32_e32 v152, v152
	s_nop 0
	v_fmac_f32_e32 v149, 0x3f317218, v152
	v_mul_f32_e32 v125, 0xbd800000, v149
	v_xor_b32_e32 v150, 0x80000000, v150
	v_mul_f32_e64 v152, |v150|, s28
	v_exp_f32_e32 v152, v152
	v_max_f32_e32 v150, 0, v150
	v_add_f32_e32 v152, 1.0, v152
	v_log_f32_e32 v152, v152
	s_nop 0
	v_fmac_f32_e32 v150, 0x3f317218, v152
	v_mul_f32_e32 v126, 0xbd800000, v150
	v_xor_b32_e32 v151, 0x80000000, v151
	v_mul_f32_e64 v152, |v151|, s28
	v_exp_f32_e32 v152, v152
	v_max_f32_e32 v151, 0, v151
	v_add_f32_e32 v152, 1.0, v152
	v_log_f32_e32 v152, v152
	s_nop 0
	v_fmac_f32_e32 v151, 0x3f317218, v152
	v_mul_f32_e32 v127, 0xbd800000, v151
	v_add_f32_e32 v124, v124, v120
	v_add_f32_e32 v125, v125, v121
	v_add_f32_e32 v126, v126, v122
	v_add_f32_e32 v127, v127, v123
	v_readlane_b32 s48, v176, 24
	v_readlane_b32 s49, v176, 25
	v_readlane_b32 s50, v176, 26
	v_readlane_b32 s51, v176, 27
	v_readlane_b32 s52, v176, 28
	v_readlane_b32 s53, v176, 29
	v_readlane_b32 s54, v176, 30
	v_readlane_b32 s55, v176, 31
	v_mov_b32_e32 v148, v112
	v_mov_b32_e32 v149, v113
	v_mov_b32_e32 v150, v114
	v_mov_b32_e32 v151, v115
	s_lshl_b32 s56, s48, 16
	s_and_b32 s57, s48, 0xffff0000
	v_fmac_f32_e32 v148, s56, v48
	v_fmac_f32_e32 v149, s56, v49
	v_fmac_f32_e32 v150, s56, v50
	v_fmac_f32_e32 v151, s56, v51
	v_fmac_f32_e32 v148, s57, v52
	v_fmac_f32_e32 v149, s57, v53
	v_fmac_f32_e32 v150, s57, v54
	v_fmac_f32_e32 v151, s57, v55
	s_lshl_b32 s56, s49, 16
	s_and_b32 s57, s49, 0xffff0000
	v_fmac_f32_e32 v148, s56, v56
	v_fmac_f32_e32 v149, s56, v57
	v_fmac_f32_e32 v150, s56, v58
	v_fmac_f32_e32 v151, s56, v59
	v_fmac_f32_e32 v148, s57, v60
	v_fmac_f32_e32 v149, s57, v61
	v_fmac_f32_e32 v150, s57, v62
	v_fmac_f32_e32 v151, s57, v63
	s_lshl_b32 s56, s50, 16
	s_and_b32 s57, s50, 0xffff0000
	v_fmac_f32_e32 v148, s56, v64
	v_fmac_f32_e32 v149, s56, v65
	v_fmac_f32_e32 v150, s56, v66
	v_fmac_f32_e32 v151, s56, v67
	v_fmac_f32_e32 v148, s57, v68
	v_fmac_f32_e32 v149, s57, v69
	v_fmac_f32_e32 v150, s57, v70
	v_fmac_f32_e32 v151, s57, v71
	s_lshl_b32 s56, s51, 16
	s_and_b32 s57, s51, 0xffff0000
	v_fmac_f32_e32 v148, s56, v72
	v_fmac_f32_e32 v149, s56, v73
	v_fmac_f32_e32 v150, s56, v74
	v_fmac_f32_e32 v151, s56, v75
	v_fmac_f32_e32 v148, s57, v76
	v_fmac_f32_e32 v149, s57, v77
	v_fmac_f32_e32 v150, s57, v78
	v_fmac_f32_e32 v151, s57, v79
	s_lshl_b32 s56, s52, 16
	s_and_b32 s57, s52, 0xffff0000
	v_fmac_f32_e32 v148, s56, v80
	v_fmac_f32_e32 v149, s56, v81
	v_fmac_f32_e32 v150, s56, v82
	v_fmac_f32_e32 v151, s56, v83
	v_fmac_f32_e32 v148, s57, v84
	v_fmac_f32_e32 v149, s57, v85
	v_fmac_f32_e32 v150, s57, v86
	v_fmac_f32_e32 v151, s57, v87
	s_lshl_b32 s56, s53, 16
	s_and_b32 s57, s53, 0xffff0000
	v_fmac_f32_e32 v148, s56, v88
	v_fmac_f32_e32 v149, s56, v89
	v_fmac_f32_e32 v150, s56, v90
	v_fmac_f32_e32 v151, s56, v91
	v_fmac_f32_e32 v148, s57, v92
	v_fmac_f32_e32 v149, s57, v93
	v_fmac_f32_e32 v150, s57, v94
	v_fmac_f32_e32 v151, s57, v95
	s_lshl_b32 s56, s54, 16
	s_and_b32 s57, s54, 0xffff0000
	v_fmac_f32_e32 v148, s56, v96
	v_fmac_f32_e32 v149, s56, v97
	v_fmac_f32_e32 v150, s56, v98
	v_fmac_f32_e32 v151, s56, v99
	v_fmac_f32_e32 v148, s57, v100
	v_fmac_f32_e32 v149, s57, v101
	v_fmac_f32_e32 v150, s57, v102
	v_fmac_f32_e32 v151, s57, v103
	s_lshl_b32 s56, s55, 16
	s_and_b32 s57, s55, 0xffff0000
	v_fmac_f32_e32 v148, s56, v104
	v_fmac_f32_e32 v149, s56, v105
	v_fmac_f32_e32 v150, s56, v106
	v_fmac_f32_e32 v151, s56, v107
	v_fmac_f32_e32 v148, s57, v108
	v_fmac_f32_e32 v149, s57, v109
	v_fmac_f32_e32 v150, s57, v110
	v_fmac_f32_e32 v151, s57, v111
	v_xor_b32_e32 v148, 0x80000000, v148
	v_mul_f32_e64 v152, |v148|, s28
	v_exp_f32_e32 v152, v152
	v_max_f32_e32 v148, 0, v148
	v_add_f32_e32 v152, 1.0, v152
	v_log_f32_e32 v152, v152
	s_nop 0
	v_fmac_f32_e32 v148, 0x3f317218, v152
	v_mul_f32_e32 v128, 0xbd800000, v148
	v_xor_b32_e32 v149, 0x80000000, v149
	v_mul_f32_e64 v152, |v149|, s28
	v_exp_f32_e32 v152, v152
	v_max_f32_e32 v149, 0, v149
; __device__ __forceinline__ float softplusf_(float x) { return fmaxf(x, 0.f) + __logf(1.0f + __expf(-fabsf(x))); }
; __device__ void prep_gla(const Ctx& c, int ck, int blk) {
;     ...
;                 for (int j = 0; j < 8; ++j) { const int l = lh + l0 + j;
;                     float x = b2;
; #pragma unroll
;                     for (int r4 = 0; r4 < 16; r4 += 4) { const f32x4 lv = *(const f32x4*)(lr_s + l * 16 + r4); x += lv[0] * w2r[r4] + lv[1] * w2r[r4 + 1] + lv[2] * w2r[r4 + 2] + lv[3] * w2r[r4 + 3]; }
;                     G += -softplusf_(-x) * (1.0f / 16.0f);
	v_add_f32_e32 v152, 1.0, v152
	v_log_f32_e32 v152, v152
	s_nop 0
	v_fmac_f32_e32 v149, 0x3f317218, v152
	v_mul_f32_e32 v129, 0xbd800000, v149
	v_xor_b32_e32 v150, 0x80000000, v150
	v_mul_f32_e64 v152, |v150|, s28
	v_exp_f32_e32 v152, v152
	v_max_f32_e32 v150, 0, v150
	v_add_f32_e32 v152, 1.0, v152
	v_log_f32_e32 v152, v152
	s_nop 0
	v_fmac_f32_e32 v150, 0x3f317218, v152
	v_mul_f32_e32 v130, 0xbd800000, v150
	v_xor_b32_e32 v151, 0x80000000, v151
	v_mul_f32_e64 v152, |v151|, s28
	v_exp_f32_e32 v152, v152
	v_max_f32_e32 v151, 0, v151
	v_add_f32_e32 v152, 1.0, v152
	v_log_f32_e32 v152, v152
	s_nop 0
	v_fmac_f32_e32 v151, 0x3f317218, v152
	v_mul_f32_e32 v131, 0xbd800000, v151
	v_add_f32_e32 v128, v128, v124
	v_add_f32_e32 v129, v129, v125
	v_add_f32_e32 v130, v130, v126
	v_add_f32_e32 v131, v131, v127
	v_readlane_b32 s48, v176, 32
	v_readlane_b32 s49, v176, 33
	v_readlane_b32 s50, v176, 34
	v_readlane_b32 s51, v176, 35
	v_readlane_b32 s52, v176, 36
	v_readlane_b32 s53, v176, 37
	v_readlane_b32 s54, v176, 38
	v_readlane_b32 s55, v176, 39
	v_mov_b32_e32 v148, v112
	v_mov_b32_e32 v149, v113
	v_mov_b32_e32 v150, v114
	v_mov_b32_e32 v151, v115
	s_lshl_b32 s56, s48, 16
	s_and_b32 s57, s48, 0xffff0000
	v_fmac_f32_e32 v148, s56, v48
	v_fmac_f32_e32 v149, s56, v49
	v_fmac_f32_e32 v150, s56, v50
	v_fmac_f32_e32 v151, s56, v51
	v_fmac_f32_e32 v148, s57, v52
	v_fmac_f32_e32 v149, s57, v53
	v_fmac_f32_e32 v150, s57, v54
	v_fmac_f32_e32 v151, s57, v55
	s_lshl_b32 s56, s49, 16
	s_and_b32 s57, s49, 0xffff0000
	v_fmac_f32_e32 v148, s56, v56
	v_fmac_f32_e32 v149, s56, v57
	v_fmac_f32_e32 v150, s56, v58
	v_fmac_f32_e32 v151, s56, v59
	v_fmac_f32_e32 v148, s57, v60
	v_fmac_f32_e32 v149, s57, v61
	v_fmac_f32_e32 v150, s57, v62
	v_fmac_f32_e32 v151, s57, v63
	s_lshl_b32 s56, s50, 16
	s_and_b32 s57, s50, 0xffff0000
	v_fmac_f32_e32 v148, s56, v64
	v_fmac_f32_e32 v149, s56, v65
	v_fmac_f32_e32 v150, s56, v66
	v_fmac_f32_e32 v151, s56, v67
	v_fmac_f32_e32 v148, s57, v68
	v_fmac_f32_e32 v149, s57, v69
	v_fmac_f32_e32 v150, s57, v70
	v_fmac_f32_e32 v151, s57, v71
	s_lshl_b32 s56, s51, 16
	s_and_b32 s57, s51, 0xffff0000
	v_fmac_f32_e32 v148, s56, v72
	v_fmac_f32_e32 v149, s56, v73
	v_fmac_f32_e32 v150, s56, v74
	v_fmac_f32_e32 v151, s56, v75
	v_fmac_f32_e32 v148, s57, v76
	v_fmac_f32_e32 v149, s57, v77
	v_fmac_f32_e32 v150, s57, v78
	v_fmac_f32_e32 v151, s57, v79
	s_lshl_b32 s56, s52, 16
	s_and_b32 s57, s52, 0xffff0000
	v_fmac_f32_e32 v148, s56, v80
	v_fmac_f32_e32 v149, s56, v81
	v_fmac_f32_e32 v150, s56, v82
	v_fmac_f32_e32 v151, s56, v83
	v_fmac_f32_e32 v148, s57, v84
	v_fmac_f32_e32 v149, s57, v85
	v_fmac_f32_e32 v150, s57, v86
	v_fmac_f32_e32 v151, s57, v87
	s_lshl_b32 s56, s53, 16
	s_and_b32 s57, s53, 0xffff0000
	v_fmac_f32_e32 v148, s56, v88
	v_fmac_f32_e32 v149, s56, v89
	v_fmac_f32_e32 v150, s56, v90
	v_fmac_f32_e32 v151, s56, v91
	v_fmac_f32_e32 v148, s57, v92
	v_fmac_f32_e32 v149, s57, v93
	v_fmac_f32_e32 v150, s57, v94
	v_fmac_f32_e32 v151, s57, v95
	s_lshl_b32 s56, s54, 16
	s_and_b32 s57, s54, 0xffff0000
	v_fmac_f32_e32 v148, s56, v96
	v_fmac_f32_e32 v149, s56, v97
	v_fmac_f32_e32 v150, s56, v98
	v_fmac_f32_e32 v151, s56, v99
	v_fmac_f32_e32 v148, s57, v100
	v_fmac_f32_e32 v149, s57, v101
	v_fmac_f32_e32 v150, s57, v102
	v_fmac_f32_e32 v151, s57, v103
	s_lshl_b32 s56, s55, 16
	s_and_b32 s57, s55, 0xffff0000
	v_fmac_f32_e32 v148, s56, v104
	v_fmac_f32_e32 v149, s56, v105
	v_fmac_f32_e32 v150, s56, v106
	v_fmac_f32_e32 v151, s56, v107
	v_fmac_f32_e32 v148, s57, v108
	v_fmac_f32_e32 v149, s57, v109
	v_fmac_f32_e32 v150, s57, v110
	v_fmac_f32_e32 v151, s57, v111
	v_xor_b32_e32 v148, 0x80000000, v148
	v_mul_f32_e64 v152, |v148|, s28
	v_exp_f32_e32 v152, v152
	v_max_f32_e32 v148, 0, v148
	v_add_f32_e32 v152, 1.0, v152
	v_log_f32_e32 v152, v152
	s_nop 0
	v_fmac_f32_e32 v148, 0x3f317218, v152
	v_mul_f32_e32 v132, 0xbd800000, v148
	v_xor_b32_e32 v149, 0x80000000, v149
	v_mul_f32_e64 v152, |v149|, s28
	v_exp_f32_e32 v152, v152
	v_max_f32_e32 v149, 0, v149
	v_add_f32_e32 v152, 1.0, v152
	v_log_f32_e32 v152, v152
	s_nop 0
	v_fmac_f32_e32 v149, 0x3f317218, v152
	v_mul_f32_e32 v133, 0xbd800000, v149
	v_xor_b32_e32 v150, 0x80000000, v150
	v_mul_f32_e64 v152, |v150|, s28
	v_exp_f32_e32 v152, v152
	v_max_f32_e32 v150, 0, v150
	v_add_f32_e32 v152, 1.0, v152
	v_log_f32_e32 v152, v152
	s_nop 0
	v_fmac_f32_e32 v150, 0x3f317218, v152
	v_mul_f32_e32 v134, 0xbd800000, v150
	v_xor_b32_e32 v151, 0x80000000, v151
	v_mul_f32_e64 v152, |v151|, s28
	v_exp_f32_e32 v152, v152
	v_max_f32_e32 v151, 0, v151
	v_add_f32_e32 v152, 1.0, v152
	v_log_f32_e32 v152, v152
	s_nop 0
	v_fmac_f32_e32 v151, 0x3f317218, v152
	v_mul_f32_e32 v135, 0xbd800000, v151
	v_add_f32_e32 v132, v132, v128
	v_add_f32_e32 v133, v133, v129
	v_add_f32_e32 v134, v134, v130
	v_add_f32_e32 v135, v135, v131
	v_readlane_b32 s48, v176, 40
	v_readlane_b32 s49, v176, 41
	v_readlane_b32 s50, v176, 42
	v_readlane_b32 s51, v176, 43
	v_readlane_b32 s52, v176, 44
	v_readlane_b32 s53, v176, 45
	v_readlane_b32 s54, v176, 46
	v_readlane_b32 s55, v176, 47
	v_mov_b32_e32 v148, v112
	v_mov_b32_e32 v149, v113
	v_mov_b32_e32 v150, v114
	v_mov_b32_e32 v151, v115
	s_lshl_b32 s56, s48, 16
	s_and_b32 s57, s48, 0xffff0000
	v_fmac_f32_e32 v148, s56, v48
	v_fmac_f32_e32 v149, s56, v49
	v_fmac_f32_e32 v150, s56, v50
	v_fmac_f32_e32 v151, s56, v51
	v_fmac_f32_e32 v148, s57, v52
	v_fmac_f32_e32 v149, s57, v53
	v_fmac_f32_e32 v150, s57, v54
	v_fmac_f32_e32 v151, s57, v55
	s_lshl_b32 s56, s49, 16
	s_and_b32 s57, s49, 0xffff0000
	v_fmac_f32_e32 v148, s56, v56
	v_fmac_f32_e32 v149, s56, v57
	v_fmac_f32_e32 v150, s56, v58
	v_fmac_f32_e32 v151, s56, v59
; __device__ __forceinline__ float softplusf_(float x) { return fmaxf(x, 0.f) + __logf(1.0f + __expf(-fabsf(x))); }
; __device__ void prep_gla(const Ctx& c, int ck, int blk) {
;     ...
;                 for (int j = 0; j < 8; ++j) { const int l = lh + l0 + j;
;                     float x = b2;
; #pragma unroll
;                     for (int r4 = 0; r4 < 16; r4 += 4) { const f32x4 lv = *(const f32x4*)(lr_s + l * 16 + r4); x += lv[0] * w2r[r4] + lv[1] * w2r[r4 + 1] + lv[2] * w2r[r4 + 2] + lv[3] * w2r[r4 + 3]; }
;                     G += -softplusf_(-x) * (1.0f / 16.0f);
	v_fmac_f32_e32 v148, s57, v60
	v_fmac_f32_e32 v149, s57, v61
	v_fmac_f32_e32 v150, s57, v62
	v_fmac_f32_e32 v151, s57, v63
	s_lshl_b32 s56, s50, 16
	s_and_b32 s57, s50, 0xffff0000
	v_fmac_f32_e32 v148, s56, v64
	v_fmac_f32_e32 v149, s56, v65
	v_fmac_f32_e32 v150, s56, v66
	v_fmac_f32_e32 v151, s56, v67
	v_fmac_f32_e32 v148, s57, v68
	v_fmac_f32_e32 v149, s57, v69
	v_fmac_f32_e32 v150, s57, v70
	v_fmac_f32_e32 v151, s57, v71
	s_lshl_b32 s56, s51, 16
	s_and_b32 s57, s51, 0xffff0000
	v_fmac_f32_e32 v148, s56, v72
	v_fmac_f32_e32 v149, s56, v73
	v_fmac_f32_e32 v150, s56, v74
	v_fmac_f32_e32 v151, s56, v75
	v_fmac_f32_e32 v148, s57, v76
	v_fmac_f32_e32 v149, s57, v77
	v_fmac_f32_e32 v150, s57, v78
	v_fmac_f32_e32 v151, s57, v79
	s_lshl_b32 s56, s52, 16
	s_and_b32 s57, s52, 0xffff0000
	v_fmac_f32_e32 v148, s56, v80
	v_fmac_f32_e32 v149, s56, v81
	v_fmac_f32_e32 v150, s56, v82
	v_fmac_f32_e32 v151, s56, v83
	v_fmac_f32_e32 v148, s57, v84
	v_fmac_f32_e32 v149, s57, v85
	v_fmac_f32_e32 v150, s57, v86
	v_fmac_f32_e32 v151, s57, v87
	s_lshl_b32 s56, s53, 16
	s_and_b32 s57, s53, 0xffff0000
	v_fmac_f32_e32 v148, s56, v88
	v_fmac_f32_e32 v149, s56, v89
	v_fmac_f32_e32 v150, s56, v90
	v_fmac_f32_e32 v151, s56, v91
	v_fmac_f32_e32 v148, s57, v92
	v_fmac_f32_e32 v149, s57, v93
	v_fmac_f32_e32 v150, s57, v94
	v_fmac_f32_e32 v151, s57, v95
	s_lshl_b32 s56, s54, 16
	s_and_b32 s57, s54, 0xffff0000
	v_fmac_f32_e32 v148, s56, v96
	v_fmac_f32_e32 v149, s56, v97
	v_fmac_f32_e32 v150, s56, v98
	v_fmac_f32_e32 v151, s56, v99
	v_fmac_f32_e32 v148, s57, v100
	v_fmac_f32_e32 v149, s57, v101
	v_fmac_f32_e32 v150, s57, v102
	v_fmac_f32_e32 v151, s57, v103
	s_lshl_b32 s56, s55, 16
	s_and_b32 s57, s55, 0xffff0000
	v_fmac_f32_e32 v148, s56, v104
	v_fmac_f32_e32 v149, s56, v105
	v_fmac_f32_e32 v150, s56, v106
	v_fmac_f32_e32 v151, s56, v107
	v_fmac_f32_e32 v148, s57, v108
	v_fmac_f32_e32 v149, s57, v109
	v_fmac_f32_e32 v150, s57, v110
	v_fmac_f32_e32 v151, s57, v111
	v_xor_b32_e32 v148, 0x80000000, v148
	v_mul_f32_e64 v152, |v148|, s28
	v_exp_f32_e32 v152, v152
	v_max_f32_e32 v148, 0, v148
	v_add_f32_e32 v152, 1.0, v152
	v_log_f32_e32 v152, v152
	s_nop 0
	v_fmac_f32_e32 v148, 0x3f317218, v152
	v_mul_f32_e32 v136, 0xbd800000, v148
	v_xor_b32_e32 v149, 0x80000000, v149
	v_mul_f32_e64 v152, |v149|, s28
	v_exp_f32_e32 v152, v152
	v_max_f32_e32 v149, 0, v149
	v_add_f32_e32 v152, 1.0, v152
	v_log_f32_e32 v152, v152
	s_nop 0
	v_fmac_f32_e32 v149, 0x3f317218, v152
	v_mul_f32_e32 v137, 0xbd800000, v149
	v_xor_b32_e32 v150, 0x80000000, v150
	v_mul_f32_e64 v152, |v150|, s28
	v_exp_f32_e32 v152, v152
	v_max_f32_e32 v150, 0, v150
	v_add_f32_e32 v152, 1.0, v152
	v_log_f32_e32 v152, v152
	s_nop 0
	v_fmac_f32_e32 v150, 0x3f317218, v152
	v_mul_f32_e32 v138, 0xbd800000, v150
	v_xor_b32_e32 v151, 0x80000000, v151
	v_mul_f32_e64 v152, |v151|, s28
	v_exp_f32_e32 v152, v152
	v_max_f32_e32 v151, 0, v151
	v_add_f32_e32 v152, 1.0, v152
	v_log_f32_e32 v152, v152
	s_nop 0
	v_fmac_f32_e32 v151, 0x3f317218, v152
	v_mul_f32_e32 v139, 0xbd800000, v151
	v_add_f32_e32 v136, v136, v132
	v_add_f32_e32 v137, v137, v133
	v_add_f32_e32 v138, v138, v134
	v_add_f32_e32 v139, v139, v135
	v_readlane_b32 s48, v176, 48
	v_readlane_b32 s49, v176, 49
	v_readlane_b32 s50, v176, 50
	v_readlane_b32 s51, v176, 51
	v_readlane_b32 s52, v176, 52
	v_readlane_b32 s53, v176, 53
	v_readlane_b32 s54, v176, 54
	v_readlane_b32 s55, v176, 55
	v_mov_b32_e32 v148, v112
	v_mov_b32_e32 v149, v113
	v_mov_b32_e32 v150, v114
	v_mov_b32_e32 v151, v115
	s_lshl_b32 s56, s48, 16
	s_and_b32 s57, s48, 0xffff0000
	v_fmac_f32_e32 v148, s56, v48
	v_fmac_f32_e32 v149, s56, v49
	v_fmac_f32_e32 v150, s56, v50
	v_fmac_f32_e32 v151, s56, v51
	v_fmac_f32_e32 v148, s57, v52
	v_fmac_f32_e32 v149, s57, v53
	v_fmac_f32_e32 v150, s57, v54
	v_fmac_f32_e32 v151, s57, v55
	s_lshl_b32 s56, s49, 16
	s_and_b32 s57, s49, 0xffff0000
	v_fmac_f32_e32 v148, s56, v56
	v_fmac_f32_e32 v149, s56, v57
	v_fmac_f32_e32 v150, s56, v58
	v_fmac_f32_e32 v151, s56, v59
	v_fmac_f32_e32 v148, s57, v60
	v_fmac_f32_e32 v149, s57, v61
	v_fmac_f32_e32 v150, s57, v62
	v_fmac_f32_e32 v151, s57, v63
	s_lshl_b32 s56, s50, 16
	s_and_b32 s57, s50, 0xffff0000
	v_fmac_f32_e32 v148, s56, v64
	v_fmac_f32_e32 v149, s56, v65
	v_fmac_f32_e32 v150, s56, v66
	v_fmac_f32_e32 v151, s56, v67
	v_fmac_f32_e32 v148, s57, v68
	v_fmac_f32_e32 v149, s57, v69
	v_fmac_f32_e32 v150, s57, v70
	v_fmac_f32_e32 v151, s57, v71
	s_lshl_b32 s56, s51, 16
	s_and_b32 s57, s51, 0xffff0000
	v_fmac_f32_e32 v148, s56, v72
	v_fmac_f32_e32 v149, s56, v73
	v_fmac_f32_e32 v150, s56, v74
	v_fmac_f32_e32 v151, s56, v75
	v_fmac_f32_e32 v148, s57, v76
	v_fmac_f32_e32 v149, s57, v77
	v_fmac_f32_e32 v150, s57, v78
	v_fmac_f32_e32 v151, s57, v79
	s_lshl_b32 s56, s52, 16
	s_and_b32 s57, s52, 0xffff0000
	v_fmac_f32_e32 v148, s56, v80
	v_fmac_f32_e32 v149, s56, v81
	v_fmac_f32_e32 v150, s56, v82
	v_fmac_f32_e32 v151, s56, v83
	v_fmac_f32_e32 v148, s57, v84
	v_fmac_f32_e32 v149, s57, v85
	v_fmac_f32_e32 v150, s57, v86
	v_fmac_f32_e32 v151, s57, v87
	s_lshl_b32 s56, s53, 16
	s_and_b32 s57, s53, 0xffff0000
	v_fmac_f32_e32 v148, s56, v88
	v_fmac_f32_e32 v149, s56, v89
	v_fmac_f32_e32 v150, s56, v90
	v_fmac_f32_e32 v151, s56, v91
	v_fmac_f32_e32 v148, s57, v92
	v_fmac_f32_e32 v149, s57, v93
	v_fmac_f32_e32 v150, s57, v94
	v_fmac_f32_e32 v151, s57, v95
	s_lshl_b32 s56, s54, 16
	s_and_b32 s57, s54, 0xffff0000
	v_fmac_f32_e32 v148, s56, v96
	v_fmac_f32_e32 v149, s56, v97
	v_fmac_f32_e32 v150, s56, v98
	v_fmac_f32_e32 v151, s56, v99
	v_fmac_f32_e32 v148, s57, v100
	v_fmac_f32_e32 v149, s57, v101
	v_fmac_f32_e32 v150, s57, v102
	v_fmac_f32_e32 v151, s57, v103
; __device__ __forceinline__ float softplusf_(float x) { return fmaxf(x, 0.f) + __logf(1.0f + __expf(-fabsf(x))); }
; __device__ void prep_gla(const Ctx& c, int ck, int blk) {
;     ...
;                 for (int j = 0; j < 8; ++j) { const int l = lh + l0 + j;
;                     float x = b2;
; #pragma unroll
;                     for (int r4 = 0; r4 < 16; r4 += 4) { const f32x4 lv = *(const f32x4*)(lr_s + l * 16 + r4); x += lv[0] * w2r[r4] + lv[1] * w2r[r4 + 1] + lv[2] * w2r[r4 + 2] + lv[3] * w2r[r4 + 3]; }
;                     G += -softplusf_(-x) * (1.0f / 16.0f);
	s_lshl_b32 s56, s55, 16
	s_and_b32 s57, s55, 0xffff0000
	v_fmac_f32_e32 v148, s56, v104
	v_fmac_f32_e32 v149, s56, v105
	v_fmac_f32_e32 v150, s56, v106
	v_fmac_f32_e32 v151, s56, v107
	v_fmac_f32_e32 v148, s57, v108
	v_fmac_f32_e32 v149, s57, v109
	v_fmac_f32_e32 v150, s57, v110
	v_fmac_f32_e32 v151, s57, v111
	v_xor_b32_e32 v148, 0x80000000, v148
	v_mul_f32_e64 v152, |v148|, s28
	v_exp_f32_e32 v152, v152
	v_max_f32_e32 v148, 0, v148
	v_add_f32_e32 v152, 1.0, v152
	v_log_f32_e32 v152, v152
	s_nop 0
	v_fmac_f32_e32 v148, 0x3f317218, v152
	v_mul_f32_e32 v140, 0xbd800000, v148
	v_xor_b32_e32 v149, 0x80000000, v149
	v_mul_f32_e64 v152, |v149|, s28
	v_exp_f32_e32 v152, v152
	v_max_f32_e32 v149, 0, v149
	v_add_f32_e32 v152, 1.0, v152
	v_log_f32_e32 v152, v152
	s_nop 0
	v_fmac_f32_e32 v149, 0x3f317218, v152
	v_mul_f32_e32 v141, 0xbd800000, v149
	v_xor_b32_e32 v150, 0x80000000, v150
	v_mul_f32_e64 v152, |v150|, s28
	v_exp_f32_e32 v152, v152
	v_max_f32_e32 v150, 0, v150
	v_add_f32_e32 v152, 1.0, v152
	v_log_f32_e32 v152, v152
	s_nop 0
	v_fmac_f32_e32 v150, 0x3f317218, v152
	v_mul_f32_e32 v142, 0xbd800000, v150
	v_xor_b32_e32 v151, 0x80000000, v151
	v_mul_f32_e64 v152, |v151|, s28
	v_exp_f32_e32 v152, v152
	v_max_f32_e32 v151, 0, v151
	v_add_f32_e32 v152, 1.0, v152
	v_log_f32_e32 v152, v152
	s_nop 0
	v_fmac_f32_e32 v151, 0x3f317218, v152
	v_mul_f32_e32 v143, 0xbd800000, v151
	v_add_f32_e32 v140, v140, v136
	v_add_f32_e32 v141, v141, v137
	v_add_f32_e32 v142, v142, v138
	v_add_f32_e32 v143, v143, v139
	v_readlane_b32 s48, v176, 56
	v_readlane_b32 s49, v176, 57
	v_readlane_b32 s50, v176, 58
	v_readlane_b32 s51, v176, 59
	v_readlane_b32 s52, v176, 60
	v_readlane_b32 s53, v176, 61
	v_readlane_b32 s54, v176, 62
	v_readlane_b32 s55, v176, 63
	v_mov_b32_e32 v148, v112
	v_mov_b32_e32 v149, v113
	v_mov_b32_e32 v150, v114
	v_mov_b32_e32 v151, v115
	s_lshl_b32 s56, s48, 16
	s_and_b32 s57, s48, 0xffff0000
	v_fmac_f32_e32 v148, s56, v48
	v_fmac_f32_e32 v149, s56, v49
	v_fmac_f32_e32 v150, s56, v50
	v_fmac_f32_e32 v151, s56, v51
	v_fmac_f32_e32 v148, s57, v52
	v_fmac_f32_e32 v149, s57, v53
	v_fmac_f32_e32 v150, s57, v54
	v_fmac_f32_e32 v151, s57, v55
	s_lshl_b32 s56, s49, 16
	s_and_b32 s57, s49, 0xffff0000
	v_fmac_f32_e32 v148, s56, v56
	v_fmac_f32_e32 v149, s56, v57
	v_fmac_f32_e32 v150, s56, v58
	v_fmac_f32_e32 v151, s56, v59
	v_fmac_f32_e32 v148, s57, v60
	v_fmac_f32_e32 v149, s57, v61
	v_fmac_f32_e32 v150, s57, v62
	v_fmac_f32_e32 v151, s57, v63
	s_lshl_b32 s56, s50, 16
	s_and_b32 s57, s50, 0xffff0000
	v_fmac_f32_e32 v148, s56, v64
	v_fmac_f32_e32 v149, s56, v65
	v_fmac_f32_e32 v150, s56, v66
	v_fmac_f32_e32 v151, s56, v67
	v_fmac_f32_e32 v148, s57, v68
	v_fmac_f32_e32 v149, s57, v69
	v_fmac_f32_e32 v150, s57, v70
	v_fmac_f32_e32 v151, s57, v71
	s_lshl_b32 s56, s51, 16
	s_and_b32 s57, s51, 0xffff0000
	v_fmac_f32_e32 v148, s56, v72
	v_fmac_f32_e32 v149, s56, v73
	v_fmac_f32_e32 v150, s56, v74
	v_fmac_f32_e32 v151, s56, v75
	v_fmac_f32_e32 v148, s57, v76
	v_fmac_f32_e32 v149, s57, v77
	v_fmac_f32_e32 v150, s57, v78
	v_fmac_f32_e32 v151, s57, v79
	s_lshl_b32 s56, s52, 16
	s_and_b32 s57, s52, 0xffff0000
	v_fmac_f32_e32 v148, s56, v80
	v_fmac_f32_e32 v149, s56, v81
	v_fmac_f32_e32 v150, s56, v82
	v_fmac_f32_e32 v151, s56, v83
	v_fmac_f32_e32 v148, s57, v84
	v_fmac_f32_e32 v149, s57, v85
	v_fmac_f32_e32 v150, s57, v86
	v_fmac_f32_e32 v151, s57, v87
	s_lshl_b32 s56, s53, 16
	s_and_b32 s57, s53, 0xffff0000
	v_fmac_f32_e32 v148, s56, v88
	v_fmac_f32_e32 v149, s56, v89
	v_fmac_f32_e32 v150, s56, v90
	v_fmac_f32_e32 v151, s56, v91
	v_fmac_f32_e32 v148, s57, v92
	v_fmac_f32_e32 v149, s57, v93
	v_fmac_f32_e32 v150, s57, v94
	v_fmac_f32_e32 v151, s57, v95
	s_lshl_b32 s56, s54, 16
	s_and_b32 s57, s54, 0xffff0000
	v_fmac_f32_e32 v148, s56, v96
	v_fmac_f32_e32 v149, s56, v97
	v_fmac_f32_e32 v150, s56, v98
	v_fmac_f32_e32 v151, s56, v99
	v_fmac_f32_e32 v148, s57, v100
	v_fmac_f32_e32 v149, s57, v101
	v_fmac_f32_e32 v150, s57, v102
	v_fmac_f32_e32 v151, s57, v103
	s_lshl_b32 s56, s55, 16
	s_and_b32 s57, s55, 0xffff0000
	v_fmac_f32_e32 v148, s56, v104
	v_fmac_f32_e32 v149, s56, v105
	v_fmac_f32_e32 v150, s56, v106
	v_fmac_f32_e32 v151, s56, v107
	v_fmac_f32_e32 v148, s57, v108
	v_fmac_f32_e32 v149, s57, v109
	v_fmac_f32_e32 v150, s57, v110
	v_fmac_f32_e32 v151, s57, v111
	v_xor_b32_e32 v148, 0x80000000, v148
	v_mul_f32_e64 v152, |v148|, s28
	v_exp_f32_e32 v152, v152
	v_max_f32_e32 v148, 0, v148
	v_add_f32_e32 v152, 1.0, v152
	v_log_f32_e32 v152, v152
	s_nop 0
	v_fmac_f32_e32 v148, 0x3f317218, v152
	v_mul_f32_e32 v144, 0xbd800000, v148
	v_xor_b32_e32 v149, 0x80000000, v149
	v_mul_f32_e64 v152, |v149|, s28
	v_exp_f32_e32 v152, v152
	v_max_f32_e32 v149, 0, v149
	v_add_f32_e32 v152, 1.0, v152
	v_log_f32_e32 v152, v152
	s_nop 0
	v_fmac_f32_e32 v149, 0x3f317218, v152
	v_mul_f32_e32 v145, 0xbd800000, v149
	v_xor_b32_e32 v150, 0x80000000, v150
	v_mul_f32_e64 v152, |v150|, s28
	v_exp_f32_e32 v152, v152
	v_max_f32_e32 v150, 0, v150
	v_add_f32_e32 v152, 1.0, v152
	v_log_f32_e32 v152, v152
	s_nop 0
	v_fmac_f32_e32 v150, 0x3f317218, v152
	v_mul_f32_e32 v146, 0xbd800000, v150
	v_xor_b32_e32 v151, 0x80000000, v151
	v_mul_f32_e64 v152, |v151|, s28
	v_exp_f32_e32 v152, v152
	v_max_f32_e32 v151, 0, v151
	v_add_f32_e32 v152, 1.0, v152
	v_log_f32_e32 v152, v152
	s_nop 0
	v_fmac_f32_e32 v151, 0x3f317218, v152
	v_mul_f32_e32 v147, 0xbd800000, v151
	v_add_f32_e32 v144, v144, v140
	v_add_f32_e32 v145, v145, v141
	v_add_f32_e32 v146, v146, v142
	v_add_f32_e32 v147, v147, v143
	v_lshlrev_b32_e32 v13, 4, v3
	s_lshl_b32 s22, s9, 10
	v_add_u32_e32 v14, s22, v13
	ds_write_b128 v14, v[144:147] offset:8192
	s_waitcnt lgkmcnt(0)
	s_barrier
; __device__ __forceinline__ unsigned pk2(float lo, float hi) { const f32v2_t v = {lo, hi}; const bf16v2_t b = __builtin_convertvector(v, bf16v2_t); return __builtin_bit_cast(unsigned, b); }
; __device__ __forceinline__ float softplusf_(float x) { return fmaxf(x, 0.f) + __logf(1.0f + __expf(-fabsf(x))); }
; __device__ void prep_gla(const Ctx& c, int ck, int blk) {
;     ...
;                     G += -softplusf_(-x) * (1.0f / 16.0f);
;                     const float qv = qr[l0 + j] * 0.08838834764831845f, kv = kr[l0 + j];
;                     const size_t o = ((size_t)(ck * 4 + h) * 64 + l) * 128 + k;
;                     gQg[o] = f2bf(qv * __expf(G)); const float kneg = kv * __expf(-G); gKn[o] = f2bf(kneg); kn[j] = kneg; }
;                 u32x4 a; a.x = pk2(kn[0], kn[1]); a.y = pk2(kn[2], kn[3]); a.z = pk2(kn[4], kn[5]); a.w = pk2(kn[6], kn[7]);
;                 *(u32x4*)(gKnT + ((size_t)(ck * 4 + h) * 128 + k) * 64 + lh + l0) = a;
	v_mov_b32_e32 v148, 0
	v_mov_b32_e32 v149, 0
	v_mov_b32_e32 v150, 0
	v_mov_b32_e32 v151, 0
	s_cmp_gt_u32 s9, 0
	s_cbranch_scc0 .Lprep_goff_done
	ds_read_b128 v[152:155], v13 offset:8192
	s_waitcnt lgkmcnt(0)
	v_add_f32_e32 v148, v148, v152
	v_add_f32_e32 v149, v149, v153
	v_add_f32_e32 v150, v150, v154
	v_add_f32_e32 v151, v151, v155
	s_cmp_gt_u32 s9, 1
	s_cbranch_scc0 .Lprep_goff_done
	ds_read_b128 v[152:155], v13 offset:9216
	s_waitcnt lgkmcnt(0)
	v_add_f32_e32 v148, v148, v152
	v_add_f32_e32 v149, v149, v153
	v_add_f32_e32 v150, v150, v154
	v_add_f32_e32 v151, v151, v155
	s_cmp_gt_u32 s9, 2
	s_cbranch_scc0 .Lprep_goff_done
	ds_read_b128 v[152:155], v13 offset:10240
	s_waitcnt lgkmcnt(0)
	v_add_f32_e32 v148, v148, v152
	v_add_f32_e32 v149, v149, v153
	v_add_f32_e32 v150, v150, v154
	v_add_f32_e32 v151, v151, v155
	s_cmp_gt_u32 s9, 3
	s_cbranch_scc0 .Lprep_goff_done
	ds_read_b128 v[152:155], v13 offset:11264
	s_waitcnt lgkmcnt(0)
	v_add_f32_e32 v148, v148, v152
	v_add_f32_e32 v149, v149, v153
	v_add_f32_e32 v150, v150, v154
	v_add_f32_e32 v151, v151, v155
	s_cmp_gt_u32 s9, 4
	s_cbranch_scc0 .Lprep_goff_done
	ds_read_b128 v[152:155], v13 offset:12288
	s_waitcnt lgkmcnt(0)
	v_add_f32_e32 v148, v148, v152
	v_add_f32_e32 v149, v149, v153
	v_add_f32_e32 v150, v150, v154
	v_add_f32_e32 v151, v151, v155
	s_cmp_gt_u32 s9, 5
	s_cbranch_scc0 .Lprep_goff_done
	ds_read_b128 v[152:155], v13 offset:13312
	s_waitcnt lgkmcnt(0)
	v_add_f32_e32 v148, v148, v152
	v_add_f32_e32 v149, v149, v153
	v_add_f32_e32 v150, v150, v154
	v_add_f32_e32 v151, v151, v155
	s_cmp_gt_u32 s9, 6
	s_cbranch_scc0 .Lprep_goff_done
	ds_read_b128 v[152:155], v13 offset:14336
	s_waitcnt lgkmcnt(0)
	v_add_f32_e32 v148, v148, v152
	v_add_f32_e32 v149, v149, v153
	v_add_f32_e32 v150, v150, v154
	v_add_f32_e32 v151, v151, v155
.Lprep_goff_done:
	v_lshrrev_b32_e32 v14, 5, v3
	s_lshl_b32 s22, s7, 2
	s_lshl_b32 s23, s8, 1
	s_add_u32 s22, s22, s23
	v_add_u32_e32 v14, s22, v14
	v_lshlrev_b32_e32 v14, 14, v14
	v_and_b32_e32 v15, 31, v3
	v_lshl_add_u32 v4, v15, 3, v14
	s_lshl_b32 s22, s9, 11
	v_add_u32_e32 v4, s22, v4
	v_add_u32_e32 v5, 0x30d81000, v4
	v_add_u32_e32 v4, 0x30581000, v4
	s_lshl_b32 s22, s7, 2
	s_lshl_b32 s23, s8, 1
	s_add_u32 s22, s22, s23
	s_lshl_b32 s22, s22, 14
	v_lshl_add_u32 v6, v3, 9, s22
	s_lshl_b32 s23, s9, 4
	v_add_u32_e32 v6, s23, v6
	v_add_u32_e32 v6, 0x31581000, v6
	v_add_f32_e32 v116, v116, v148
	v_mul_f32_e32 v152, 0x3fb8aa3b, v116
	v_mul_f32_e32 v156, 0xbfb8aa3b, v116
	v_add_f32_e32 v117, v117, v149
	v_mul_f32_e32 v153, 0x3fb8aa3b, v117
	v_mul_f32_e32 v157, 0xbfb8aa3b, v117
	v_add_f32_e32 v118, v118, v150
	v_mul_f32_e32 v154, 0x3fb8aa3b, v118
	v_mul_f32_e32 v158, 0xbfb8aa3b, v118
	v_add_f32_e32 v119, v119, v151
	v_mul_f32_e32 v155, 0x3fb8aa3b, v119
	v_mul_f32_e32 v159, 0xbfb8aa3b, v119
	v_exp_f32_e32 v152, v152
	v_exp_f32_e32 v153, v153
	v_exp_f32_e32 v154, v154
	v_exp_f32_e32 v155, v155
	v_exp_f32_e32 v156, v156
	v_exp_f32_e32 v157, v157
	v_exp_f32_e32 v158, v158
	v_exp_f32_e32 v159, v159
	v_lshlrev_b32_e32 v160, 16, v16
	v_and_b32_e32 v161, 0xffff0000, v16
	v_lshlrev_b32_e32 v168, 16, v32
	v_and_b32_e32 v169, 0xffff0000, v32
	v_lshlrev_b32_e32 v162, 16, v17
	v_and_b32_e32 v163, 0xffff0000, v17
	v_lshlrev_b32_e32 v170, 16, v33
	v_and_b32_e32 v171, 0xffff0000, v33
	v_mul_f32_e32 v160, 0x3db504f3, v160
	v_mul_f32_e32 v160, v160, v152
	v_mul_f32_e32 v168, v168, v156
	v_mul_f32_e32 v161, 0x3db504f3, v161
	v_mul_f32_e32 v161, v161, v153
	v_mul_f32_e32 v169, v169, v157
	v_mul_f32_e32 v162, 0x3db504f3, v162
	v_mul_f32_e32 v162, v162, v154
	v_mul_f32_e32 v170, v170, v158
	v_mul_f32_e32 v163, 0x3db504f3, v163
	v_mul_f32_e32 v163, v163, v155
	v_mul_f32_e32 v171, v171, v159
	v_cvt_pk_bf16_f32 v164, v160, v161
	v_cvt_pk_bf16_f32 v165, v162, v163
	v_cvt_pk_bf16_f32 v166, v168, v169
	v_cvt_pk_bf16_f32 v167, v170, v171
	global_store_dwordx2 v4, v[164:165], s[4:5] offset:0
	global_store_dwordx2 v5, v[166:167], s[4:5] offset:0
	v_add_f32_e32 v120, v120, v148
	v_mul_f32_e32 v152, 0x3fb8aa3b, v120
	v_mul_f32_e32 v156, 0xbfb8aa3b, v120
	v_add_f32_e32 v121, v121, v149
	v_mul_f32_e32 v153, 0x3fb8aa3b, v121
	v_mul_f32_e32 v157, 0xbfb8aa3b, v121
	v_add_f32_e32 v122, v122, v150
	v_mul_f32_e32 v154, 0x3fb8aa3b, v122
	v_mul_f32_e32 v158, 0xbfb8aa3b, v122
	v_add_f32_e32 v123, v123, v151
	v_mul_f32_e32 v155, 0x3fb8aa3b, v123
	v_mul_f32_e32 v159, 0xbfb8aa3b, v123
	v_exp_f32_e32 v152, v152
	v_exp_f32_e32 v153, v153
	v_exp_f32_e32 v154, v154
	v_exp_f32_e32 v155, v155
	v_exp_f32_e32 v156, v156
	v_exp_f32_e32 v157, v157
	v_exp_f32_e32 v158, v158
	v_exp_f32_e32 v159, v159
	v_lshlrev_b32_e32 v160, 16, v18
	v_and_b32_e32 v161, 0xffff0000, v18
	v_lshlrev_b32_e32 v172, 16, v34
	v_and_b32_e32 v173, 0xffff0000, v34
	v_lshlrev_b32_e32 v162, 16, v19
	v_and_b32_e32 v163, 0xffff0000, v19
	v_lshlrev_b32_e32 v174, 16, v35
	v_and_b32_e32 v175, 0xffff0000, v35
	v_mul_f32_e32 v160, 0x3db504f3, v160
	v_mul_f32_e32 v160, v160, v152
	v_mul_f32_e32 v172, v172, v156
	v_mul_f32_e32 v161, 0x3db504f3, v161
	v_mul_f32_e32 v161, v161, v153
	v_mul_f32_e32 v173, v173, v157
	v_mul_f32_e32 v162, 0x3db504f3, v162
	v_mul_f32_e32 v162, v162, v154
	v_mul_f32_e32 v174, v174, v158
	v_mul_f32_e32 v163, 0x3db504f3, v163
	v_mul_f32_e32 v163, v163, v155
	v_mul_f32_e32 v175, v175, v159
	v_cvt_pk_bf16_f32 v164, v160, v161
	v_cvt_pk_bf16_f32 v165, v162, v163
	v_cvt_pk_bf16_f32 v166, v172, v173
	v_cvt_pk_bf16_f32 v167, v174, v175
	global_store_dwordx2 v4, v[164:165], s[4:5] offset:256
	global_store_dwordx2 v5, v[166:167], s[4:5] offset:256
	v_cvt_pk_bf16_f32 v192, v168, v172
	v_cvt_pk_bf16_f32 v196, v169, v173
	v_cvt_pk_bf16_f32 v200, v170, v174
; __device__ __forceinline__ unsigned pk2(float lo, float hi) { const f32v2_t v = {lo, hi}; const bf16v2_t b = __builtin_convertvector(v, bf16v2_t); return __builtin_bit_cast(unsigned, b); }
; __device__ void prep_gla(const Ctx& c, int ck, int blk) {
;     ...
;                     const float qv = qr[l0 + j] * 0.08838834764831845f, kv = kr[l0 + j];
;                     const size_t o = ((size_t)(ck * 4 + h) * 64 + l) * 128 + k;
;                     gQg[o] = f2bf(qv * __expf(G)); const float kneg = kv * __expf(-G); gKn[o] = f2bf(kneg); kn[j] = kneg; }
;                 u32x4 a; a.x = pk2(kn[0], kn[1]); a.y = pk2(kn[2], kn[3]); a.z = pk2(kn[4], kn[5]); a.w = pk2(kn[6], kn[7]);
;                 *(u32x4*)(gKnT + ((size_t)(ck * 4 + h) * 128 + k) * 64 + lh + l0) = a;
	v_cvt_pk_bf16_f32 v204, v171, v175
	v_add_f32_e32 v124, v124, v148
	v_mul_f32_e32 v152, 0x3fb8aa3b, v124
	v_mul_f32_e32 v156, 0xbfb8aa3b, v124
	v_add_f32_e32 v125, v125, v149
	v_mul_f32_e32 v153, 0x3fb8aa3b, v125
	v_mul_f32_e32 v157, 0xbfb8aa3b, v125
	v_add_f32_e32 v126, v126, v150
	v_mul_f32_e32 v154, 0x3fb8aa3b, v126
	v_mul_f32_e32 v158, 0xbfb8aa3b, v126
	v_add_f32_e32 v127, v127, v151
	v_mul_f32_e32 v155, 0x3fb8aa3b, v127
	v_mul_f32_e32 v159, 0xbfb8aa3b, v127
	v_exp_f32_e32 v152, v152
	v_exp_f32_e32 v153, v153
	v_exp_f32_e32 v154, v154
	v_exp_f32_e32 v155, v155
	v_exp_f32_e32 v156, v156
	v_exp_f32_e32 v157, v157
	v_exp_f32_e32 v158, v158
	v_exp_f32_e32 v159, v159
	v_lshlrev_b32_e32 v160, 16, v20
	v_and_b32_e32 v161, 0xffff0000, v20
	v_lshlrev_b32_e32 v168, 16, v36
	v_and_b32_e32 v169, 0xffff0000, v36
	v_lshlrev_b32_e32 v162, 16, v21
	v_and_b32_e32 v163, 0xffff0000, v21
	v_lshlrev_b32_e32 v170, 16, v37
	v_and_b32_e32 v171, 0xffff0000, v37
	v_mul_f32_e32 v160, 0x3db504f3, v160
	v_mul_f32_e32 v160, v160, v152
	v_mul_f32_e32 v168, v168, v156
	v_mul_f32_e32 v161, 0x3db504f3, v161
	v_mul_f32_e32 v161, v161, v153
	v_mul_f32_e32 v169, v169, v157
	v_mul_f32_e32 v162, 0x3db504f3, v162
	v_mul_f32_e32 v162, v162, v154
	v_mul_f32_e32 v170, v170, v158
	v_mul_f32_e32 v163, 0x3db504f3, v163
	v_mul_f32_e32 v163, v163, v155
	v_mul_f32_e32 v171, v171, v159
	v_cvt_pk_bf16_f32 v164, v160, v161
	v_cvt_pk_bf16_f32 v165, v162, v163
	v_cvt_pk_bf16_f32 v166, v168, v169
	v_cvt_pk_bf16_f32 v167, v170, v171
	global_store_dwordx2 v4, v[164:165], s[4:5] offset:512
	global_store_dwordx2 v5, v[166:167], s[4:5] offset:512
	v_add_f32_e32 v128, v128, v148
	v_mul_f32_e32 v152, 0x3fb8aa3b, v128
	v_mul_f32_e32 v156, 0xbfb8aa3b, v128
	v_add_f32_e32 v129, v129, v149
	v_mul_f32_e32 v153, 0x3fb8aa3b, v129
	v_mul_f32_e32 v157, 0xbfb8aa3b, v129
	v_add_f32_e32 v130, v130, v150
	v_mul_f32_e32 v154, 0x3fb8aa3b, v130
	v_mul_f32_e32 v158, 0xbfb8aa3b, v130
	v_add_f32_e32 v131, v131, v151
	v_mul_f32_e32 v155, 0x3fb8aa3b, v131
	v_mul_f32_e32 v159, 0xbfb8aa3b, v131
	v_exp_f32_e32 v152, v152
	v_exp_f32_e32 v153, v153
	v_exp_f32_e32 v154, v154
	v_exp_f32_e32 v155, v155
	v_exp_f32_e32 v156, v156
	v_exp_f32_e32 v157, v157
	v_exp_f32_e32 v158, v158
	v_exp_f32_e32 v159, v159
	v_lshlrev_b32_e32 v160, 16, v22
	v_and_b32_e32 v161, 0xffff0000, v22
	v_lshlrev_b32_e32 v172, 16, v38
	v_and_b32_e32 v173, 0xffff0000, v38
	v_lshlrev_b32_e32 v162, 16, v23
	v_and_b32_e32 v163, 0xffff0000, v23
	v_lshlrev_b32_e32 v174, 16, v39
	v_and_b32_e32 v175, 0xffff0000, v39
	v_mul_f32_e32 v160, 0x3db504f3, v160
	v_mul_f32_e32 v160, v160, v152
	v_mul_f32_e32 v172, v172, v156
	v_mul_f32_e32 v161, 0x3db504f3, v161
	v_mul_f32_e32 v161, v161, v153
	v_mul_f32_e32 v173, v173, v157
	v_mul_f32_e32 v162, 0x3db504f3, v162
	v_mul_f32_e32 v162, v162, v154
	v_mul_f32_e32 v174, v174, v158
	v_mul_f32_e32 v163, 0x3db504f3, v163
	v_mul_f32_e32 v163, v163, v155
	v_mul_f32_e32 v175, v175, v159
	v_cvt_pk_bf16_f32 v164, v160, v161
	v_cvt_pk_bf16_f32 v165, v162, v163
	v_cvt_pk_bf16_f32 v166, v172, v173
	v_cvt_pk_bf16_f32 v167, v174, v175
	global_store_dwordx2 v4, v[164:165], s[4:5] offset:768
	global_store_dwordx2 v5, v[166:167], s[4:5] offset:768
	v_cvt_pk_bf16_f32 v193, v168, v172
	v_cvt_pk_bf16_f32 v197, v169, v173
	v_cvt_pk_bf16_f32 v201, v170, v174
	v_cvt_pk_bf16_f32 v205, v171, v175
	v_add_f32_e32 v132, v132, v148
	v_mul_f32_e32 v152, 0x3fb8aa3b, v132
	v_mul_f32_e32 v156, 0xbfb8aa3b, v132
	v_add_f32_e32 v133, v133, v149
	v_mul_f32_e32 v153, 0x3fb8aa3b, v133
	v_mul_f32_e32 v157, 0xbfb8aa3b, v133
	v_add_f32_e32 v134, v134, v150
	v_mul_f32_e32 v154, 0x3fb8aa3b, v134
	v_mul_f32_e32 v158, 0xbfb8aa3b, v134
	v_add_f32_e32 v135, v135, v151
	v_mul_f32_e32 v155, 0x3fb8aa3b, v135
	v_mul_f32_e32 v159, 0xbfb8aa3b, v135
	v_exp_f32_e32 v152, v152
	v_exp_f32_e32 v153, v153
	v_exp_f32_e32 v154, v154
	v_exp_f32_e32 v155, v155
	v_exp_f32_e32 v156, v156
	v_exp_f32_e32 v157, v157
	v_exp_f32_e32 v158, v158
	v_exp_f32_e32 v159, v159
	v_lshlrev_b32_e32 v160, 16, v24
	v_and_b32_e32 v161, 0xffff0000, v24
	v_lshlrev_b32_e32 v168, 16, v40
	v_and_b32_e32 v169, 0xffff0000, v40
	v_lshlrev_b32_e32 v162, 16, v25
	v_and_b32_e32 v163, 0xffff0000, v25
	v_lshlrev_b32_e32 v170, 16, v41
	v_and_b32_e32 v171, 0xffff0000, v41
	v_mul_f32_e32 v160, 0x3db504f3, v160
	v_mul_f32_e32 v160, v160, v152
	v_mul_f32_e32 v168, v168, v156
	v_mul_f32_e32 v161, 0x3db504f3, v161
	v_mul_f32_e32 v161, v161, v153
	v_mul_f32_e32 v169, v169, v157
	v_mul_f32_e32 v162, 0x3db504f3, v162
	v_mul_f32_e32 v162, v162, v154
	v_mul_f32_e32 v170, v170, v158
	v_mul_f32_e32 v163, 0x3db504f3, v163
	v_mul_f32_e32 v163, v163, v155
	v_mul_f32_e32 v171, v171, v159
	v_cvt_pk_bf16_f32 v164, v160, v161
	v_cvt_pk_bf16_f32 v165, v162, v163
	v_cvt_pk_bf16_f32 v166, v168, v169
	v_cvt_pk_bf16_f32 v167, v170, v171
	global_store_dwordx2 v4, v[164:165], s[4:5] offset:1024
	global_store_dwordx2 v5, v[166:167], s[4:5] offset:1024
	v_add_f32_e32 v136, v136, v148
	v_mul_f32_e32 v152, 0x3fb8aa3b, v136
	v_mul_f32_e32 v156, 0xbfb8aa3b, v136
	v_add_f32_e32 v137, v137, v149
	v_mul_f32_e32 v153, 0x3fb8aa3b, v137
	v_mul_f32_e32 v157, 0xbfb8aa3b, v137
	v_add_f32_e32 v138, v138, v150
	v_mul_f32_e32 v154, 0x3fb8aa3b, v138
	v_mul_f32_e32 v158, 0xbfb8aa3b, v138
	v_add_f32_e32 v139, v139, v151
	v_mul_f32_e32 v155, 0x3fb8aa3b, v139
	v_mul_f32_e32 v159, 0xbfb8aa3b, v139
	v_exp_f32_e32 v152, v152
	v_exp_f32_e32 v153, v153
	v_exp_f32_e32 v154, v154
	v_exp_f32_e32 v155, v155
	v_exp_f32_e32 v156, v156
	v_exp_f32_e32 v157, v157
	v_exp_f32_e32 v158, v158
	v_exp_f32_e32 v159, v159
	v_lshlrev_b32_e32 v160, 16, v26
	v_and_b32_e32 v161, 0xffff0000, v26
; __device__ __forceinline__ unsigned pk2(float lo, float hi) { const f32v2_t v = {lo, hi}; const bf16v2_t b = __builtin_convertvector(v, bf16v2_t); return __builtin_bit_cast(unsigned, b); }
;     template <class Tp> __device__ __forceinline__ Tp* W(size_t off) const { return (Tp*)(ws + off); }
; __device__ void prep_gla(const Ctx& c, int ck, int blk) {
;     ...
;                     const size_t o = ((size_t)(ck * 4 + h) * 64 + l) * 128 + k;
;                     gQg[o] = f2bf(qv * __expf(G)); const float kneg = kv * __expf(-G); gKn[o] = f2bf(kneg); kn[j] = kneg; }
;                 u32x4 a; a.x = pk2(kn[0], kn[1]); a.y = pk2(kn[2], kn[3]); a.z = pk2(kn[4], kn[5]); a.w = pk2(kn[6], kn[7]);
;                 *(u32x4*)(gKnT + ((size_t)(ck * 4 + h) * 128 + k) * 64 + lh + l0) = a;
;             }
;         }
;         c.W<float>(WS_GDEC)[(size_t)ck * 512 + ch] = __expf(G);
	v_lshlrev_b32_e32 v172, 16, v42
	v_and_b32_e32 v173, 0xffff0000, v42
	v_lshlrev_b32_e32 v162, 16, v27
	v_and_b32_e32 v163, 0xffff0000, v27
	v_lshlrev_b32_e32 v174, 16, v43
	v_and_b32_e32 v175, 0xffff0000, v43
	v_mul_f32_e32 v160, 0x3db504f3, v160
	v_mul_f32_e32 v160, v160, v152
	v_mul_f32_e32 v172, v172, v156
	v_mul_f32_e32 v161, 0x3db504f3, v161
	v_mul_f32_e32 v161, v161, v153
	v_mul_f32_e32 v173, v173, v157
	v_mul_f32_e32 v162, 0x3db504f3, v162
	v_mul_f32_e32 v162, v162, v154
	v_mul_f32_e32 v174, v174, v158
	v_mul_f32_e32 v163, 0x3db504f3, v163
	v_mul_f32_e32 v163, v163, v155
	v_mul_f32_e32 v175, v175, v159
	v_cvt_pk_bf16_f32 v164, v160, v161
	v_cvt_pk_bf16_f32 v165, v162, v163
	v_cvt_pk_bf16_f32 v166, v172, v173
	v_cvt_pk_bf16_f32 v167, v174, v175
	global_store_dwordx2 v4, v[164:165], s[4:5] offset:1280
	global_store_dwordx2 v5, v[166:167], s[4:5] offset:1280
	v_cvt_pk_bf16_f32 v194, v168, v172
	v_cvt_pk_bf16_f32 v198, v169, v173
	v_cvt_pk_bf16_f32 v202, v170, v174
	v_cvt_pk_bf16_f32 v206, v171, v175
	v_add_f32_e32 v140, v140, v148
	v_mul_f32_e32 v152, 0x3fb8aa3b, v140
	v_mul_f32_e32 v156, 0xbfb8aa3b, v140
	v_add_f32_e32 v141, v141, v149
	v_mul_f32_e32 v153, 0x3fb8aa3b, v141
	v_mul_f32_e32 v157, 0xbfb8aa3b, v141
	v_add_f32_e32 v142, v142, v150
	v_mul_f32_e32 v154, 0x3fb8aa3b, v142
	v_mul_f32_e32 v158, 0xbfb8aa3b, v142
	v_add_f32_e32 v143, v143, v151
	v_mul_f32_e32 v155, 0x3fb8aa3b, v143
	v_mul_f32_e32 v159, 0xbfb8aa3b, v143
	v_exp_f32_e32 v152, v152
	v_exp_f32_e32 v153, v153
	v_exp_f32_e32 v154, v154
	v_exp_f32_e32 v155, v155
	v_exp_f32_e32 v156, v156
	v_exp_f32_e32 v157, v157
	v_exp_f32_e32 v158, v158
	v_exp_f32_e32 v159, v159
	v_lshlrev_b32_e32 v160, 16, v28
	v_and_b32_e32 v161, 0xffff0000, v28
	v_lshlrev_b32_e32 v168, 16, v44
	v_and_b32_e32 v169, 0xffff0000, v44
	v_lshlrev_b32_e32 v162, 16, v29
	v_and_b32_e32 v163, 0xffff0000, v29
	v_lshlrev_b32_e32 v170, 16, v45
	v_and_b32_e32 v171, 0xffff0000, v45
	v_mul_f32_e32 v160, 0x3db504f3, v160
	v_mul_f32_e32 v160, v160, v152
	v_mul_f32_e32 v168, v168, v156
	v_mul_f32_e32 v161, 0x3db504f3, v161
	v_mul_f32_e32 v161, v161, v153
	v_mul_f32_e32 v169, v169, v157
	v_mul_f32_e32 v162, 0x3db504f3, v162
	v_mul_f32_e32 v162, v162, v154
	v_mul_f32_e32 v170, v170, v158
	v_mul_f32_e32 v163, 0x3db504f3, v163
	v_mul_f32_e32 v163, v163, v155
	v_mul_f32_e32 v171, v171, v159
	v_cvt_pk_bf16_f32 v164, v160, v161
	v_cvt_pk_bf16_f32 v165, v162, v163
	v_cvt_pk_bf16_f32 v166, v168, v169
	v_cvt_pk_bf16_f32 v167, v170, v171
	global_store_dwordx2 v4, v[164:165], s[4:5] offset:1536
	global_store_dwordx2 v5, v[166:167], s[4:5] offset:1536
	v_add_f32_e32 v144, v144, v148
	v_mul_f32_e32 v152, 0x3fb8aa3b, v144
	v_mul_f32_e32 v156, 0xbfb8aa3b, v144
	v_add_f32_e32 v145, v145, v149
	v_mul_f32_e32 v153, 0x3fb8aa3b, v145
	v_mul_f32_e32 v157, 0xbfb8aa3b, v145
	v_add_f32_e32 v146, v146, v150
	v_mul_f32_e32 v154, 0x3fb8aa3b, v146
	v_mul_f32_e32 v158, 0xbfb8aa3b, v146
	v_add_f32_e32 v147, v147, v151
	v_mul_f32_e32 v155, 0x3fb8aa3b, v147
	v_mul_f32_e32 v159, 0xbfb8aa3b, v147
	v_exp_f32_e32 v152, v152
	v_exp_f32_e32 v153, v153
	v_exp_f32_e32 v154, v154
	v_exp_f32_e32 v155, v155
	v_exp_f32_e32 v156, v156
	v_exp_f32_e32 v157, v157
	v_exp_f32_e32 v158, v158
	v_exp_f32_e32 v159, v159
	v_lshlrev_b32_e32 v160, 16, v30
	v_and_b32_e32 v161, 0xffff0000, v30
	v_lshlrev_b32_e32 v172, 16, v46
	v_and_b32_e32 v173, 0xffff0000, v46
	v_lshlrev_b32_e32 v162, 16, v31
	v_and_b32_e32 v163, 0xffff0000, v31
	v_lshlrev_b32_e32 v174, 16, v47
	v_and_b32_e32 v175, 0xffff0000, v47
	v_mul_f32_e32 v160, 0x3db504f3, v160
	v_mul_f32_e32 v160, v160, v152
	v_mul_f32_e32 v172, v172, v156
	v_mul_f32_e32 v161, 0x3db504f3, v161
	v_mul_f32_e32 v161, v161, v153
	v_mul_f32_e32 v173, v173, v157
	v_mul_f32_e32 v162, 0x3db504f3, v162
	v_mul_f32_e32 v162, v162, v154
	v_mul_f32_e32 v174, v174, v158
	v_mul_f32_e32 v163, 0x3db504f3, v163
	v_mul_f32_e32 v163, v163, v155
	v_mul_f32_e32 v175, v175, v159
	v_cvt_pk_bf16_f32 v164, v160, v161
	v_cvt_pk_bf16_f32 v165, v162, v163
	v_cvt_pk_bf16_f32 v166, v172, v173
	v_cvt_pk_bf16_f32 v167, v174, v175
	global_store_dwordx2 v4, v[164:165], s[4:5] offset:1792
	global_store_dwordx2 v5, v[166:167], s[4:5] offset:1792
	v_cvt_pk_bf16_f32 v195, v168, v172
	v_cvt_pk_bf16_f32 v199, v169, v173
	v_cvt_pk_bf16_f32 v203, v170, v174
	v_cvt_pk_bf16_f32 v207, v171, v175
	global_store_dwordx4 v6, v[192:195], s[4:5] offset:0
	global_store_dwordx4 v6, v[196:199], s[4:5] offset:128
	global_store_dwordx4 v6, v[200:203], s[4:5] offset:256
	global_store_dwordx4 v6, v[204:207], s[4:5] offset:384
	s_cmp_lg_u32 s9, 7
	s_cbranch_scc1 .Lprep_gdec_done
	s_lshl_b32 s22, s7, 9
	v_add_u32_e32 v14, s22, v12
	v_lshlrev_b32_e32 v14, 2, v14
	v_add_u32_e32 v14, 0x35181000, v14
	global_store_dwordx4 v14, v[152:155], s[4:5]
; #define PIN16(a, o) asm volatile("" : "+v"(a[(o)+0]), "+v"(a[(o)+1]), "+v"(a[(o)+2]), "+v"(a[(o)+3]), "+v"(a[(o)+4]), "+v"(a[(o)+5]), "+v"(a[(o)+6]), "+v"(a[(o)+7]), \
;     "+v"(a[(o)+8]), "+v"(a[(o)+9]), "+v"(a[(o)+10]), "+v"(a[(o)+11]), "+v"(a[(o)+12]), "+v"(a[(o)+13]), "+v"(a[(o)+14]), "+v"(a[(o)+15]))
;     template <class Tp> __device__ __forceinline__ Tp* W(size_t off) const { return (Tp*)(ws + off); }
; __device__ void prep_gla(const Ctx& c, int ck, int blk) {
;     ...
;         const int ch = (blk - 1) * 512 + tid, h = ch >> 8, v = ch & 255;
;         bf16_t* gVT = c.W<bf16_t>(WS_GVT);
;         unsigned e[64];
; #pragma unroll
;         for (int l = 0; l < 64; ++l) e[l] = proj[(size_t)(t0 + l) * NP + C_GV + ch];
;         PIN16(e, 0); PIN16(e, 16); PIN16(e, 32); PIN16(e, 48);
; #pragma unroll
;         for (int l0 = 0; l0 < 64; l0 += 8) {
;             u32x4 a; a.x = e[l0] | (e[l0 + 1] << 16); a.y = e[l0 + 2] | (e[l0 + 3] << 16); a.z = e[l0 + 4] | (e[l0 + 5] << 16); a.w = e[l0 + 6] | (e[l0 + 7] << 16);
;             *(u32x4*)(gVT + ((size_t)(ck * 4 + h) * 256 + v) * 64 + l0) = a;
;         }
.Lprep_gdec_done:
	v_lshlrev_b32_e32 v12, 3, v3
	s_lshl_b32 s22, s8, 9
	v_add_u32_e32 v12, s22, v12
	v_lshlrev_b32_e32 v0, 1, v12
	v_add_u32_e32 v0, 0x3c40, v0
	s_lshl_b32 s22, s7, 10
	v_add_u32_e32 v1, s22, v12
	v_lshlrev_b32_e32 v1, 7, v1
	s_lshl_b32 s23, s9, 4
	v_add_u32_e32 v1, s23, v1
	v_add_u32_e32 v1, 0x31d81000, v1
	s_add_u32 s100, s38, 0x17a00
	s_addc_u32 s101, s39, 0
	global_load_dwordx4 v[16:19], v0, s[100:101]
	s_add_u32 s100, s100, 0x7e00
	s_addc_u32 s101, s101, 0
	global_load_dwordx4 v[20:23], v0, s[100:101]
	s_add_u32 s100, s100, 0x7e00
	s_addc_u32 s101, s101, 0
	global_load_dwordx4 v[24:27], v0, s[100:101]
	s_add_u32 s100, s100, 0x7e00
	s_addc_u32 s101, s101, 0
	global_load_dwordx4 v[28:31], v0, s[100:101]
	s_add_u32 s100, s100, 0x7e00
	s_addc_u32 s101, s101, 0
	global_load_dwordx4 v[32:35], v0, s[100:101]
	s_add_u32 s100, s100, 0x7e00
	s_addc_u32 s101, s101, 0
	global_load_dwordx4 v[36:39], v0, s[100:101]
	s_add_u32 s100, s100, 0x7e00
	s_addc_u32 s101, s101, 0
	global_load_dwordx4 v[40:43], v0, s[100:101]
	s_add_u32 s100, s100, 0x7e00
	s_addc_u32 s101, s101, 0
	global_load_dwordx4 v[44:47], v0, s[100:101]
	s_mov_b32 s22, 0x05040100
	s_mov_b32 s23, 0x07060302
	s_waitcnt vmcnt(0)
	v_perm_b32 v64, v20, v16, s22
	v_perm_b32 v65, v28, v24, s22
	v_perm_b32 v66, v36, v32, s22
	v_perm_b32 v67, v44, v40, s22
	global_store_dwordx4 v1, v[64:67], s[4:5] offset:0
	v_perm_b32 v68, v20, v16, s23
	v_perm_b32 v69, v28, v24, s23
	v_perm_b32 v70, v36, v32, s23
	v_perm_b32 v71, v44, v40, s23
	global_store_dwordx4 v1, v[68:71], s[4:5] offset:128
	v_perm_b32 v64, v21, v17, s22
	v_perm_b32 v65, v29, v25, s22
	v_perm_b32 v66, v37, v33, s22
	v_perm_b32 v67, v45, v41, s22
	global_store_dwordx4 v1, v[64:67], s[4:5] offset:256
	v_perm_b32 v68, v21, v17, s23
	v_perm_b32 v69, v29, v25, s23
	v_perm_b32 v70, v37, v33, s23
	v_perm_b32 v71, v45, v41, s23
	global_store_dwordx4 v1, v[68:71], s[4:5] offset:384
	v_perm_b32 v64, v22, v18, s22
	v_perm_b32 v65, v30, v26, s22
	v_perm_b32 v66, v38, v34, s22
	v_perm_b32 v67, v46, v42, s22
	global_store_dwordx4 v1, v[64:67], s[4:5] offset:512
	v_perm_b32 v68, v22, v18, s23
	v_perm_b32 v69, v30, v26, s23
	v_perm_b32 v70, v38, v34, s23
	v_perm_b32 v71, v46, v42, s23
	global_store_dwordx4 v1, v[68:71], s[4:5] offset:640
	v_perm_b32 v64, v23, v19, s22
	v_perm_b32 v65, v31, v27, s22
	v_perm_b32 v66, v39, v35, s22
	v_perm_b32 v67, v47, v43, s22
	global_store_dwordx4 v1, v[64:67], s[4:5] offset:768
	v_perm_b32 v68, v23, v19, s23
	v_perm_b32 v69, v31, v27, s23
	v_perm_b32 v70, v39, v35, s23
	v_perm_b32 v71, v47, v43, s23
	global_store_dwordx4 v1, v[68:71], s[4:5] offset:896
	s_waitcnt vmcnt(0) lgkmcnt(0)
	s_barrier
